# v056 + MLA static prio waves4-7 + rcp+Newton division chains in m3 output and attention finalizers
# speedup vs baseline: 1.0030x; 1.0030x over previous
; #define SHX(v, m) __int_as_float(__builtin_amdgcn_ds_bpermute(((LANE ^ (m)) << 2), __float_as_int(v)))
; __device__ void phase_m3(const P& p, int l) {
;     ...
;       float dsum = 0.f;
;       bf16x8 pf[2];
; #pragma unroll
;       for (int st = 0; st < 4; ++st)
; #pragma unroll
;         for (int j = 0; j < 4; ++j) {
;           int sp = st * 16 + quad * 4 + j;
;           bool valid = dir == 0 ? (sp <= t) : (sp >= t);
;           float dm = bct - bc[sp] + li[sp] - mt;
;           float v = valid ? s[st][j] * __expf(dm) : 0.f;
;           dsum += v;
;           pf[st >> 1][(st & 1) * 4 + j] = (short)f2bf(v);
;         }
;       dsum += SHX(dsum, 16);
;       dsum += SHX(dsum, 32);
;       f32x4 hi[8], hx[8];
; #pragma unroll
;       for (int e = 0; e < 8; ++e) { hi[e] = f32x4{0.f, 0.f, 0.f, 0.f}; hx[e] = f32x4{0.f, 0.f, 0.f, 0.f}; }
; #pragma unroll
;       for (int kk = 0; kk < 2; ++kk)
; #pragma unroll
;         for (int e = 0; e < 8; ++e) {
;           const u16* vb = vT + (e * 16 + l15) * 72 + kk * 32 + quad * 4;
;           bf16x4 v0 = *(const bf16x4*)vb, v1 = *(const bf16x4*)(vb + 16);
;           bf16x8 va = {v0[0], v0[1], v0[2], v0[3], v1[0], v1[1], v1[2], v1[3]};
;           hi[e] = __builtin_amdgcn_mfma_f32_16x16x32_bf16(va, pf[kk], hi[e], 0, 0, 0);
;         }
;       const u16* cin = (const u16*)(ws + O_CIN) + (size_t)itemd[dir] * 16384;
;       {
;         bf16x8 cn[8];
; #pragma unroll
;         for (int e = 0; e < 8; ++e) cn[e] = *(const bf16x8*)(cin + (e * 16 + l15) * 128 + quad * 8);
; #pragma unroll
;         for (int ks = 0; ks < 4; ++ks) {
;           bf16x8 ca[8];
; #pragma unroll
;           for (int e = 0; e < 8; ++e) ca[e] = cn[e];
;           if (ks + 1 < 4) {
; #pragma unroll
;             for (int e = 0; e < 8; ++e) cn[e] = *(const bf16x8*)(cin + (e * 16 + l15) * 128 + (ks + 1) * 32 + quad * 8);
;           }
; #pragma unroll
;           for (int e = 0; e < 8; ++e) hx[e] = __builtin_amdgcn_mfma_f32_16x16x32_bf16(ca[e], qf[ks], hx[e], 0, 0, 0);
;         }
;       }
.LBB0_458:
	s_or_b64 exec, exec, s[0:1]
	v_bfe_u32 v99, v155, 16, 1
	v_lshlrev_b64 v[66:67], 15, v[66:67]
	v_add3_u32 v184, v155, v99, s33
	v_lshl_add_u64 v[192:193], v[94:95], 0, v[66:67]
	v_mov_b32_e32 v99, v1
	v_lshl_add_u64 v[236:237], v[192:193], 0, v[98:99]
	global_load_dwordx4 v[172:175], v[236:237], off
	v_bfe_u32 v50, v148, 16, 1
	v_add3_u32 v80, v148, v50, s33
	v_bfe_u32 v50, v151, 16, 1
	v_add3_u32 v81, v151, v50, s33
	v_bfe_u32 v50, v150, 16, 1
	v_add3_u32 v105, v150, v50, s33
	v_bfe_u32 v50, v153, 16, 1
	v_add3_u32 v107, v153, v50, s33
	v_bfe_u32 v50, v142, 16, 1
	v_add_u32_e32 v113, 0xa000, v139
	v_add3_u32 v54, v142, v50, s33
	v_bfe_u32 v50, v143, 16, 1
	v_bfe_u32 v72, v152, 16, 1
	ds_read2_b64 v[68:71], v113 offset0:96 offset1:100
	v_add_u32_e32 v220, 0xa800, v139
	v_add3_u32 v62, v143, v50, s33
	v_bfe_u32 v50, v141, 16, 1
	v_add3_u32 v157, v152, v72, s33
	ds_read2_b64 v[72:75], v220 offset0:128 offset1:132
	v_add3_u32 v55, v141, v50, s33
	v_bfe_u32 v50, v145, 16, 1
	v_add3_u32 v63, v145, v50, s33
	v_bfe_u32 v50, v144, 16, 1
	v_add3_u32 v56, v144, v50, s33
	v_bfe_u32 v50, v147, 16, 1
	v_add3_u32 v58, v147, v50, s33
	v_bfe_u32 v50, v146, 16, 1
	v_add3_u32 v57, v146, v50, s33
	v_bfe_u32 v50, v149, 16, 1
	v_add3_u32 v59, v149, v50, s33
	v_perm_b32 v57, v59, v57, s27
	v_perm_b32 v56, v58, v56, s27
	v_perm_b32 v55, v63, v55, s27
	v_perm_b32 v54, v62, v54, s27
	v_add_u32_e32 v103, 0x8800, v139
	v_add_u32_e32 v109, 0x9000, v139
	v_add_u32_e32 v111, 0x9800, v139
	v_add_u32_e32 v221, 0xb000, v139
	s_waitcnt lgkmcnt(1)
	v_mfma_f32_16x16x32_bf16 v[158:161], v[68:71], v[54:57], 0
	v_bfe_u32 v68, v154, 16, 1
	v_add_u32_e32 v222, 0xb800, v139
	v_add_u32_e32 v223, 0xc000, v139
	ds_read2_b64 v[50:53], v103 offset1:4
	ds_read2_b64 v[58:61], v109 offset0:32 offset1:36
	ds_read2_b64 v[62:65], v111 offset0:64 offset1:68
	ds_read2_b64 v[76:79], v221 offset0:160 offset1:164
	v_add3_u32 v185, v154, v68, s33
	s_waitcnt lgkmcnt(4)
	v_mfma_f32_16x16x32_bf16 v[162:165], v[72:75], v[54:57], 0
	ds_read2_b64 v[68:71], v222 offset0:192 offset1:196
	ds_read2_b64 v[72:75], v223 offset0:224 offset1:228
	v_bfe_u32 v180, v156, 16, 1
	s_waitcnt lgkmcnt(5)
	v_mfma_f32_16x16x32_bf16 v[50:53], v[50:53], v[54:57], 0
	v_mov_b32_e32 v101, v1
	v_perm_b32 v186, v184, v157, s27
	v_perm_b32 v184, v81, v80, s27
	s_waitcnt lgkmcnt(4)
	v_mfma_f32_16x16x32_bf16 v[58:61], v[58:61], v[54:57], 0
	v_lshl_add_u64 v[66:67], v[192:193], 0, v[100:101]
	v_lshl_add_u64 v[232:233], v[192:193], 0, 64
	s_mov_b64 s[0:1], 0xc0
	s_waitcnt lgkmcnt(3)
	v_mfma_f32_16x16x32_bf16 v[62:65], v[62:65], v[54:57], 0
	v_add_f32_e32 v99, 0, v142
	v_sub_f32_e32 v0, v0, v97
	v_mul_f32_e32 v0, 0x3fb8aa3b, v0
	s_waitcnt lgkmcnt(2)
	v_mfma_f32_16x16x32_bf16 v[166:169], v[76:79], v[54:57], 0
	v_exp_f32_e32 v0, v0
	v_mul_f32_e32 v97, 0xbfb8aa3b, v97
	v_exp_f32_e32 v97, v97
	s_waitcnt lgkmcnt(1)
	v_mfma_f32_16x16x32_bf16 v[176:179], v[68:71], v[54:57], 0
	v_add3_u32 v68, v156, v180, s33
	v_perm_b32 v187, v68, v185, s27
	v_perm_b32 v185, v107, v105, s27
	s_waitcnt lgkmcnt(0)
	v_mfma_f32_16x16x32_bf16 v[180:183], v[72:75], v[54:57], 0
	ds_read2_b64 v[54:57], v103 offset0:8 offset1:12
	v_mov_b32_e32 v103, v1
	v_mov_b32_e32 v105, v1
	v_mov_b32_e32 v107, v1
	v_lshl_add_u64 v[68:69], v[192:193], 0, v[102:103]
	s_waitcnt lgkmcnt(0)
	v_mfma_f32_16x16x32_bf16 v[78:81], v[54:57], v[184:187], v[50:53]
	s_nop 2
	v_lshl_add_u64 v[50:51], v[192:193], 0, v[104:105]
	v_lshl_add_u64 v[54:55], v[192:193], 0, v[106:107]
	global_load_dwordx4 v[188:191], v[66:67], off
	global_load_dwordx4 v[204:207], v[68:69], off
	ds_read2_b64 v[66:69], v109 offset0:40 offset1:44
	global_load_dwordx4 v[208:211], v[50:51], off
	global_load_dwordx4 v[212:215], v[54:55], off
	ds_read2_b64 v[50:53], v111 offset0:72 offset1:76
	ds_read2_b64 v[54:57], v113 offset0:104 offset1:108
	v_mov_b32_e32 v109, v1
	v_mov_b32_e32 v111, v1
	s_waitcnt lgkmcnt(2)
	v_mfma_f32_16x16x32_bf16 v[74:77], v[66:69], v[184:187], v[58:61]
	v_mov_b32_e32 v113, v1
	v_lshl_add_u64 v[224:225], v[232:233], 0, v[108:109]
	v_lshl_add_u64 v[228:229], v[232:233], 0, v[110:111]
	s_waitcnt lgkmcnt(1)
	v_mfma_f32_16x16x32_bf16 v[70:73], v[50:53], v[184:187], v[62:65]
	v_lshl_add_u64 v[50:51], v[192:193], 0, v[108:109]
	global_load_dwordx4 v[216:219], v[50:51], off
	s_lshl_b32 s20, s4, 1
	s_waitcnt lgkmcnt(0)
	v_mfma_f32_16x16x32_bf16 v[66:69], v[54:57], v[184:187], v[158:161]
	v_lshl_add_u64 v[54:55], v[192:193], 0, v[110:111]
	global_load_dwordx4 v[228:231], v[228:229], off
	s_nop 0
	global_load_dwordx4 v[158:161], v[54:55], off
	ds_read2_b64 v[50:53], v220 offset0:136 offset1:140
	s_waitcnt lgkmcnt(0)
	v_mfma_f32_16x16x32_bf16 v[62:65], v[50:53], v[184:187], v[162:165]
	ds_read2_b64 v[50:53], v221 offset0:168 offset1:172
	v_lshl_add_u64 v[220:221], v[232:233], 0, v[104:105]
	s_nop 0
	global_load_dwordx4 v[162:165], v[236:237], off offset:64
	s_waitcnt lgkmcnt(0)
	v_mfma_f32_16x16x32_bf16 v[58:61], v[50:53], v[184:187], v[166:169]
	ds_read2_b64 v[50:53], v222 offset0:200 offset1:204
	global_load_dwordx4 v[224:227], v[224:225], off
	s_waitcnt lgkmcnt(0)
	v_mfma_f32_16x16x32_bf16 v[54:57], v[50:53], v[184:187], v[176:179]
	s_nop 2
	v_lshl_add_u64 v[176:177], v[192:193], 0, v[112:113]
	ds_read2_b64 v[50:53], v223 offset0:232 offset1:236
	s_waitcnt vmcnt(9)
	v_mfma_f32_16x16x32_bf16 v[166:169], v[172:175], v[46:49], 0
	global_load_dwordx4 v[172:175], v[176:177], off
	s_waitcnt lgkmcnt(0)
	v_mfma_f32_16x16x32_bf16 v[50:53], v[50:53], v[184:187], v[180:183]
	s_nop 2
	v_lshl_add_u64 v[180:181], v[232:233], 0, v[100:101]
	global_load_dwordx4 v[180:183], v[180:181], off
	s_waitcnt vmcnt(10)
; __device__ void phase_m3(const P& p, int l) {
;     ...
;       const u16* cin = (const u16*)(ws + O_CIN) + (size_t)itemd[dir] * 16384;
;       {
;         bf16x8 cn[8];
; #pragma unroll
;         for (int e = 0; e < 8; ++e) cn[e] = *(const bf16x8*)(cin + (e * 16 + l15) * 128 + quad * 8);
; #pragma unroll
;         for (int ks = 0; ks < 4; ++ks) {
;           bf16x8 ca[8];
; #pragma unroll
;           for (int e = 0; e < 8; ++e) ca[e] = cn[e];
;           if (ks + 1 < 4) {
; #pragma unroll
;             for (int e = 0; e < 8; ++e) cn[e] = *(const bf16x8*)(cin + (e * 16 + l15) * 128 + (ks + 1) * 32 + quad * 8);
;           }
; #pragma unroll
;           for (int e = 0; e < 8; ++e) hx[e] = __builtin_amdgcn_mfma_f32_16x16x32_bf16(ca[e], qf[ks], hx[e], 0, 0, 0);
;         }
;       }
;       float a = __expf(bct + m_in - mt);
;       float den = a * qn[dir * 64 + t] + dsum;
;       float idn = 1.f / fmaxf(fabsf(den), __expf(-mt));
	v_mfma_f32_16x16x32_bf16 v[176:179], v[188:191], v[46:49], 0
	v_lshl_add_u64 v[188:189], v[232:233], 0, v[102:103]
	global_load_dwordx4 v[188:191], v[188:189], off
	s_waitcnt vmcnt(10)
	v_mfma_f32_16x16x32_bf16 v[184:187], v[204:207], v[46:49], 0
	s_waitcnt vmcnt(9)
	v_mfma_f32_16x16x32_bf16 v[204:207], v[208:211], v[46:49], 0
	global_load_dwordx4 v[208:211], v[220:221], off
	v_lshl_add_u64 v[220:221], v[232:233], 0, v[106:107]
	v_lshl_add_u64 v[232:233], v[232:233], 0, v[112:113]
	s_waitcnt vmcnt(9)
	v_mfma_f32_16x16x32_bf16 v[212:215], v[212:215], v[46:49], 0
	global_load_dwordx4 v[220:223], v[220:221], off
	s_waitcnt vmcnt(9)
	v_mfma_f32_16x16x32_bf16 v[216:219], v[216:219], v[46:49], 0
	s_waitcnt vmcnt(7)
	v_mfma_f32_16x16x32_bf16 v[158:161], v[158:161], v[46:49], 0
	s_waitcnt vmcnt(4)
	v_mfma_f32_16x16x32_bf16 v[46:49], v[172:175], v[46:49], 0
	global_load_dwordx4 v[172:175], v[232:233], off
	v_lshl_add_u64 v[232:233], v[192:193], 0, s[24:25]
	v_lshl_add_u64 v[234:235], v[232:233], 0, v[100:101]
	s_waitcnt vmcnt(4)
	v_mfma_f32_16x16x32_bf16 v[176:179], v[180:183], v[42:45], v[176:179]
	global_load_dwordx4 v[180:183], v[234:235], off
	v_lshl_add_u64 v[234:235], v[232:233], 0, v[102:103]
	v_lshl_add_u64 v[192:193], v[192:193], 0, s[0:1]
	v_mfma_f32_16x16x32_bf16 v[162:165], v[162:165], v[42:45], v[166:169]
	s_nop 2
	global_load_dwordx4 v[166:169], v[236:237], off offset:128
	s_waitcnt vmcnt(5)
	v_mfma_f32_16x16x32_bf16 v[184:187], v[188:191], v[42:45], v[184:187]
	global_load_dwordx4 v[188:191], v[234:235], off
	v_lshl_add_u64 v[234:235], v[232:233], 0, v[104:105]
	s_waitcnt vmcnt(5)
	v_mfma_f32_16x16x32_bf16 v[204:207], v[208:211], v[42:45], v[204:207]
	global_load_dwordx4 v[208:211], v[234:235], off
	s_waitcnt vmcnt(5)
	v_mfma_f32_16x16x32_bf16 v[212:215], v[220:223], v[42:45], v[212:215]
	v_mfma_f32_16x16x32_bf16 v[216:219], v[224:227], v[42:45], v[216:219]
	v_mfma_f32_16x16x32_bf16 v[158:161], v[228:231], v[42:45], v[158:161]
	s_waitcnt vmcnt(4)
	v_mfma_f32_16x16x32_bf16 v[42:45], v[172:175], v[42:45], v[46:49]
	s_nop 2
	global_load_dwordx4 v[46:49], v[236:237], off offset:192
	v_lshl_add_u64 v[234:235], v[232:233], 0, v[106:107]
	global_load_dwordx4 v[220:223], v[234:235], off
	v_lshl_add_u64 v[234:235], v[232:233], 0, v[108:109]
	global_load_dwordx4 v[224:227], v[234:235], off
	v_lshl_add_u64 v[234:235], v[232:233], 0, v[110:111]
	v_lshl_add_u64 v[232:233], v[232:233], 0, v[112:113]
	global_load_dwordx4 v[228:231], v[234:235], off
	v_lshl_add_u64 v[172:173], v[192:193], 0, v[100:101]
	global_load_dwordx4 v[232:235], v[232:233], off
	v_lshl_add_u64 v[236:237], v[192:193], 0, v[102:103]
	s_waitcnt vmcnt(7)
	v_mfma_f32_16x16x32_bf16 v[162:165], v[166:169], v[38:41], v[162:165]
	global_load_dwordx4 v[166:169], v[172:173], off
	ds_read_b32 v103, v126 offset:55360
	v_mfma_f32_16x16x32_bf16 v[172:175], v[180:183], v[38:41], v[176:179]
	s_nop 2
	global_load_dwordx4 v[176:179], v[236:237], off
	v_lshl_add_u64 v[236:237], v[192:193], 0, v[104:105]
	s_waitcnt vmcnt(8)
	v_mfma_f32_16x16x32_bf16 v[180:183], v[188:191], v[38:41], v[184:187]
	s_nop 2
	global_load_dwordx4 v[184:187], v[236:237], off
	v_lshl_add_u64 v[236:237], v[192:193], 0, v[106:107]
	s_waitcnt vmcnt(8)
	v_mfma_f32_16x16x32_bf16 v[188:191], v[208:211], v[38:41], v[204:207]
	s_nop 2
	global_load_dwordx4 v[204:207], v[236:237], off
	v_lshl_add_u64 v[236:237], v[192:193], 0, v[108:109]
	s_waitcnt vmcnt(7)
	v_mfma_f32_16x16x32_bf16 v[208:211], v[220:223], v[38:41], v[212:215]
	v_lshl_add_u64 v[220:221], v[192:193], 0, v[110:111]
	v_lshl_add_u64 v[192:193], v[192:193], 0, v[112:113]
	s_nop 0
	global_load_dwordx4 v[212:215], v[236:237], off
	s_waitcnt vmcnt(7)
	v_mfma_f32_16x16x32_bf16 v[216:219], v[224:227], v[38:41], v[216:219]
	global_load_dwordx4 v[220:223], v[220:221], off
	s_nop 0
	global_load_dwordx4 v[224:227], v[192:193], off
	s_waitcnt vmcnt(8)
	v_mfma_f32_16x16x32_bf16 v[158:161], v[228:231], v[38:41], v[158:161]
	s_waitcnt vmcnt(7)
	v_mfma_f32_16x16x32_bf16 v[38:41], v[232:235], v[38:41], v[42:45]
	s_nop 2
	v_add_f32_e32 v42, v99, v143
	v_add_f32_e32 v42, v42, v141
	v_add_f32_e32 v99, v42, v145
	v_mfma_f32_16x16x32_bf16 v[42:45], v[46:49], v[34:37], v[162:165]
	v_add_f32_e32 v46, v99, v144
	v_add_f32_e32 v46, v46, v147
	v_add_f32_e32 v99, v46, v146
	v_add_f32_e32 v99, v99, v149
	v_add_f32_e32 v99, v99, v148
	v_add_f32_e32 v99, v99, v151
	v_add_f32_e32 v99, v99, v150
	v_add_f32_e32 v99, v99, v153
	v_add_f32_e32 v99, v99, v152
	v_add_f32_e32 v99, v99, v155
	v_add_f32_e32 v99, v99, v154
	v_add_f32_e32 v99, v99, v156
	ds_bpermute_b32 v101, v124, v99
	s_waitcnt vmcnt(6)
	v_mfma_f32_16x16x32_bf16 v[46:49], v[166:169], v[34:37], v[172:175]
	s_waitcnt lgkmcnt(0)
	v_add_f32_e32 v99, v99, v101
	ds_bpermute_b32 v101, v125, v99
	s_waitcnt vmcnt(5)
	v_mfma_f32_16x16x32_bf16 v[142:145], v[176:179], v[34:37], v[180:183]
	s_waitcnt lgkmcnt(0)
	v_add_f32_e32 v99, v99, v101
	v_fmac_f32_e32 v99, v0, v103
	v_max_f32_e64 v97, |v99|, v97
	v_rcp_f32_e32 v99, v97
	s_nop 0
	s_waitcnt vmcnt(4)
	v_mfma_f32_16x16x32_bf16 v[146:149], v[184:187], v[34:37], v[188:191]
	s_waitcnt vmcnt(3)
	v_mfma_f32_16x16x32_bf16 v[150:153], v[204:207], v[34:37], v[208:211]
	s_waitcnt vmcnt(2)
	v_mfma_f32_16x16x32_bf16 v[154:157], v[212:215], v[34:37], v[216:219]
	s_waitcnt vmcnt(1)
	v_mfma_f32_16x16x32_bf16 v[158:161], v[220:223], v[34:37], v[158:161]
	s_waitcnt vmcnt(0)
; DEVI float bf2f(u16 h) { return __uint_as_float(((unsigned)h) << 16); }
; DEVI float bfs(short h) { return __uint_as_float(((unsigned)(u16)h) << 16); }
; DEVI float silu_f(float x) { return x / (1.f + __expf(-x)); }
; DEVI float sigm_f(float x) { return 1.f / (1.f + __expf(-x)); }
; #define SHX(v, m) __int_as_float(__builtin_amdgcn_ds_bpermute(((LANE ^ (m)) << 2), __float_as_int(v)))
; __device__ void phase_m3(const P& p, int l) {
;     ...
;       float a = __expf(bct + m_in - mt);
;       float den = a * qn[dir * 64 + t] + dsum;
;       float idn = 1.f / fmaxf(fabsf(den), __expf(-mt));
; #pragma unroll
;       for (int e = 0; e < 8; ++e)
; #pragma unroll
;         for (int j = 0; j < 4; ++j) hbuf[(dir * 64 + t) * 129 + e * 16 + quad * 4 + j] = (a * hx[e][j] + hi[e][j]) * idn;
;     }
;     __syncthreads();
;     {
;       int t = TIDX >> 3, part = TIDX & 7;
;       float hv[16], ss = 0.f;
; #pragma unroll
;       for (int e = 0; e < 16; ++e) {
;         hv[e] = hbuf[t * 129 + part * 16 + e] + hbuf[(64 + t) * 129 + part * 16 + e];
;         ss += hv[e] * hv[e];
;       }
;       ss += SHX(ss, 1);
;       ss += SHX(ss, 2);
;       ss += SHX(ss, 4);
;       float rs = rsqrtf(ss * (1.f / 128.f) + EPS);
;       int r = R0 + t;
;       const u16* pr = proj + (size_t)r * NP;
;       u16* ys = (u16*)(ws + O_YS) + (size_t)r * 2048 + 1536 + h * 128 + part * 16;
;       const int ch0 = h * 128 + part * 16;
;       float dox[16], dgx[16], gn[16];
; #pragma unroll
;       for (int e = 0; e < 8; ++e) {
;         dox[e] = bfs(ldo[0][e]); dox[8 + e] = bfs(ldo[1][e]);
;         dgx[e] = bfs(ldg[0][e]); dgx[8 + e] = bfs(ldg[1][e]);
;       }
; #pragma unroll
;       for (int e4 = 0; e4 < 4; ++e4)
; #pragma unroll
;         for (int e = 0; e < 4; ++e) gn[e4 * 4 + e] = lgn[e4][e];
;       float yo[16];
; #pragma unroll
;       for (int e = 0; e < 16; ++e) {
;         float y = hv[e] * rs * gn[e] * sigm_f(dox[e]);
;         yo[e] = bf2f(f2bf(y)) * silu_f(dgx[e]);
	v_mfma_f32_16x16x32_bf16 v[34:37], v[224:227], v[34:37], v[38:41]
	s_nop 2
	v_fma_f32 v38, -v97, v99, 1.0
	v_fma_f32 v99, v38, v99, v99
	v_mov_b32_e32 v38, v99
	v_mov_b32_e32 v38, v38
	v_pk_fma_f32 v[40:41], v[0:1], v[42:43], v[78:79] op_sel_hi:[0,1,1]
	v_pk_mul_f32 v[40:41], v[40:41], v[38:39] op_sel_hi:[1,0]
	v_add_u32_e32 v39, 0xde40, v140
	ds_write2_b32 v39, v40, v41 offset1:1
	v_pk_fma_f32 v[40:41], v[0:1], v[44:45], v[80:81] op_sel_hi:[0,1,1]
	v_pk_mul_f32 v[40:41], v[40:41], v[38:39] op_sel_hi:[1,0]
	v_add_u32_e32 v39, 0xde48, v140
	ds_write2_b32 v39, v40, v41 offset1:1
	v_pk_fma_f32 v[40:41], v[0:1], v[46:47], v[74:75] op_sel_hi:[0,1,1]
	v_pk_mul_f32 v[40:41], v[40:41], v[38:39] op_sel_hi:[1,0]
	v_add_u32_e32 v39, 0xde80, v140
	ds_write2_b32 v39, v40, v41 offset1:1
	v_pk_fma_f32 v[40:41], v[0:1], v[48:49], v[76:77] op_sel_hi:[0,1,1]
	v_pk_mul_f32 v[40:41], v[40:41], v[38:39] op_sel_hi:[1,0]
	v_add_u32_e32 v39, 0xde88, v140
	ds_write2_b32 v39, v40, v41 offset1:1
	v_pk_fma_f32 v[40:41], v[0:1], v[142:143], v[70:71] op_sel_hi:[0,1,1]
	v_pk_mul_f32 v[40:41], v[40:41], v[38:39] op_sel_hi:[1,0]
	v_add_u32_e32 v39, 0xdec0, v140
	ds_write2_b32 v39, v40, v41 offset1:1
	v_pk_fma_f32 v[40:41], v[0:1], v[144:145], v[72:73] op_sel_hi:[0,1,1]
	v_pk_mul_f32 v[40:41], v[40:41], v[38:39] op_sel_hi:[1,0]
	v_add_u32_e32 v39, 0xdec8, v140
	ds_write2_b32 v39, v40, v41 offset1:1
	v_pk_fma_f32 v[40:41], v[0:1], v[146:147], v[66:67] op_sel_hi:[0,1,1]
	v_pk_mul_f32 v[40:41], v[40:41], v[38:39] op_sel_hi:[1,0]
	v_add_u32_e32 v39, 0xdf00, v140
	ds_write2_b32 v39, v40, v41 offset1:1
	v_pk_fma_f32 v[40:41], v[0:1], v[148:149], v[68:69] op_sel_hi:[0,1,1]
	v_pk_mul_f32 v[40:41], v[40:41], v[38:39] op_sel_hi:[1,0]
	v_add_u32_e32 v39, 0xdf08, v140
	ds_write2_b32 v39, v40, v41 offset1:1
	v_pk_fma_f32 v[40:41], v[0:1], v[150:151], v[62:63] op_sel_hi:[0,1,1]
	v_pk_mul_f32 v[40:41], v[40:41], v[38:39] op_sel_hi:[1,0]
	v_add_u32_e32 v39, 0xdf40, v140
	ds_write2_b32 v39, v40, v41 offset1:1
	v_pk_fma_f32 v[40:41], v[0:1], v[152:153], v[64:65] op_sel_hi:[0,1,1]
	v_pk_mul_f32 v[40:41], v[40:41], v[38:39] op_sel_hi:[1,0]
	v_add_u32_e32 v39, 0xdf48, v140
	ds_write2_b32 v39, v40, v41 offset1:1
	v_pk_fma_f32 v[40:41], v[0:1], v[154:155], v[58:59] op_sel_hi:[0,1,1]
	v_pk_mul_f32 v[40:41], v[40:41], v[38:39] op_sel_hi:[1,0]
	v_add_u32_e32 v39, 0xdf80, v140
	ds_write2_b32 v39, v40, v41 offset1:1
	v_pk_fma_f32 v[40:41], v[0:1], v[156:157], v[60:61] op_sel_hi:[0,1,1]
	v_pk_mul_f32 v[40:41], v[40:41], v[38:39] op_sel_hi:[1,0]
	v_add_u32_e32 v39, 0xdf88, v140
	ds_write2_b32 v39, v40, v41 offset1:1
	v_pk_fma_f32 v[40:41], v[0:1], v[158:159], v[54:55] op_sel_hi:[0,1,1]
	v_pk_mul_f32 v[40:41], v[40:41], v[38:39] op_sel_hi:[1,0]
	v_add_u32_e32 v39, 0xdfc0, v140
	ds_write2_b32 v39, v40, v41 offset1:1
	v_pk_fma_f32 v[40:41], v[0:1], v[160:161], v[56:57] op_sel_hi:[0,1,1]
	v_pk_mul_f32 v[40:41], v[40:41], v[38:39] op_sel_hi:[1,0]
	v_add_u32_e32 v39, 0xdfc8, v140
	v_pk_fma_f32 v[34:35], v[0:1], v[34:35], v[50:51] op_sel_hi:[0,1,1]
	ds_write2_b32 v39, v40, v41 offset1:1
	v_pk_mul_f32 v[34:35], v[34:35], v[38:39] op_sel_hi:[1,0]
	v_add_u32_e32 v39, 0xe000, v140
	ds_write2_b32 v39, v34, v35 offset1:1
	v_pk_fma_f32 v[34:35], v[0:1], v[36:37], v[52:53] op_sel_hi:[0,1,1]
	v_pk_mul_f32 v[34:35], v[34:35], v[38:39] op_sel_hi:[1,0]
	v_add_u32_e32 v0, 0xe008, v140
	ds_write2_b32 v0, v34, v35 offset1:1
	v_add_u32_e32 v0, 0xde70, v127
	v_add_u32_e32 v36, 0x8130, v128
	s_waitcnt lgkmcnt(0)
	s_barrier
	ds_read2_b32 v[34:35], v0 offset1:1
	ds_read2_b32 v[36:37], v36 offset1:1
	v_add_u32_e32 v0, 0xde78, v127
	ds_read2_b32 v[42:43], v0 offset1:1
	ds_read2_b32 v[44:45], v128 offset1:1
	v_add_u32_e32 v0, 0x8138, v128
	v_lshlrev_b32_e32 v60, 16, v26
	s_waitcnt lgkmcnt(2)
	v_pk_add_f32 v[38:39], v[34:35], v[36:37]
	ds_read2_b32 v[34:35], v0 offset1:1
	v_add_u32_e32 v0, 0xde58, v127
	v_add_u32_e32 v36, 0x8118, v128
	v_add_u32_e32 v37, 0xde50, v127
	ds_read2_b32 v[46:47], v0 offset1:1
	ds_read2_b32 v[48:49], v36 offset1:1
	ds_read2_b32 v[50:51], v37 offset1:1
	v_lshlrev_b32_e32 v0, 16, v30
	v_and_b32_e32 v30, 0xffff0000, v30
	v_mul_f32_e32 v0, 0xbfb8aa3b, v0
	v_and_b32_e32 v61, 0xffff0000, v26
	v_lshlrev_b32_e32 v26, 16, v31
	v_lshlrev_b32_e32 v72, 16, v28
	v_and_b32_e32 v73, 0xffff0000, v28
	v_exp_f32_e32 v28, v0
	v_mul_f32_e32 v0, 0xbfb8aa3b, v30
	v_and_b32_e32 v31, 0xffff0000, v31
	v_lshlrev_b32_e32 v74, 16, v29
	v_and_b32_e32 v75, 0xffff0000, v29
	v_exp_f32_e32 v29, v0
	v_mul_f32_e32 v0, 0xbfb8aa3b, v26
	v_lshlrev_b32_e32 v62, 16, v27
	v_and_b32_e32 v63, 0xffff0000, v27
	v_lshlrev_b32_e32 v27, 16, v32
	v_exp_f32_e32 v30, v0
	v_mul_f32_e32 v0, 0xbfb8aa3b, v31
	v_and_b32_e32 v52, 0xffff0000, v32
	v_exp_f32_e32 v31, v0
	v_mul_f32_e32 v0, 0xbfb8aa3b, v27
	v_exp_f32_e32 v32, v0
	v_mul_f32_e32 v0, 0xbfb8aa3b, v52
	v_lshlrev_b32_e32 v53, 16, v33
	v_and_b32_e32 v54, 0xffff0000, v33
	v_exp_f32_e32 v33, v0
	v_mul_f32_e32 v0, 0xbfb8aa3b, v53
	v_exp_f32_e32 v52, v0
	v_mul_f32_e32 v0, 0xbfb8aa3b, v54
	v_exp_f32_e32 v53, v0
	v_add_u32_e32 v0, 0x8110, v128
	v_pk_add_f32 v[32:33], v[32:33], 1.0 op_sel_hi:[1,0]
	s_waitcnt lgkmcnt(1)
; DEVI float bf2f(u16 h) { return __uint_as_float(((unsigned)h) << 16); }
; DEVI float bfs(short h) { return __uint_as_float(((unsigned)(u16)h) << 16); }
; DEVI float silu_f(float x) { return x / (1.f + __expf(-x)); }
; DEVI float sigm_f(float x) { return 1.f / (1.f + __expf(-x)); }
; #define SHX(v, m) __int_as_float(__builtin_amdgcn_ds_bpermute(((LANE ^ (m)) << 2), __float_as_int(v)))
; __device__ void phase_m3(const P& p, int l) {
;     ...
;       int t = TIDX >> 3, part = TIDX & 7;
;       float hv[16], ss = 0.f;
; #pragma unroll
;       for (int e = 0; e < 16; ++e) {
;         hv[e] = hbuf[t * 129 + part * 16 + e] + hbuf[(64 + t) * 129 + part * 16 + e];
;         ss += hv[e] * hv[e];
;       }
;       ss += SHX(ss, 1);
;       ss += SHX(ss, 2);
;       ss += SHX(ss, 4);
;       float rs = rsqrtf(ss * (1.f / 128.f) + EPS);
;       int r = R0 + t;
;       const u16* pr = proj + (size_t)r * NP;
;       u16* ys = (u16*)(ws + O_YS) + (size_t)r * 2048 + 1536 + h * 128 + part * 16;
;       const int ch0 = h * 128 + part * 16;
;       float dox[16], dgx[16], gn[16];
; #pragma unroll
;       for (int e = 0; e < 8; ++e) {
;         dox[e] = bfs(ldo[0][e]); dox[8 + e] = bfs(ldo[1][e]);
;         dgx[e] = bfs(ldg[0][e]); dgx[8 + e] = bfs(ldg[1][e]);
;       }
; #pragma unroll
;       for (int e4 = 0; e4 < 4; ++e4)
; #pragma unroll
;         for (int e = 0; e < 4; ++e) gn[e4 * 4 + e] = lgn[e4][e];
;       float yo[16];
; #pragma unroll
;       for (int e = 0; e < 16; ++e) {
;         float y = hv[e] * rs * gn[e] * sigm_f(dox[e]);
;         yo[e] = bf2f(f2bf(y)) * silu_f(dgx[e]);
	v_pk_add_f32 v[26:27], v[46:47], v[48:49]
	ds_read2_b32 v[48:49], v0 offset1:1
	v_rcp_f32_e32 v0, v33
	s_nop 0
	v_pk_add_f32 v[30:31], v[30:31], 1.0 op_sel_hi:[1,0]
	v_pk_add_f32 v[28:29], v[28:29], 1.0 op_sel_hi:[1,0]
	v_pk_add_f32 v[52:53], v[52:53], 1.0 op_sel_hi:[1,0]
	v_fma_f32 v65, -v33, v0, 1.0
	v_fma_f32 v0, v65, v0, v0
	v_rcp_f32_e32 v65, v32
	s_nop 0
	v_mov_b32_e32 v33, v0
	v_add_u32_e32 v54, 0xde48, v127
	v_fma_f32 v0, -v32, v65, 1.0
	v_fma_f32 v65, v0, v65, v65
	v_mov_b32_e32 v0, v65
	v_rcp_f32_e32 v64, v31
	s_nop 0
	v_mov_b32_e32 v32, v0
	v_add_u32_e32 v56, 0x8108, v128
	v_add_u32_e32 v58, 0x8100, v128
	v_fma_f32 v0, -v31, v64, 1.0
	v_fma_f32 v64, v0, v64, v64
	v_mov_b32_e32 v0, v64
	v_rcp_f32_e32 v64, v30
	s_nop 0
	v_mov_b32_e32 v31, v0
	ds_read2_b32 v[54:55], v54 offset1:1
	ds_read2_b32 v[56:57], v56 offset1:1
	ds_read2_b32 v[58:59], v58 offset1:1
	v_fma_f32 v0, -v30, v64, 1.0
	v_fma_f32 v64, v0, v64, v64
	v_mov_b32_e32 v0, v64
	v_rcp_f32_e32 v64, v29
	s_nop 0
	v_mov_b32_e32 v30, v0
	s_waitcnt lgkmcnt(0)
	v_pk_add_f32 v[44:45], v[44:45], v[58:59]
	v_pk_add_f32 v[54:55], v[54:55], v[56:57]
	v_fma_f32 v0, -v29, v64, 1.0
	v_fma_f32 v64, v0, v64, v64
	v_mov_b32_e32 v0, v64
	v_rcp_f32_e32 v64, v28
	s_nop 0
	v_mov_b32_e32 v29, v0
	v_pk_mul_f32 v[58:59], v[44:45], v[44:45]
	v_fma_f32 v0, -v28, v64, 1.0
	v_fma_f32 v64, v0, v64, v64
	v_mov_b32_e32 v0, v64
	v_rcp_f32_e32 v64, v53
	s_nop 0
	v_mov_b32_e32 v28, v0
	v_add_u32_e32 v70, 0x8120, v128
	v_fma_f32 v0, -v53, v64, 1.0
	v_fma_f32 v64, v0, v64, v64
	v_mov_b32_e32 v0, v64
	v_rcp_f32_e32 v64, v52
	s_nop 0
	v_mov_b32_e32 v53, v0
	v_pk_mul_f32 v[56:57], v[54:55], v[54:55]
	v_fma_f32 v0, -v52, v64, 1.0
	v_fma_f32 v64, v0, v64, v64
	v_mov_b32_e32 v0, v64
	v_mov_b32_e32 v52, v0
	v_mul_f32_e32 v0, 0xbfb8aa3b, v60
	v_exp_f32_e32 v60, v0
	v_mul_f32_e32 v0, 0xbfb8aa3b, v61
	v_exp_f32_e32 v61, v0
	v_mul_f32_e32 v0, 0xbfb8aa3b, v62
	v_exp_f32_e32 v62, v0
	v_mul_f32_e32 v0, 0xbfb8aa3b, v63
	v_exp_f32_e32 v63, v0
	v_add_u32_e32 v0, 0xde68, v127
	v_add_u32_e32 v66, 0x8128, v128
	ds_read2_b32 v[64:65], v0 offset1:1
	ds_read2_b32 v[66:67], v66 offset1:1
	v_add_u32_e32 v0, 0xde60, v127
	ds_read2_b32 v[68:69], v0 offset1:1
	ds_read2_b32 v[70:71], v70 offset1:1
	v_add_f32_e32 v58, v58, v59
	v_pk_add_f32 v[48:49], v[50:51], v[48:49]
	v_add_f32_e32 v56, v58, v56
	v_pk_mul_f32 v[50:51], v[48:49], v[48:49]
	v_add_f32_e32 v56, v56, v57
	v_add_f32_e32 v50, v56, v50
	v_pk_mul_f32 v[46:47], v[26:27], v[26:27]
	v_add_f32_e32 v50, v50, v51
	s_waitcnt lgkmcnt(0)
	v_pk_add_f32 v[68:69], v[68:69], v[70:71]
	v_add_f32_e32 v46, v50, v46
	v_pk_mul_f32 v[70:71], v[68:69], v[68:69]
	v_add_f32_e32 v46, v46, v47
	v_pk_add_f32 v[64:65], v[64:65], v[66:67]
	v_pk_add_f32 v[60:61], v[60:61], 1.0 op_sel_hi:[1,0]
	v_add_f32_e32 v46, v46, v70
	v_rcp_f32_e32 v0, v61
	v_pk_mul_f32 v[66:67], v[64:65], v[64:65]
	v_add_f32_e32 v46, v46, v71
	s_nop 0
	v_add_f32_e32 v46, v46, v66
	v_pk_mul_f32 v[40:41], v[38:39], v[38:39]
	v_add_f32_e32 v46, v46, v67
	v_pk_add_f32 v[36:37], v[42:43], v[34:35]
	v_add_f32_e32 v40, v46, v40
	v_pk_mul_f32 v[42:43], v[36:37], v[36:37]
	v_add_f32_e32 v40, v40, v41
	v_fma_f32 v77, -v61, v0, 1.0
	v_add_f32_e32 v40, v40, v42
	v_fma_f32 v0, v77, v0, v0
	v_add_f32_e32 v40, v40, v43
	ds_bpermute_b32 v42, v120, v40
	v_mov_b32_e32 v41, v0
	s_waitcnt lgkmcnt(0)
	v_add_f32_e32 v0, v40, v42
	ds_bpermute_b32 v40, v121, v0
	v_rcp_f32_e32 v43, v60
	s_nop 0
	s_mov_b32 s0, 0x800000
	s_waitcnt lgkmcnt(0)
	v_add_f32_e32 v0, v0, v40
	ds_bpermute_b32 v40, v129, v0
	v_fma_f32 v42, -v60, v43, 1.0
	v_fma_f32 v43, v42, v43, v43
	s_waitcnt lgkmcnt(0)
	v_add_f32_e32 v0, v0, v40
	v_fmamk_f32 v0, v0, 0x3c000000, v170
	v_mul_f32_e32 v40, 0x4b800000, v0
	v_cmp_gt_f32_e64 s[0:1], s0, v0
	v_cndmask_b32_e64 v0, v0, v40, s[0:1]
	v_rsq_f32_e32 v0, v0
	v_mov_b32_e32 v42, v43
	v_mov_b32_e32 v40, v42
	v_mul_f32_e32 v42, 0x45800000, v0
	v_cndmask_b32_e64 v0, v0, v42, s[0:1]
	v_pk_mul_f32 v[42:43], v[44:45], v[0:1] op_sel_hi:[1,0]
	v_mov_b32_e32 v40, v40
	v_pk_mul_f32 v[22:23], v[22:23], v[42:43]
	v_lshlrev_b64 v[34:35], 12, v[114:115]
	v_pk_mul_f32 v[28:29], v[28:29], v[22:23]
	v_pk_mul_f32 v[22:23], v[54:55], v[0:1] op_sel_hi:[1,0]
	v_lshl_add_u64 v[34:35], s[28:29], 0, v[34:35]
	v_pk_mul_f32 v[22:23], v[24:25], v[22:23]
	v_pk_add_f32 v[24:25], v[62:63], 1.0 op_sel_hi:[1,0]
	v_pk_mul_f32 v[30:31], v[30:31], v[22:23]
	v_pk_mul_f32 v[22:23], v[48:49], v[0:1] op_sel_hi:[1,0]
	v_lshl_add_u64 v[34:35], v[34:35], 0, s[20:21]
	v_pk_mul_f32 v[18:19], v[18:19], v[22:23]
	s_nop 0
	v_pk_mul_f32 v[22:23], v[32:33], v[18:19]
	v_pk_mul_f32 v[18:19], v[26:27], v[0:1] op_sel_hi:[1,0]
	v_rcp_f32_e32 v26, v25
	v_pk_mul_f32 v[18:19], v[20:21], v[18:19]
	s_nop 0
	v_pk_mul_f32 v[20:21], v[52:53], v[18:19]
	v_pk_mul_f32 v[18:19], v[68:69], v[0:1] op_sel_hi:[1,0]
	v_and_b32_sdwa v33, v28, v195 dst_sel:DWORD dst_unused:UNUSED_PAD src0_sel:WORD_1 src1_sel:DWORD
	v_pk_mul_f32 v[14:15], v[14:15], v[18:19]
	v_add3_u32 v28, v28, v33, s33
	v_pk_mul_f32 v[18:19], v[40:41], v[14:15]
	v_pk_mul_f32 v[14:15], v[64:65], v[0:1] op_sel_hi:[1,0]
	v_and_b32_e32 v28, 0xffff0000, v28
	v_pk_mul_f32 v[14:15], v[16:17], v[14:15]
	v_fma_f32 v16, -v25, v26, 1.0
	v_fma_f32 v26, v16, v26, v26
	v_mov_b32_e32 v16, v26
	v_rcp_f32_e32 v26, v24
	s_nop 0
	v_mov_b32_e32 v17, v16
	v_fma_f32 v16, -v24, v26, 1.0
	v_fma_f32 v26, v16, v26, v26
	v_mov_b32_e32 v16, v26
	v_mul_f32_e32 v26, 0xbfb8aa3b, v72
	v_mul_f32_e32 v27, 0xbfb8aa3b, v73
	v_exp_f32_e32 v26, v26
	v_exp_f32_e32 v27, v27
	v_mov_b32_e32 v16, v16
	v_pk_mul_f32 v[16:17], v[16:17], v[14:15]
	v_pk_add_f32 v[24:25], v[26:27], 1.0 op_sel_hi:[1,0]
; DEVI float bf2f(u16 h) { return __uint_as_float(((unsigned)h) << 16); }
; DEVI float silu_f(float x) { return x / (1.f + __expf(-x)); }
; DEVI float sigm_f(float x) { return 1.f / (1.f + __expf(-x)); }
; __device__ void phase_m3(const P& p, int l) {
;     ...
;       float yo[16];
; #pragma unroll
;       for (int e = 0; e < 16; ++e) {
;         float y = hv[e] * rs * gn[e] * sigm_f(dox[e]);
;         yo[e] = bf2f(f2bf(y)) * silu_f(dgx[e]);
;       }
;       st8(ys, yo);
;       st8(ys + 8, yo + 8);
	v_pk_mul_f32 v[14:15], v[38:39], v[0:1] op_sel_hi:[1,0]
	v_rcp_f32_e32 v26, v25
	s_nop 0
	v_pk_mul_f32 v[10:11], v[10:11], v[14:15]
	v_fma_f32 v14, -v25, v26, 1.0
	v_fma_f32 v26, v14, v26, v26
	v_mov_b32_e32 v14, v26
	v_rcp_f32_e32 v26, v24
	s_nop 0
	v_mov_b32_e32 v15, v14
	v_fma_f32 v14, -v24, v26, 1.0
	v_fma_f32 v26, v14, v26, v26
	v_mov_b32_e32 v14, v26
	v_mul_f32_e32 v26, 0xbfb8aa3b, v74
	v_mul_f32_e32 v27, 0xbfb8aa3b, v75
	v_exp_f32_e32 v26, v26
	v_exp_f32_e32 v27, v27
	v_mov_b32_e32 v14, v14
	v_pk_mul_f32 v[14:15], v[14:15], v[10:11]
	v_pk_add_f32 v[24:25], v[26:27], 1.0 op_sel_hi:[1,0]
	v_pk_mul_f32 v[10:11], v[36:37], v[0:1] op_sel_hi:[1,0]
	v_rcp_f32_e32 v26, v25
	s_nop 0
	v_pk_mul_f32 v[10:11], v[12:13], v[10:11]
	v_fma_f32 v0, -v25, v26, 1.0
	v_fma_f32 v26, v0, v26, v26
	v_mov_b32_e32 v0, v26
	v_rcp_f32_e32 v26, v24
	s_nop 0
	v_mov_b32_e32 v13, v0
	s_mov_b64 s[0:1], 0x2223cc00
	v_fma_f32 v0, -v24, v26, 1.0
	v_fma_f32 v26, v0, v26, v26
	v_mov_b32_e32 v0, v26
	v_mov_b32_e32 v12, v0
	v_lshlrev_b32_e32 v0, 1, v84
	v_lshl_add_u64 v[24:25], v[34:35], 0, v[0:1]
	v_and_b32_e32 v0, 0xffff0000, v6
	v_lshlrev_b32_e32 v6, 16, v6
	v_mul_f32_e32 v26, 0xbfb8aa3b, v6
	v_mul_f32_e32 v27, 0xbfb8aa3b, v0
	v_exp_f32_e32 v26, v26
	v_exp_f32_e32 v27, v27
	v_and_b32_sdwa v32, v29, v195 dst_sel:DWORD dst_unused:UNUSED_PAD src0_sel:WORD_1 src1_sel:DWORD
	v_pk_mul_f32 v[12:13], v[12:13], v[10:11]
	v_lshl_add_u64 v[10:11], v[24:25], 0, s[0:1]
	v_pk_add_f32 v[26:27], v[26:27], 1.0 op_sel_hi:[1,0]
	v_add3_u32 v29, v29, v32, s33
	v_rcp_f32_e32 v32, v27
	s_nop 0
	v_and_b32_e32 v29, 0xffff0000, v29
	v_fma_f32 v33, -v27, v32, 1.0
	v_fma_f32 v32, v33, v32, v32
	v_rcp_f32_e32 v33, v26
	s_nop 0
	v_mul_f32_e32 v27, v0, v32
	v_fma_f32 v0, -v26, v33, 1.0
	v_fma_f32 v33, v0, v33, v33
	v_mov_b32_e32 v0, v33
	v_mul_f32_e32 v26, v6, v0
	v_and_b32_e32 v0, 0xffff0000, v7
	v_lshlrev_b32_e32 v32, 16, v7
	v_mul_f32_e32 v6, 0xbfb8aa3b, v32
	v_mul_f32_e32 v7, 0xbfb8aa3b, v0
	v_exp_f32_e32 v6, v6
	v_exp_f32_e32 v7, v7
	v_pk_mul_f32 v[26:27], v[26:27], v[28:29]
	v_and_b32_sdwa v28, v31, v195 dst_sel:DWORD dst_unused:UNUSED_PAD src0_sel:WORD_1 src1_sel:DWORD
	v_add3_u32 v28, v31, v28, s33
	v_pk_add_f32 v[6:7], v[6:7], 1.0 op_sel_hi:[1,0]
	v_and_b32_sdwa v29, v30, v195 dst_sel:DWORD dst_unused:UNUSED_PAD src0_sel:WORD_1 src1_sel:DWORD
	v_rcp_f32_e32 v31, v7
	s_nop 0
	v_add3_u32 v30, v30, v29, s33
	v_and_b32_e32 v29, 0xffff0000, v28
	v_and_b32_e32 v28, 0xffff0000, v30
	v_fma_f32 v30, -v7, v31, 1.0
	v_fma_f32 v31, v30, v31, v31
	v_mov_b32_e32 v30, v31
	v_rcp_f32_e32 v31, v6
	s_nop 0
	v_mul_f32_e32 v7, v0, v30
	v_fma_f32 v0, -v6, v31, 1.0
	v_fma_f32 v31, v0, v31, v31
	v_mov_b32_e32 v0, v31
	v_mul_f32_e32 v6, v32, v0
	v_and_b32_e32 v0, 0xffff0000, v8
	v_lshlrev_b32_e32 v8, 16, v8
	v_pk_mul_f32 v[6:7], v[6:7], v[28:29]
	v_mul_f32_e32 v28, 0xbfb8aa3b, v8
	v_mul_f32_e32 v29, 0xbfb8aa3b, v0
	v_exp_f32_e32 v28, v28
	v_exp_f32_e32 v29, v29
	v_and_b32_sdwa v30, v23, v195 dst_sel:DWORD dst_unused:UNUSED_PAD src0_sel:WORD_1 src1_sel:DWORD
	v_add3_u32 v23, v23, v30, s33
	v_and_b32_sdwa v31, v22, v195 dst_sel:DWORD dst_unused:UNUSED_PAD src0_sel:WORD_1 src1_sel:DWORD
	v_pk_add_f32 v[28:29], v[28:29], 1.0 op_sel_hi:[1,0]
	v_add3_u32 v22, v22, v31, s33
	v_rcp_f32_e32 v30, v29
	s_nop 0
	v_and_b32_e32 v23, 0xffff0000, v23
	v_and_b32_e32 v22, 0xffff0000, v22
	v_fma_f32 v31, -v29, v30, 1.0
	v_fma_f32 v30, v31, v30, v30
	v_rcp_f32_e32 v31, v28
	s_nop 0
	v_mul_f32_e32 v29, v0, v30
	v_fma_f32 v0, -v28, v31, 1.0
	v_fma_f32 v31, v0, v31, v31
	v_mov_b32_e32 v0, v31
	v_mul_f32_e32 v28, v8, v0
	v_pk_mul_f32 v[22:23], v[28:29], v[22:23]
	v_and_b32_e32 v0, 0xffff0000, v9
	v_lshlrev_b32_e32 v28, 16, v9
	v_mul_f32_e32 v8, 0xbfb8aa3b, v28
	v_mul_f32_e32 v9, 0xbfb8aa3b, v0
	v_exp_f32_e32 v8, v8
	v_exp_f32_e32 v9, v9
	v_and_b32_sdwa v29, v21, v195 dst_sel:DWORD dst_unused:UNUSED_PAD src0_sel:WORD_1 src1_sel:DWORD
	v_add3_u32 v21, v21, v29, s33
	v_and_b32_sdwa v30, v20, v195 dst_sel:DWORD dst_unused:UNUSED_PAD src0_sel:WORD_1 src1_sel:DWORD
	v_pk_add_f32 v[8:9], v[8:9], 1.0 op_sel_hi:[1,0]
	v_add3_u32 v20, v20, v30, s33
	v_rcp_f32_e32 v29, v9
	s_nop 0
	v_and_b32_e32 v21, 0xffff0000, v21
	v_and_b32_e32 v20, 0xffff0000, v20
	v_fma_f32 v30, -v9, v29, 1.0
	v_fma_f32 v29, v30, v29, v29
	v_rcp_f32_e32 v30, v8
	s_nop 0
	v_mul_f32_e32 v9, v0, v29
	v_bfe_u32 v32, v26, 16, 1
	v_fma_f32 v0, -v8, v30, 1.0
	v_fma_f32 v30, v0, v30, v30
	v_mov_b32_e32 v0, v30
	v_mul_f32_e32 v8, v28, v0
	v_pk_mul_f32 v[8:9], v[8:9], v[20:21]
	v_bfe_u32 v21, v23, 16, 1
	v_bfe_u32 v0, v9, 16, 1
	v_bfe_u32 v20, v8, 16, 1
	v_bfe_u32 v28, v22, 16, 1
; DEVI float bf2f(u16 h) { return __uint_as_float(((unsigned)h) << 16); }
; DEVI float silu_f(float x) { return x / (1.f + __expf(-x)); }
; DEVI float sigm_f(float x) { return 1.f / (1.f + __expf(-x)); }
; __device__ void phase_m3(const P& p, int l) {
;     ...
;       float yo[16];
; #pragma unroll
;       for (int e = 0; e < 16; ++e) {
;         float y = hv[e] * rs * gn[e] * sigm_f(dox[e]);
;         yo[e] = bf2f(f2bf(y)) * silu_f(dgx[e]);
;       }
;       st8(ys, yo);
;       st8(ys + 8, yo + 8);
	v_bfe_u32 v29, v7, 16, 1
	v_bfe_u32 v30, v6, 16, 1
	v_bfe_u32 v31, v27, 16, 1
	v_add3_u32 v26, v26, v32, s33
	v_add3_u32 v27, v27, v31, s33
	v_add3_u32 v6, v6, v30, s33
	v_add3_u32 v7, v7, v29, s33
	v_add3_u32 v22, v22, v28, s33
	v_add3_u32 v21, v23, v21, s33
	v_add3_u32 v8, v8, v20, s33
	v_add3_u32 v0, v9, v0, s33
	v_add_co_u32_e32 v20, vcc, s17, v24
	v_perm_b32 v9, v0, v8, s27
	v_perm_b32 v8, v21, v22, s27
	v_perm_b32 v7, v7, v6, s27
	v_perm_b32 v6, v27, v26, s27
	v_addc_co_u32_e32 v21, vcc, 0, v25, vcc
	v_and_b32_e32 v0, 0xffff0000, v2
	v_lshlrev_b32_e32 v2, 16, v2
	global_store_dwordx4 v[20:21], v[6:9], off offset:3072
	s_nop 1
	v_mul_f32_e32 v6, 0xbfb8aa3b, v2
	v_mul_f32_e32 v7, 0xbfb8aa3b, v0
	v_exp_f32_e32 v6, v6
	v_exp_f32_e32 v7, v7
	v_and_b32_sdwa v8, v19, v195 dst_sel:DWORD dst_unused:UNUSED_PAD src0_sel:WORD_1 src1_sel:DWORD
	v_add3_u32 v8, v19, v8, s33
	v_and_b32_sdwa v9, v18, v195 dst_sel:DWORD dst_unused:UNUSED_PAD src0_sel:WORD_1 src1_sel:DWORD
	v_pk_add_f32 v[6:7], v[6:7], 1.0 op_sel_hi:[1,0]
	v_add3_u32 v18, v18, v9, s33
	v_rcp_f32_e32 v19, v7
	s_nop 0
	v_and_b32_e32 v9, 0xffff0000, v8
	v_and_b32_e32 v8, 0xffff0000, v18
	v_fma_f32 v18, -v7, v19, 1.0
	v_fma_f32 v19, v18, v19, v19
	v_mov_b32_e32 v18, v19
	v_rcp_f32_e32 v19, v6
	s_nop 0
	v_mul_f32_e32 v7, v0, v18
	v_fma_f32 v0, -v6, v19, 1.0
	v_fma_f32 v19, v0, v19, v19
	v_mov_b32_e32 v0, v19
	v_mul_f32_e32 v6, v2, v0
	v_and_b32_e32 v0, 0xffff0000, v3
	v_lshlrev_b32_e32 v18, 16, v3
	v_mul_f32_e32 v2, 0xbfb8aa3b, v18
	v_mul_f32_e32 v3, 0xbfb8aa3b, v0
	v_exp_f32_e32 v2, v2
	v_exp_f32_e32 v3, v3
	v_pk_mul_f32 v[6:7], v[6:7], v[8:9]
	v_and_b32_sdwa v8, v17, v195 dst_sel:DWORD dst_unused:UNUSED_PAD src0_sel:WORD_1 src1_sel:DWORD
	v_add3_u32 v8, v17, v8, s33
	v_pk_add_f32 v[2:3], v[2:3], 1.0 op_sel_hi:[1,0]
	v_and_b32_sdwa v9, v16, v195 dst_sel:DWORD dst_unused:UNUSED_PAD src0_sel:WORD_1 src1_sel:DWORD
	v_rcp_f32_e32 v17, v3
	s_nop 0
	v_add3_u32 v16, v16, v9, s33
	v_and_b32_e32 v9, 0xffff0000, v8
	v_and_b32_e32 v8, 0xffff0000, v16
	v_fma_f32 v16, -v3, v17, 1.0
	v_fma_f32 v17, v16, v17, v17
	v_mov_b32_e32 v16, v17
	v_rcp_f32_e32 v17, v2
	s_nop 0
	v_mul_f32_e32 v3, v0, v16
	v_fma_f32 v0, -v2, v17, 1.0
	v_fma_f32 v17, v0, v17, v17
	v_mov_b32_e32 v0, v17
	v_mul_f32_e32 v2, v18, v0
	v_and_b32_e32 v0, 0xffff0000, v4
	v_lshlrev_b32_e32 v4, 16, v4
	v_pk_mul_f32 v[2:3], v[2:3], v[8:9]
	v_mul_f32_e32 v8, 0xbfb8aa3b, v4
	v_mul_f32_e32 v9, 0xbfb8aa3b, v0
	v_exp_f32_e32 v8, v8
	v_exp_f32_e32 v9, v9
	v_and_b32_sdwa v16, v15, v195 dst_sel:DWORD dst_unused:UNUSED_PAD src0_sel:WORD_1 src1_sel:DWORD
	v_add3_u32 v15, v15, v16, s33
	v_and_b32_sdwa v17, v14, v195 dst_sel:DWORD dst_unused:UNUSED_PAD src0_sel:WORD_1 src1_sel:DWORD
	v_pk_add_f32 v[8:9], v[8:9], 1.0 op_sel_hi:[1,0]
	v_add3_u32 v14, v14, v17, s33
	v_rcp_f32_e32 v16, v9
	s_nop 0
	v_and_b32_e32 v15, 0xffff0000, v15
	v_and_b32_e32 v14, 0xffff0000, v14
	v_fma_f32 v17, -v9, v16, 1.0
	v_fma_f32 v16, v17, v16, v16
	v_rcp_f32_e32 v17, v8
	s_nop 0
	v_mul_f32_e32 v9, v0, v16
	v_fma_f32 v0, -v8, v17, 1.0
	v_fma_f32 v17, v0, v17, v17
	v_mov_b32_e32 v0, v17
	v_mul_f32_e32 v8, v4, v0
	v_pk_mul_f32 v[8:9], v[8:9], v[14:15]
	v_and_b32_e32 v0, 0xffff0000, v5
	v_lshlrev_b32_e32 v14, 16, v5
	v_mul_f32_e32 v4, 0xbfb8aa3b, v14
	v_mul_f32_e32 v5, 0xbfb8aa3b, v0
	v_exp_f32_e32 v4, v4
	v_exp_f32_e32 v5, v5
	v_and_b32_sdwa v15, v13, v195 dst_sel:DWORD dst_unused:UNUSED_PAD src0_sel:WORD_1 src1_sel:DWORD
	v_add3_u32 v13, v13, v15, s33
	v_and_b32_sdwa v16, v12, v195 dst_sel:DWORD dst_unused:UNUSED_PAD src0_sel:WORD_1 src1_sel:DWORD
	v_pk_add_f32 v[4:5], v[4:5], 1.0 op_sel_hi:[1,0]
	v_add3_u32 v12, v12, v16, s33
	v_rcp_f32_e32 v15, v5
	s_nop 0
	v_and_b32_e32 v13, 0xffff0000, v13
	v_and_b32_e32 v12, 0xffff0000, v12
	v_fma_f32 v16, -v5, v15, 1.0
	v_fma_f32 v15, v16, v15, v15
	v_rcp_f32_e32 v16, v4
	s_nop 0
	v_mul_f32_e32 v5, v0, v15
	v_bfe_u32 v18, v6, 16, 1
	v_fma_f32 v0, -v4, v16, 1.0
	v_fma_f32 v16, v0, v16, v16
	v_mov_b32_e32 v0, v16
	v_mul_f32_e32 v4, v14, v0
	v_pk_mul_f32 v[4:5], v[4:5], v[12:13]
	v_bfe_u32 v13, v9, 16, 1
	v_bfe_u32 v0, v5, 16, 1
	v_bfe_u32 v12, v4, 16, 1
	v_bfe_u32 v14, v8, 16, 1
	v_bfe_u32 v15, v3, 16, 1
	v_bfe_u32 v16, v2, 16, 1
	v_bfe_u32 v17, v7, 16, 1
	v_add3_u32 v6, v6, v18, s33
	v_add3_u32 v7, v7, v17, s33
	v_add3_u32 v2, v2, v16, s33
	v_add3_u32 v3, v3, v15, s33
	v_add3_u32 v8, v8, v14, s33
	v_add3_u32 v9, v9, v13, s33
	v_add3_u32 v4, v4, v12, s33
	v_add3_u32 v0, v5, v0, s33
	v_perm_b32 v5, v0, v4, s27
	v_perm_b32 v4, v9, v8, s27
	v_perm_b32 v3, v3, v2, s27
	v_perm_b32 v2, v7, v6, s27
	global_store_dwordx4 v[10:11], v[2:5], off offset:16

; template <int DQK, int QT, bool NA> ...
;     ...
;         float mnew = fmaxf(mrun[qt], mx);
;         float alpha = __builtin_amdgcn_exp2f(mrun[qt] - mnew);
;         mrun[qt] = mnew;
;         float ls = 0.f;
; #pragma unroll
;         for (int kt = 0; kt < 4; ++kt)
; #pragma unroll
;           for (int j = 0; j < 4; ++j) {
;             float pv = __builtin_amdgcn_exp2f(s[kt][qt][j] - mnew);
;             ls += pv;
;             s[kt][qt][j] = pv;
;           }
;         lrun[qt] = lrun[qt] * alpha + ls;
;         if (__builtin_amdgcn_ballot_w64(alpha != 1.f)) {
; #pragma unroll
;           for (int dt = 0; dt < 8; ++dt)
; #pragma unroll
;             for (int j = 0; j < 4; ++j) o[dt][qt][j] *= alpha;
;         }
; #pragma unroll
;         for (int kk = 0; kk < 2; ++kk) {
;           union { bf16x8 v; unsigned u[4]; } cv;
;           cv.u[0] = pk2(s[2 * kk][qt][0], s[2 * kk][qt][1]);
;           cv.u[1] = pk2(s[2 * kk][qt][2], s[2 * kk][qt][3]);
;           cv.u[2] = pk2(s[2 * kk + 1][qt][0], s[2 * kk + 1][qt][1]);
;           cv.u[3] = pk2(s[2 * kk + 1][qt][2], s[2 * kk + 1][qt][3]);
;           pf[qt][kk] = cv.v;
;         }
;       }
;       {
;         const u16* vb0 = Vs + l15 * 72 + quad * 4;
;         bf16x4 n0 = *(const bf16x4*)vb0, n1 = *(const bf16x4*)(vb0 + 16);
; #pragma unroll
;         for (int idx = 0; idx < 16; ++idx) {
;           const int kk = idx >> 3, dt = idx & 7;
;           bf16x8 va = {n0[0], n0[1], n0[2], n0[3], n1[0], n1[1], n1[2], n1[3]};
;           if (idx + 1 < 16) {
;             const int kk2 = (idx + 1) >> 3, dt2 = (idx + 1) & 7;
;             const u16* vb = Vs + (dt2 * 16 + l15) * 72 + kk2 * 32 + quad * 4;
;             n0 = *(const bf16x4*)vb;
;             n1 = *(const bf16x4*)(vb + 16);
;           }
; #pragma unroll
;           for (int qt = 0; qt < QT; ++qt) o[dt][qt] = __builtin_amdgcn_mfma_f32_16x16x32_bf16(va, pf[qt][kk], o[dt][qt], 0, 0, 0);
;         }
.LBB0_636:
	v_sub_f32_e32 v2, v20, v35
	v_exp_f32_e32 v20, v2
	v_sub_f32_e32 v2, v19, v35
	v_exp_f32_e32 v19, v2
	v_sub_f32_e32 v2, v22, v35
	v_exp_f32_e32 v22, v2
	v_sub_f32_e32 v2, v21, v35
	v_exp_f32_e32 v21, v2
	v_sub_f32_e32 v2, v24, v35
	v_exp_f32_e32 v24, v2
	v_sub_f32_e32 v2, v23, v35
	v_exp_f32_e32 v23, v2
	v_sub_f32_e32 v2, v26, v35
	v_exp_f32_e32 v26, v2
	v_sub_f32_e32 v2, v25, v35
	v_exp_f32_e32 v25, v2
	v_sub_f32_e32 v2, v28, v35
	v_exp_f32_e32 v28, v2
	v_sub_f32_e32 v2, v27, v35
	v_exp_f32_e32 v27, v2
	v_sub_f32_e32 v2, v30, v35
	v_exp_f32_e32 v30, v2
	v_sub_f32_e32 v2, v29, v35
	v_exp_f32_e32 v29, v2
	v_sub_f32_e32 v2, v32, v35
	v_sub_f32_e32 v109, v109, v16
	v_exp_f32_e32 v32, v2
	v_sub_f32_e32 v2, v31, v35
	v_exp_f32_e32 v109, v109
	v_sub_f32_e32 v108, v108, v16
	v_exp_f32_e32 v31, v2
	v_sub_f32_e32 v2, v34, v35
	v_exp_f32_e32 v108, v108
	v_sub_f32_e32 v43, v43, v16
	v_exp_f32_e32 v34, v2
	v_sub_f32_e32 v2, v33, v35
	v_exp_f32_e32 v43, v43
	v_sub_f32_e32 v42, v42, v16
	v_exp_f32_e32 v33, v2
	v_add_f32_e32 v2, 0, v159
	v_exp_f32_e32 v42, v42
	v_sub_f32_e32 v41, v41, v16
	v_add_f32_e32 v2, v166, v2
	v_add_f32_e32 v110, 0, v109
	v_exp_f32_e32 v41, v41
	v_sub_f32_e32 v40, v40, v16
	v_add_f32_e32 v2, v167, v2
	v_add_f32_e32 v110, v108, v110
	v_exp_f32_e32 v40, v40
	v_sub_f32_e32 v39, v39, v16
	v_add_f32_e32 v2, v168, v2
	v_add_f32_e32 v110, v43, v110
	v_exp_f32_e32 v39, v39
	v_sub_f32_e32 v38, v38, v16
	v_add_f32_e32 v2, v169, v2
	v_add_f32_e32 v110, v42, v110
	v_exp_f32_e32 v38, v38
	v_sub_f32_e32 v37, v37, v16
	v_add_f32_e32 v2, v172, v2
	v_add_f32_e32 v110, v41, v110
	v_exp_f32_e32 v37, v37
	v_sub_f32_e32 v36, v36, v16
	v_add_f32_e32 v2, v173, v2
	v_add_f32_e32 v110, v40, v110
	v_exp_f32_e32 v36, v36
	v_sub_f32_e32 v17, v17, v16
	v_add_f32_e32 v2, v174, v2
	v_add_f32_e32 v110, v39, v110
	v_exp_f32_e32 v17, v17
	v_sub_f32_e32 v15, v15, v16
	v_add_f32_e32 v2, v175, v2
	v_add_f32_e32 v110, v38, v110
	v_exp_f32_e32 v15, v15
	v_sub_f32_e32 v14, v14, v16
	v_add_f32_e32 v2, v176, v2
	v_add_f32_e32 v110, v37, v110
	v_exp_f32_e32 v14, v14
	v_sub_f32_e32 v13, v13, v16
	v_add_f32_e32 v2, v177, v2
	v_add_f32_e32 v110, v36, v110
	v_exp_f32_e32 v111, v13
	v_sub_f32_e32 v12, v12, v16
	v_add_f32_e32 v2, v178, v2
	v_add_f32_e32 v110, v17, v110
	v_exp_f32_e32 v113, v12
	v_sub_f32_e32 v11, v11, v16
	v_add_f32_e32 v2, v179, v2
	v_add_f32_e32 v110, v15, v110
	v_exp_f32_e32 v16, v11
	v_add_f32_e32 v2, v180, v2
	v_add_f32_e32 v110, v14, v110
	v_add_f32_e32 v2, v181, v2
	v_add_f32_e32 v13, v111, v110
	v_add_f32_e32 v35, v204, v2
	v_add_f32_e32 v12, v113, v13
	v_fmac_f32_e32 v35, v165, v140
	v_add_f32_e32 v112, v16, v12
	v_fmac_f32_e32 v112, v35, v10
	v_add_f32_e32 v10, 0, v141
	v_add_f32_e32 v10, v142, v10
	v_add_f32_e32 v10, v143, v10
	v_add_f32_e32 v10, v144, v10
	v_add_f32_e32 v10, v145, v10
	v_add_f32_e32 v10, v146, v10
	v_add_f32_e32 v10, v147, v10
	v_add_f32_e32 v10, v148, v10
	v_add_f32_e32 v10, v149, v10
	v_add_f32_e32 v10, v150, v10
	v_add_f32_e32 v10, v151, v10
	v_add_f32_e32 v10, v152, v10
	v_add_f32_e32 v10, v153, v10
	v_add_f32_e32 v10, v154, v10
	v_add_f32_e32 v10, v155, v10
	v_add_f32_e32 v10, v156, v10
	v_fmac_f32_e32 v10, v164, v0
	v_add_f32_e32 v0, 0, v20
	v_add_f32_e32 v0, v19, v0
	v_add_f32_e32 v0, v22, v0
	v_add_f32_e32 v0, v21, v0
	v_add_f32_e32 v0, v24, v0
	v_add_f32_e32 v0, v23, v0
	v_add_f32_e32 v0, v26, v0
	v_add_f32_e32 v0, v25, v0
	v_add_f32_e32 v0, v28, v0
	v_add_f32_e32 v0, v27, v0
	v_add_f32_e32 v0, v30, v0
	v_add_f32_e32 v0, v29, v0
	v_add_f32_e32 v0, v32, v0
	v_add_f32_e32 v0, v31, v0
	v_add_f32_e32 v0, v34, v0
	v_add_f32_e32 v0, v33, v0
	v_cvt_pk_bf16_f32 v6, v20, v19
	v_cvt_pk_bf16_f32 v7, v22, v21
	v_cvt_pk_bf16_f32 v9, v26, v25
	v_cvt_pk_bf16_f32 v2, v28, v27
	v_cvt_pk_bf16_f32 v3, v30, v29
	v_cvt_pk_bf16_f32 v4, v32, v31
	v_cvt_pk_bf16_f32 v5, v34, v33
	v_fmac_f32_e32 v0, v10, v18
	v_cvt_pk_bf16_f32 v10, v109, v108
	v_cvt_pk_bf16_f32 v109, v17, v15
	v_cvt_pk_bf16_f32 v110, v14, v111
	v_cvt_pk_bf16_f32 v111, v113, v16
	ds_read2_b64 v[14:17], v184 offset0:128 offset1:132
	ds_read2_b64 v[18:21], v187 offset0:160 offset1:164
	ds_read2_b64 v[26:29], v185 offset0:192 offset1:196
	ds_read2_b64 v[30:33], v186 offset0:224 offset1:228
	v_cvt_pk_bf16_f32 v8, v24, v23
	v_cvt_pk_bf16_f32 v11, v43, v42
	v_cvt_pk_bf16_f32 v12, v41, v40
	v_cvt_pk_bf16_f32 v13, v39, v38
	s_waitcnt lgkmcnt(1)
	v_mfma_f32_16x16x32_bf16 v[38:41], v[26:29], v[6:9], v[88:91]
	v_cvt_pk_bf16_f32 v108, v37, v36
	s_lshl_b32 s20, s38, 8
	s_movk_i32 s4, 0xd600
	v_mfma_f32_16x16x32_bf16 v[84:87], v[26:29], v[10:13], v[84:87]
	ds_read2_b64 v[26:29], v188 offset1:4
	s_mov_b32 s5, 0x2223c000
	s_waitcnt lgkmcnt(1)
	v_mfma_f32_16x16x32_bf16 v[80:83], v[30:33], v[6:9], v[80:83]
	v_mfma_f32_16x16x32_bf16 v[76:79], v[30:33], v[10:13], v[76:79]
	ds_read2_b64 v[30:33], v189 offset0:32 offset1:36
	v_mfma_f32_16x16x32_bf16 v[34:37], v[18:21], v[6:9], v[96:99]
	v_mfma_f32_16x16x32_bf16 v[18:21], v[18:21], v[10:13], v[92:95]
	s_waitcnt lgkmcnt(1)
	v_mfma_f32_16x16x32_bf16 v[72:75], v[26:29], v[6:9], v[72:75]
	v_mfma_f32_16x16x32_bf16 v[68:71], v[26:29], v[10:13], v[68:71]
	ds_read2_b64 v[26:29], v190 offset0:64 offset1:68
	s_waitcnt lgkmcnt(1)
	v_mfma_f32_16x16x32_bf16 v[88:91], v[30:33], v[6:9], v[64:67]
	v_mfma_f32_16x16x32_bf16 v[92:95], v[30:33], v[10:13], v[60:63]
	ds_read2_b64 v[30:33], v191 offset0:96 offset1:100
	v_mfma_f32_16x16x32_bf16 v[22:25], v[14:17], v[6:9], v[104:107]
	v_mfma_f32_16x16x32_bf16 v[14:17], v[14:17], v[10:13], v[100:103]
	s_waitcnt lgkmcnt(1)
	v_mfma_f32_16x16x32_bf16 v[96:99], v[26:29], v[6:9], v[56:59]
	v_mfma_f32_16x16x32_bf16 v[100:103], v[26:29], v[10:13], v[52:55]
	ds_read2_b64 v[26:29], v184 offset0:136 offset1:140
	s_waitcnt lgkmcnt(1)
	v_mfma_f32_16x16x32_bf16 v[104:107], v[30:33], v[6:9], v[48:51]
	ds_read2_b64 v[6:9], v187 offset0:168 offset1:172
	v_mfma_f32_16x16x32_bf16 v[114:117], v[30:33], v[10:13], v[44:47]
	ds_read2_b64 v[10:13], v185 offset0:200 offset1:204
	s_waitcnt lgkmcnt(2)
	v_mfma_f32_16x16x32_bf16 v[62:65], v[26:29], v[2:5], v[22:25]
	v_mfma_f32_16x16x32_bf16 v[30:33], v[26:29], v[108:111], v[14:17]
	s_waitcnt lgkmcnt(1)
	v_mfma_f32_16x16x32_bf16 v[58:61], v[6:9], v[2:5], v[34:37]
	v_mfma_f32_16x16x32_bf16 v[26:29], v[6:9], v[108:111], v[18:21]
	ds_read2_b64 v[6:9], v186 offset0:232 offset1:236
	s_nop 0
	ds_read2_b64 v[34:37], v190 offset0:72 offset1:76
	s_waitcnt lgkmcnt(2)
	v_mfma_f32_16x16x32_bf16 v[54:57], v[10:13], v[2:5], v[38:41]
	v_mfma_f32_16x16x32_bf16 v[22:25], v[10:13], v[108:111], v[84:87]
	ds_read2_b64 v[10:13], v188 offset0:8 offset1:12
	s_waitcnt lgkmcnt(2)
	v_mfma_f32_16x16x32_bf16 v[50:53], v[6:9], v[2:5], v[80:83]
	v_mfma_f32_16x16x32_bf16 v[18:21], v[6:9], v[108:111], v[76:79]
	ds_read2_b64 v[6:9], v189 offset0:40 offset1:44
	s_waitcnt lgkmcnt(1)
	v_mfma_f32_16x16x32_bf16 v[14:17], v[10:13], v[108:111], v[68:71]
	s_nop 2
	ds_read2_b64 v[66:69], v191 offset0:104 offset1:108
	v_mfma_f32_16x16x32_bf16 v[46:49], v[10:13], v[2:5], v[72:75]
	s_waitcnt lgkmcnt(0)
	s_barrier
; DEVI float bf2f(u16 h) { return __uint_as_float(((unsigned)h) << 16); }
; DEVI float bfs(short h) { return __uint_as_float(((unsigned)(u16)h) << 16); }
; DEVI float silu_f(float x) { return x / (1.f + __expf(-x)); }
; #define SHX(v, m) __int_as_float(__builtin_amdgcn_ds_bpermute(((LANE ^ (m)) << 2), __float_as_int(v)))
; template <int DQK, int QT, bool NA> ...
;     ...
;   for (int qt = 0; qt < QT; ++qt) {
;     float lt = lrun[qt];
;     lt += SHX(lt, 16);
;     lt += SHX(lt, 32);
;     float il = 1.f / lt;
;     int r = qrow0 + wid * 16 * QT + qt * 16 + l15;
; #pragma unroll
;     for (int dt = 0; dt < 8; ++dt) {
;       int dv = dt * 16 + quad * 4;
;       bf16x4 g = *(const bf16x4*)(proj + (size_t)r * NP + gatecol + h * 128 + dv);
;       bf16x4 ov;
; #pragma unroll
;       for (int j = 0; j < 4; ++j) {
;         float y = bf2f(f2bf(o[dt][qt][j] * il));
;         ov[j] = (short)f2bf(y * silu_f(bfs(g[j])));
;       }
;       *(bf16x4*)(ys + (size_t)r * 2048 + ycol + h * 128 + dv) = ov;
;     }
	s_waitcnt lgkmcnt(1)
	v_mfma_f32_16x16x32_bf16 v[42:45], v[6:9], v[2:5], v[88:91]
	v_mfma_f32_16x16x32_bf16 v[10:13], v[6:9], v[108:111], v[92:95]
	v_mfma_f32_16x16x32_bf16 v[38:41], v[34:37], v[2:5], v[96:99]
	v_mfma_f32_16x16x32_bf16 v[6:9], v[34:37], v[108:111], v[100:103]
	s_waitcnt lgkmcnt(0)
	v_mfma_f32_16x16x32_bf16 v[34:37], v[66:69], v[2:5], v[104:107]
	v_mfma_f32_16x16x32_bf16 v[2:5], v[66:69], v[108:111], v[114:117]
	ds_bpermute_b32 v66, v161, v0
	s_waitcnt lgkmcnt(0)
	v_add_f32_e32 v0, v0, v66
	ds_bpermute_b32 v66, v163, v0
	s_waitcnt lgkmcnt(0)
	v_add_f32_e32 v0, v0, v66
	v_rcp_f32_e32 v66, v0
	s_nop 0
	s_movk_i32 s2, 0x3a00
	s_mov_b32 s3, 0xa28c000
	v_fma_f32 v68, -v0, v66, 1.0
	v_fma_f32 v66, v68, v66, v66
	v_mov_b32_e32 v68, v66
	v_mov_b64_e32 v[66:67], s[0:1]
	v_mad_i64_i32 v[70:71], s[0:1], v162, s2, v[66:67]
	v_lshl_add_u64 v[74:75], v[70:71], 0, s[20:21]
	v_lshlrev_b32_e32 v0, 1, v182
	v_mad_i64_i32 v[70:71], s[0:1], v162, s4, v[70:71]
	v_lshl_add_u64 v[74:75], v[74:75], 0, v[0:1]
	v_lshl_add_u64 v[72:73], v[70:71], 0, s[20:21]
	v_lshl_add_u64 v[70:71], v[74:75], 0, s[14:15]
	v_add_co_u32_e32 v74, vcc, s3, v74
	v_pk_mul_f32 v[62:63], v[62:63], v[68:69] op_sel_hi:[1,0]
	s_nop 0
	v_addc_co_u32_e32 v75, vcc, 0, v75, vcc
	global_load_dwordx2 v[74:75], v[74:75], off offset:128
	v_and_b32_sdwa v77, v63, v195 dst_sel:DWORD dst_unused:UNUSED_PAD src0_sel:WORD_1 src1_sel:DWORD
	v_add3_u32 v63, v63, v77, s33
	v_and_b32_sdwa v78, v62, v195 dst_sel:DWORD dst_unused:UNUSED_PAD src0_sel:WORD_1 src1_sel:DWORD
	v_add3_u32 v62, v62, v78, s33
	v_and_b32_e32 v63, 0xffff0000, v63
	v_and_b32_e32 v62, 0xffff0000, v62
	v_lshl_add_u64 v[72:73], v[72:73], 0, v[0:1]
	s_waitcnt vmcnt(0)
	v_and_b32_e32 v69, 0xffff0000, v74
	v_lshlrev_b32_e32 v74, 16, v74
	v_mul_f32_e32 v76, 0xbfb8aa3b, v74
	v_mul_f32_e32 v77, 0xbfb8aa3b, v69
	v_exp_f32_e32 v76, v76
	v_exp_f32_e32 v77, v77
	s_nop 0
	v_pk_add_f32 v[76:77], v[76:77], 1.0 op_sel_hi:[1,0]
	s_nop 0
	v_rcp_f32_e32 v78, v77
	s_nop 0
	s_nop 0
	v_fma_f32 v80, -v77, v78, 1.0
	v_fma_f32 v78, v80, v78, v78
	v_mul_f32_e32 v77, v69, v78
	v_rcp_f32_e32 v69, v76
	s_nop 0
	s_nop 0
	v_fma_f32 v79, -v76, v69, 1.0
	v_fma_f32 v69, v79, v69, v69
	v_mul_f32_e32 v76, v74, v69
	v_pk_mul_f32 v[64:65], v[64:65], v[68:69] op_sel_hi:[1,0]
	v_pk_mul_f32 v[62:63], v[76:77], v[62:63]
	v_and_b32_e32 v69, 0xffff0000, v75
	v_lshlrev_b32_e32 v76, 16, v75
	v_and_b32_sdwa v75, v65, v195 dst_sel:DWORD dst_unused:UNUSED_PAD src0_sel:WORD_1 src1_sel:DWORD
	v_mul_f32_e32 v74, 0xbfb8aa3b, v76
	v_add3_u32 v65, v65, v75, s33
	v_mul_f32_e32 v75, 0xbfb8aa3b, v69
	v_exp_f32_e32 v74, v74
	v_exp_f32_e32 v75, v75
	v_and_b32_sdwa v77, v64, v195 dst_sel:DWORD dst_unused:UNUSED_PAD src0_sel:WORD_1 src1_sel:DWORD
	v_add3_u32 v64, v64, v77, s33
	v_and_b32_e32 v65, 0xffff0000, v65
	v_pk_add_f32 v[74:75], v[74:75], 1.0 op_sel_hi:[1,0]
	v_and_b32_e32 v64, 0xffff0000, v64
	v_rcp_f32_e32 v77, v75
	s_nop 0
	s_nop 0
	v_fma_f32 v79, -v75, v77, 1.0
	v_fma_f32 v77, v79, v77, v77
	v_mul_f32_e32 v75, v69, v77
	v_rcp_f32_e32 v69, v74
	s_nop 0
	s_nop 0
	v_fma_f32 v78, -v74, v69, 1.0
	v_fma_f32 v69, v78, v69, v69
	v_mul_f32_e32 v74, v76, v69
	v_pk_mul_f32 v[64:65], v[74:75], v[64:65]
	v_bfe_u32 v75, v63, 16, 1
	v_bfe_u32 v69, v65, 16, 1
	v_bfe_u32 v74, v64, 16, 1
	v_bfe_u32 v76, v62, 16, 1
	v_add3_u32 v64, v64, v74, s33
	v_add3_u32 v65, v65, v69, s33
	v_add3_u32 v62, v62, v76, s33
	v_add3_u32 v63, v63, v75, s33
	v_perm_b32 v65, v65, v64, s27
	v_perm_b32 v64, v63, v62, s27
	v_lshl_add_u64 v[62:63], v[72:73], 0, s[16:17]
	v_add_co_u32_e32 v72, vcc, s5, v72
	v_pk_mul_f32 v[58:59], v[58:59], v[68:69] op_sel_hi:[1,0]
	s_nop 0
	v_addc_co_u32_e32 v73, vcc, 0, v73, vcc
	global_store_dwordx2 v[72:73], v[64:65], off offset:2048
	global_load_dwordx2 v[64:65], v[70:71], off offset:32
	v_and_b32_sdwa v73, v59, v195 dst_sel:DWORD dst_unused:UNUSED_PAD src0_sel:WORD_1 src1_sel:DWORD
	v_add3_u32 v59, v59, v73, s33
	v_and_b32_sdwa v74, v58, v195 dst_sel:DWORD dst_unused:UNUSED_PAD src0_sel:WORD_1 src1_sel:DWORD
	v_add3_u32 v58, v58, v74, s33
	v_and_b32_e32 v59, 0xffff0000, v59
	v_and_b32_e32 v58, 0xffff0000, v58
	s_waitcnt vmcnt(0)
	v_and_b32_e32 v69, 0xffff0000, v64
	v_lshlrev_b32_e32 v64, 16, v64
	v_mul_f32_e32 v72, 0xbfb8aa3b, v64
	v_mul_f32_e32 v73, 0xbfb8aa3b, v69
	v_exp_f32_e32 v72, v72
	v_exp_f32_e32 v73, v73
	s_nop 0
	v_pk_add_f32 v[72:73], v[72:73], 1.0 op_sel_hi:[1,0]
	s_nop 0
	v_rcp_f32_e32 v74, v73
	s_nop 0
	s_nop 0
	v_fma_f32 v76, -v73, v74, 1.0
	v_fma_f32 v74, v76, v74, v74
	v_mul_f32_e32 v73, v69, v74
	v_rcp_f32_e32 v69, v72
	s_nop 0
	s_nop 0
	v_fma_f32 v75, -v72, v69, 1.0
	v_fma_f32 v69, v75, v69, v69
	v_mul_f32_e32 v72, v64, v69
	v_pk_mul_f32 v[60:61], v[60:61], v[68:69] op_sel_hi:[1,0]
	v_pk_mul_f32 v[58:59], v[72:73], v[58:59]
	v_and_b32_e32 v69, 0xffff0000, v65
	v_lshlrev_b32_e32 v72, 16, v65
	v_and_b32_sdwa v65, v61, v195 dst_sel:DWORD dst_unused:UNUSED_PAD src0_sel:WORD_1 src1_sel:DWORD
	v_mul_f32_e32 v64, 0xbfb8aa3b, v72
	v_add3_u32 v61, v61, v65, s33
	v_mul_f32_e32 v65, 0xbfb8aa3b, v69
	v_exp_f32_e32 v64, v64
	v_exp_f32_e32 v65, v65
	v_and_b32_sdwa v73, v60, v195 dst_sel:DWORD dst_unused:UNUSED_PAD src0_sel:WORD_1 src1_sel:DWORD
	v_add3_u32 v60, v60, v73, s33
	v_and_b32_e32 v61, 0xffff0000, v61
	v_pk_add_f32 v[64:65], v[64:65], 1.0 op_sel_hi:[1,0]
	v_and_b32_e32 v60, 0xffff0000, v60
	v_rcp_f32_e32 v73, v65
	s_nop 0
	s_nop 0
	v_fma_f32 v75, -v65, v73, 1.0
	v_fma_f32 v73, v75, v73, v73
	v_mul_f32_e32 v65, v69, v73
	v_rcp_f32_e32 v69, v64
	s_nop 0
	s_nop 0
	v_fma_f32 v74, -v64, v69, 1.0
	v_fma_f32 v69, v74, v69, v69
	v_mul_f32_e32 v64, v72, v69
	v_pk_mul_f32 v[60:61], v[64:65], v[60:61]
	v_bfe_u32 v69, v59, 16, 1
	v_bfe_u32 v64, v61, 16, 1
	v_bfe_u32 v65, v60, 16, 1
	v_bfe_u32 v72, v58, 16, 1
	v_add3_u32 v60, v60, v65, s33
	v_add3_u32 v61, v61, v64, s33
	v_add3_u32 v58, v58, v72, s33
	v_add3_u32 v64, v59, v69, s33
	v_perm_b32 v59, v61, v60, s27
	v_perm_b32 v58, v64, v58, s27
	global_store_dwordx2 v[62:63], v[58:59], off offset:32
	global_load_dwordx2 v[58:59], v[70:71], off offset:64
	v_pk_mul_f32 v[54:55], v[54:55], v[68:69] op_sel_hi:[1,0]
	s_waitcnt vmcnt(0)
; DEVI float bf2f(u16 h) { return __uint_as_float(((unsigned)h) << 16); }
; DEVI float bfs(short h) { return __uint_as_float(((unsigned)(u16)h) << 16); }
; DEVI float silu_f(float x) { return x / (1.f + __expf(-x)); }
; template <int DQK, int QT, bool NA> ...
;     ...
;     for (int dt = 0; dt < 8; ++dt) {
;       int dv = dt * 16 + quad * 4;
;       bf16x4 g = *(const bf16x4*)(proj + (size_t)r * NP + gatecol + h * 128 + dv);
;       bf16x4 ov;
; #pragma unroll
;       for (int j = 0; j < 4; ++j) {
;         float y = bf2f(f2bf(o[dt][qt][j] * il));
;         ov[j] = (short)f2bf(y * silu_f(bfs(g[j])));
;       }
;       *(bf16x4*)(ys + (size_t)r * 2048 + ycol + h * 128 + dv) = ov;
;     }
	v_and_b32_e32 v64, 0xffff0000, v58
	v_lshlrev_b32_e32 v58, 16, v58
	v_and_b32_sdwa v61, v55, v195 dst_sel:DWORD dst_unused:UNUSED_PAD src0_sel:WORD_1 src1_sel:DWORD
	v_mul_f32_e32 v60, 0xbfb8aa3b, v58
	v_add3_u32 v55, v55, v61, s33
	v_mul_f32_e32 v61, 0xbfb8aa3b, v64
	v_exp_f32_e32 v60, v60
	v_exp_f32_e32 v61, v61
	v_and_b32_sdwa v65, v54, v195 dst_sel:DWORD dst_unused:UNUSED_PAD src0_sel:WORD_1 src1_sel:DWORD
	v_add3_u32 v54, v54, v65, s33
	v_and_b32_e32 v55, 0xffff0000, v55
	v_pk_add_f32 v[60:61], v[60:61], 1.0 op_sel_hi:[1,0]
	v_and_b32_e32 v54, 0xffff0000, v54
	v_rcp_f32_e32 v65, v61
	s_nop 0
	s_nop 0
	v_fma_f32 v72, -v61, v65, 1.0
	v_fma_f32 v65, v72, v65, v65
	v_mul_f32_e32 v61, v64, v65
	v_rcp_f32_e32 v64, v60
	s_nop 0
	s_nop 0
	v_fma_f32 v69, -v60, v64, 1.0
	v_fma_f32 v64, v69, v64, v64
	v_mul_f32_e32 v60, v58, v64
	v_pk_mul_f32 v[56:57], v[56:57], v[68:69] op_sel_hi:[1,0]
	v_pk_mul_f32 v[54:55], v[60:61], v[54:55]
	v_and_b32_e32 v60, 0xffff0000, v59
	v_lshlrev_b32_e32 v61, 16, v59
	v_and_b32_sdwa v59, v57, v195 dst_sel:DWORD dst_unused:UNUSED_PAD src0_sel:WORD_1 src1_sel:DWORD
	v_mul_f32_e32 v58, 0xbfb8aa3b, v61
	v_add3_u32 v57, v57, v59, s33
	v_mul_f32_e32 v59, 0xbfb8aa3b, v60
	v_exp_f32_e32 v58, v58
	v_exp_f32_e32 v59, v59
	v_and_b32_sdwa v64, v56, v195 dst_sel:DWORD dst_unused:UNUSED_PAD src0_sel:WORD_1 src1_sel:DWORD
	v_add3_u32 v56, v56, v64, s33
	v_and_b32_e32 v57, 0xffff0000, v57
	v_pk_add_f32 v[58:59], v[58:59], 1.0 op_sel_hi:[1,0]
	v_and_b32_e32 v56, 0xffff0000, v56
	v_rcp_f32_e32 v64, v59
	s_nop 0
	s_nop 0
	v_fma_f32 v69, -v59, v64, 1.0
	v_fma_f32 v64, v69, v64, v64
	v_mul_f32_e32 v59, v60, v64
	v_rcp_f32_e32 v60, v58
	s_nop 0
	s_nop 0
	v_fma_f32 v65, -v58, v60, 1.0
	v_fma_f32 v60, v65, v60, v60
	v_mul_f32_e32 v58, v61, v60
	v_pk_mul_f32 v[56:57], v[58:59], v[56:57]
	v_bfe_u32 v60, v55, 16, 1
	v_bfe_u32 v58, v57, 16, 1
	v_bfe_u32 v59, v56, 16, 1
	v_bfe_u32 v61, v54, 16, 1
	v_add3_u32 v56, v56, v59, s33
	v_add3_u32 v57, v57, v58, s33
	v_add3_u32 v54, v54, v61, s33
	v_add3_u32 v58, v55, v60, s33
	v_perm_b32 v55, v57, v56, s27
	v_perm_b32 v54, v58, v54, s27
	global_store_dwordx2 v[62:63], v[54:55], off offset:64
	global_load_dwordx2 v[54:55], v[70:71], off offset:96
	v_pk_mul_f32 v[50:51], v[50:51], v[68:69] op_sel_hi:[1,0]
	v_pk_mul_f32 v[52:53], v[52:53], v[68:69] op_sel_hi:[1,0]
	v_and_b32_sdwa v57, v51, v195 dst_sel:DWORD dst_unused:UNUSED_PAD src0_sel:WORD_1 src1_sel:DWORD
	v_add3_u32 v51, v51, v57, s33
	v_and_b32_sdwa v59, v50, v195 dst_sel:DWORD dst_unused:UNUSED_PAD src0_sel:WORD_1 src1_sel:DWORD
	v_add3_u32 v50, v50, v59, s33
	v_and_b32_e32 v51, 0xffff0000, v51
	v_and_b32_e32 v50, 0xffff0000, v50
	v_pk_mul_f32 v[46:47], v[46:47], v[68:69] op_sel_hi:[1,0]
	v_pk_mul_f32 v[48:49], v[48:49], v[68:69] op_sel_hi:[1,0]
	v_pk_mul_f32 v[42:43], v[42:43], v[68:69] op_sel_hi:[1,0]
	v_pk_mul_f32 v[44:45], v[44:45], v[68:69] op_sel_hi:[1,0]
	v_pk_mul_f32 v[38:39], v[38:39], v[68:69] op_sel_hi:[1,0]
	v_pk_mul_f32 v[40:41], v[40:41], v[68:69] op_sel_hi:[1,0]
	v_pk_mul_f32 v[34:35], v[34:35], v[68:69] op_sel_hi:[1,0]
	v_pk_mul_f32 v[36:37], v[36:37], v[68:69] op_sel_hi:[1,0]
	s_waitcnt vmcnt(0)
	v_and_b32_e32 v58, 0xffff0000, v54
	v_lshlrev_b32_e32 v54, 16, v54
	v_mul_f32_e32 v56, 0xbfb8aa3b, v54
	v_mul_f32_e32 v57, 0xbfb8aa3b, v58
	v_exp_f32_e32 v56, v56
	v_exp_f32_e32 v57, v57
	s_nop 0
	v_pk_add_f32 v[56:57], v[56:57], 1.0 op_sel_hi:[1,0]
	s_nop 0
	v_rcp_f32_e32 v59, v57
	s_nop 0
	s_nop 0
	v_fma_f32 v61, -v57, v59, 1.0
	v_fma_f32 v59, v61, v59, v59
	v_mul_f32_e32 v57, v58, v59
	v_rcp_f32_e32 v58, v56
	s_nop 0
	s_nop 0
	v_fma_f32 v60, -v56, v58, 1.0
	v_fma_f32 v58, v60, v58, v58
	v_mul_f32_e32 v56, v54, v58
	v_pk_mul_f32 v[50:51], v[56:57], v[50:51]
	v_and_b32_e32 v56, 0xffff0000, v55
	v_lshlrev_b32_e32 v57, 16, v55
	v_and_b32_sdwa v55, v53, v195 dst_sel:DWORD dst_unused:UNUSED_PAD src0_sel:WORD_1 src1_sel:DWORD
	v_mul_f32_e32 v54, 0xbfb8aa3b, v57
	v_add3_u32 v53, v53, v55, s33
	v_mul_f32_e32 v55, 0xbfb8aa3b, v56
	v_exp_f32_e32 v54, v54
	v_exp_f32_e32 v55, v55
	v_and_b32_sdwa v58, v52, v195 dst_sel:DWORD dst_unused:UNUSED_PAD src0_sel:WORD_1 src1_sel:DWORD
	v_add3_u32 v52, v52, v58, s33
	v_and_b32_e32 v53, 0xffff0000, v53
	v_pk_add_f32 v[54:55], v[54:55], 1.0 op_sel_hi:[1,0]
	v_and_b32_e32 v52, 0xffff0000, v52
	v_rcp_f32_e32 v58, v55
	s_nop 0
	s_nop 0
	v_fma_f32 v60, -v55, v58, 1.0
	v_fma_f32 v58, v60, v58, v58
	v_mul_f32_e32 v55, v56, v58
	v_rcp_f32_e32 v56, v54
	s_nop 0
	s_nop 0
	v_fma_f32 v59, -v54, v56, 1.0
	v_fma_f32 v56, v59, v56, v56
	v_mul_f32_e32 v54, v57, v56
	v_pk_mul_f32 v[52:53], v[54:55], v[52:53]
	v_bfe_u32 v56, v51, 16, 1
	v_bfe_u32 v54, v53, 16, 1
	v_bfe_u32 v55, v52, 16, 1
	v_bfe_u32 v57, v50, 16, 1
	v_add3_u32 v52, v52, v55, s33
	v_add3_u32 v53, v53, v54, s33
	v_add3_u32 v50, v50, v57, s33
	v_add3_u32 v54, v51, v56, s33
	v_perm_b32 v51, v53, v52, s27
	v_perm_b32 v50, v54, v50, s27
	global_store_dwordx2 v[62:63], v[50:51], off offset:96
	global_load_dwordx2 v[50:51], v[70:71], off offset:128
	v_and_b32_sdwa v53, v47, v195 dst_sel:DWORD dst_unused:UNUSED_PAD src0_sel:WORD_1 src1_sel:DWORD
	v_add3_u32 v47, v47, v53, s33
	v_and_b32_sdwa v55, v46, v195 dst_sel:DWORD dst_unused:UNUSED_PAD src0_sel:WORD_1 src1_sel:DWORD
	v_add3_u32 v46, v46, v55, s33
	v_and_b32_e32 v47, 0xffff0000, v47
	v_and_b32_e32 v46, 0xffff0000, v46
	s_waitcnt vmcnt(0)
; DEVI float bf2f(u16 h) { return __uint_as_float(((unsigned)h) << 16); }
; DEVI float bfs(short h) { return __uint_as_float(((unsigned)(u16)h) << 16); }
; DEVI float silu_f(float x) { return x / (1.f + __expf(-x)); }
; template <int DQK, int QT, bool NA> ...
;     ...
;     for (int dt = 0; dt < 8; ++dt) {
;       int dv = dt * 16 + quad * 4;
;       bf16x4 g = *(const bf16x4*)(proj + (size_t)r * NP + gatecol + h * 128 + dv);
;       bf16x4 ov;
; #pragma unroll
;       for (int j = 0; j < 4; ++j) {
;         float y = bf2f(f2bf(o[dt][qt][j] * il));
;         ov[j] = (short)f2bf(y * silu_f(bfs(g[j])));
;       }
;       *(bf16x4*)(ys + (size_t)r * 2048 + ycol + h * 128 + dv) = ov;
;     }
	v_and_b32_e32 v54, 0xffff0000, v50
	v_lshlrev_b32_e32 v50, 16, v50
	v_mul_f32_e32 v52, 0xbfb8aa3b, v50
	v_mul_f32_e32 v53, 0xbfb8aa3b, v54
	v_exp_f32_e32 v52, v52
	v_exp_f32_e32 v53, v53
	s_nop 0
	v_pk_add_f32 v[52:53], v[52:53], 1.0 op_sel_hi:[1,0]
	s_nop 0
	v_rcp_f32_e32 v55, v53
	s_nop 0
	s_nop 0
	v_fma_f32 v57, -v53, v55, 1.0
	v_fma_f32 v55, v57, v55, v55
	v_mul_f32_e32 v53, v54, v55
	v_rcp_f32_e32 v54, v52
	s_nop 0
	s_nop 0
	v_fma_f32 v56, -v52, v54, 1.0
	v_fma_f32 v54, v56, v54, v54
	v_mul_f32_e32 v52, v50, v54
	v_pk_mul_f32 v[46:47], v[52:53], v[46:47]
	v_and_b32_e32 v52, 0xffff0000, v51
	v_lshlrev_b32_e32 v53, 16, v51
	v_and_b32_sdwa v51, v49, v195 dst_sel:DWORD dst_unused:UNUSED_PAD src0_sel:WORD_1 src1_sel:DWORD
	v_mul_f32_e32 v50, 0xbfb8aa3b, v53
	v_add3_u32 v49, v49, v51, s33
	v_mul_f32_e32 v51, 0xbfb8aa3b, v52
	v_exp_f32_e32 v50, v50
	v_exp_f32_e32 v51, v51
	v_and_b32_sdwa v54, v48, v195 dst_sel:DWORD dst_unused:UNUSED_PAD src0_sel:WORD_1 src1_sel:DWORD
	v_add3_u32 v48, v48, v54, s33
	v_and_b32_e32 v49, 0xffff0000, v49
	v_pk_add_f32 v[50:51], v[50:51], 1.0 op_sel_hi:[1,0]
	v_and_b32_e32 v48, 0xffff0000, v48
	v_rcp_f32_e32 v54, v51
	s_nop 0
	s_nop 0
	v_fma_f32 v56, -v51, v54, 1.0
	v_fma_f32 v54, v56, v54, v54
	v_mul_f32_e32 v51, v52, v54
	v_rcp_f32_e32 v52, v50
	s_nop 0
	s_nop 0
	v_fma_f32 v55, -v50, v52, 1.0
	v_fma_f32 v52, v55, v52, v52
	v_mul_f32_e32 v50, v53, v52
	v_pk_mul_f32 v[48:49], v[50:51], v[48:49]
	v_bfe_u32 v52, v47, 16, 1
	v_bfe_u32 v50, v49, 16, 1
	v_bfe_u32 v51, v48, 16, 1
	v_bfe_u32 v53, v46, 16, 1
	v_add3_u32 v48, v48, v51, s33
	v_add3_u32 v49, v49, v50, s33
	v_add3_u32 v46, v46, v53, s33
	v_add3_u32 v50, v47, v52, s33
	v_perm_b32 v47, v49, v48, s27
	v_perm_b32 v46, v50, v46, s27
	global_store_dwordx2 v[62:63], v[46:47], off offset:128
	global_load_dwordx2 v[46:47], v[70:71], off offset:160
	v_and_b32_sdwa v49, v43, v195 dst_sel:DWORD dst_unused:UNUSED_PAD src0_sel:WORD_1 src1_sel:DWORD
	v_add3_u32 v43, v43, v49, s33
	v_and_b32_sdwa v51, v42, v195 dst_sel:DWORD dst_unused:UNUSED_PAD src0_sel:WORD_1 src1_sel:DWORD
	v_add3_u32 v42, v42, v51, s33
	v_and_b32_e32 v43, 0xffff0000, v43
	v_and_b32_e32 v42, 0xffff0000, v42
	s_waitcnt vmcnt(0)
	v_and_b32_e32 v50, 0xffff0000, v46
	v_lshlrev_b32_e32 v46, 16, v46
	v_mul_f32_e32 v48, 0xbfb8aa3b, v46
	v_mul_f32_e32 v49, 0xbfb8aa3b, v50
	v_exp_f32_e32 v48, v48
	v_exp_f32_e32 v49, v49
	s_nop 0
	v_pk_add_f32 v[48:49], v[48:49], 1.0 op_sel_hi:[1,0]
	s_nop 0
	v_rcp_f32_e32 v51, v49
	s_nop 0
	s_nop 0
	v_fma_f32 v53, -v49, v51, 1.0
	v_fma_f32 v51, v53, v51, v51
	v_mul_f32_e32 v49, v50, v51
	v_rcp_f32_e32 v50, v48
	s_nop 0
	s_nop 0
	v_fma_f32 v52, -v48, v50, 1.0
	v_fma_f32 v50, v52, v50, v50
	v_mul_f32_e32 v48, v46, v50
	v_pk_mul_f32 v[42:43], v[48:49], v[42:43]
	v_and_b32_e32 v48, 0xffff0000, v47
	v_lshlrev_b32_e32 v49, 16, v47
	v_and_b32_sdwa v47, v45, v195 dst_sel:DWORD dst_unused:UNUSED_PAD src0_sel:WORD_1 src1_sel:DWORD
	v_mul_f32_e32 v46, 0xbfb8aa3b, v49
	v_add3_u32 v45, v45, v47, s33
	v_mul_f32_e32 v47, 0xbfb8aa3b, v48
	v_exp_f32_e32 v46, v46
	v_exp_f32_e32 v47, v47
	v_and_b32_sdwa v50, v44, v195 dst_sel:DWORD dst_unused:UNUSED_PAD src0_sel:WORD_1 src1_sel:DWORD
	v_add3_u32 v44, v44, v50, s33
	v_and_b32_e32 v45, 0xffff0000, v45
	v_pk_add_f32 v[46:47], v[46:47], 1.0 op_sel_hi:[1,0]
	v_and_b32_e32 v44, 0xffff0000, v44
	v_rcp_f32_e32 v50, v47
	s_nop 0
	s_nop 0
	v_fma_f32 v52, -v47, v50, 1.0
	v_fma_f32 v50, v52, v50, v50
	v_mul_f32_e32 v47, v48, v50
	v_rcp_f32_e32 v48, v46
	s_nop 0
	s_nop 0
	v_fma_f32 v51, -v46, v48, 1.0
	v_fma_f32 v48, v51, v48, v48
	v_mul_f32_e32 v46, v49, v48
	v_pk_mul_f32 v[44:45], v[46:47], v[44:45]
	v_bfe_u32 v48, v43, 16, 1
	v_bfe_u32 v46, v45, 16, 1
	v_bfe_u32 v47, v44, 16, 1
	v_bfe_u32 v49, v42, 16, 1
	v_add3_u32 v44, v44, v47, s33
	v_add3_u32 v45, v45, v46, s33
	v_add3_u32 v42, v42, v49, s33
	v_add3_u32 v46, v43, v48, s33
	v_perm_b32 v43, v45, v44, s27
	v_perm_b32 v42, v46, v42, s27
	global_store_dwordx2 v[62:63], v[42:43], off offset:160
	global_load_dwordx2 v[42:43], v[70:71], off offset:192
	v_and_b32_sdwa v45, v39, v195 dst_sel:DWORD dst_unused:UNUSED_PAD src0_sel:WORD_1 src1_sel:DWORD
	v_add3_u32 v39, v39, v45, s33
	v_and_b32_sdwa v47, v38, v195 dst_sel:DWORD dst_unused:UNUSED_PAD src0_sel:WORD_1 src1_sel:DWORD
	v_add3_u32 v38, v38, v47, s33
	v_and_b32_e32 v39, 0xffff0000, v39
	v_and_b32_e32 v38, 0xffff0000, v38
	s_waitcnt vmcnt(0)
	v_and_b32_e32 v46, 0xffff0000, v42
	v_lshlrev_b32_e32 v42, 16, v42
	v_mul_f32_e32 v44, 0xbfb8aa3b, v42
	v_mul_f32_e32 v45, 0xbfb8aa3b, v46
	v_exp_f32_e32 v44, v44
	v_exp_f32_e32 v45, v45
	s_nop 0
	v_pk_add_f32 v[44:45], v[44:45], 1.0 op_sel_hi:[1,0]
	s_nop 0
	v_rcp_f32_e32 v47, v45
	s_nop 0
	s_nop 0
	v_fma_f32 v49, -v45, v47, 1.0
	v_fma_f32 v47, v49, v47, v47
	v_mul_f32_e32 v45, v46, v47
	v_rcp_f32_e32 v46, v44
	s_nop 0
	s_nop 0
	v_fma_f32 v48, -v44, v46, 1.0
	v_fma_f32 v46, v48, v46, v46
	v_mul_f32_e32 v44, v42, v46
	v_pk_mul_f32 v[38:39], v[44:45], v[38:39]
	v_and_b32_e32 v44, 0xffff0000, v43
	v_lshlrev_b32_e32 v45, 16, v43
	v_and_b32_sdwa v43, v41, v195 dst_sel:DWORD dst_unused:UNUSED_PAD src0_sel:WORD_1 src1_sel:DWORD
	v_mul_f32_e32 v42, 0xbfb8aa3b, v45
	v_add3_u32 v41, v41, v43, s33
	v_mul_f32_e32 v43, 0xbfb8aa3b, v44
	v_exp_f32_e32 v42, v42
	v_exp_f32_e32 v43, v43
	v_and_b32_sdwa v46, v40, v195 dst_sel:DWORD dst_unused:UNUSED_PAD src0_sel:WORD_1 src1_sel:DWORD
	v_add3_u32 v40, v40, v46, s33
	v_and_b32_e32 v41, 0xffff0000, v41
	v_pk_add_f32 v[42:43], v[42:43], 1.0 op_sel_hi:[1,0]
	v_and_b32_e32 v40, 0xffff0000, v40
	v_rcp_f32_e32 v46, v43
	s_nop 0
	s_nop 0
	v_fma_f32 v48, -v43, v46, 1.0
	v_fma_f32 v46, v48, v46, v46
	v_mul_f32_e32 v43, v44, v46
	v_rcp_f32_e32 v44, v42
	s_nop 0
	s_nop 0
	v_fma_f32 v47, -v42, v44, 1.0
	v_fma_f32 v44, v47, v44, v44
	v_mul_f32_e32 v42, v45, v44
	v_pk_mul_f32 v[40:41], v[42:43], v[40:41]
	v_bfe_u32 v44, v39, 16, 1
	v_bfe_u32 v42, v41, 16, 1
	v_bfe_u32 v43, v40, 16, 1
	v_bfe_u32 v45, v38, 16, 1
	v_add3_u32 v40, v40, v43, s33
	v_add3_u32 v41, v41, v42, s33
	v_add3_u32 v38, v38, v45, s33
	v_add3_u32 v42, v39, v44, s33
	v_perm_b32 v39, v41, v40, s27
	v_perm_b32 v38, v42, v38, s27
	global_store_dwordx2 v[62:63], v[38:39], off offset:192
	global_load_dwordx2 v[38:39], v[70:71], off offset:224
	v_and_b32_sdwa v41, v35, v195 dst_sel:DWORD dst_unused:UNUSED_PAD src0_sel:WORD_1 src1_sel:DWORD
	v_add3_u32 v35, v35, v41, s33
	v_and_b32_sdwa v43, v34, v195 dst_sel:DWORD dst_unused:UNUSED_PAD src0_sel:WORD_1 src1_sel:DWORD
	v_add3_u32 v34, v34, v43, s33
	v_and_b32_e32 v35, 0xffff0000, v35
	v_and_b32_e32 v34, 0xffff0000, v34
	s_waitcnt vmcnt(0)
; DEVI float bf2f(u16 h) { return __uint_as_float(((unsigned)h) << 16); }
; DEVI float bfs(short h) { return __uint_as_float(((unsigned)(u16)h) << 16); }
; DEVI float silu_f(float x) { return x / (1.f + __expf(-x)); }
; #define SHX(v, m) __int_as_float(__builtin_amdgcn_ds_bpermute(((LANE ^ (m)) << 2), __float_as_int(v)))
; template <int DQK, int QT, bool NA> ...
;     ...
;   for (int qt = 0; qt < QT; ++qt) {
;     float lt = lrun[qt];
;     lt += SHX(lt, 16);
;     lt += SHX(lt, 32);
;     float il = 1.f / lt;
;     int r = qrow0 + wid * 16 * QT + qt * 16 + l15;
; #pragma unroll
;     for (int dt = 0; dt < 8; ++dt) {
;       int dv = dt * 16 + quad * 4;
;       bf16x4 g = *(const bf16x4*)(proj + (size_t)r * NP + gatecol + h * 128 + dv);
;       bf16x4 ov;
; #pragma unroll
;       for (int j = 0; j < 4; ++j) {
;         float y = bf2f(f2bf(o[dt][qt][j] * il));
;         ov[j] = (short)f2bf(y * silu_f(bfs(g[j])));
;       }
;       *(bf16x4*)(ys + (size_t)r * 2048 + ycol + h * 128 + dv) = ov;
;     }
	v_and_b32_e32 v42, 0xffff0000, v38
	v_lshlrev_b32_e32 v38, 16, v38
	v_mul_f32_e32 v40, 0xbfb8aa3b, v38
	v_mul_f32_e32 v41, 0xbfb8aa3b, v42
	v_exp_f32_e32 v40, v40
	v_exp_f32_e32 v41, v41
	s_nop 0
	v_pk_add_f32 v[40:41], v[40:41], 1.0 op_sel_hi:[1,0]
	s_nop 0
	v_rcp_f32_e32 v43, v41
	s_nop 0
	s_nop 0
	v_fma_f32 v45, -v41, v43, 1.0
	v_fma_f32 v43, v45, v43, v43
	v_mul_f32_e32 v41, v42, v43
	v_rcp_f32_e32 v42, v40
	s_nop 0
	s_nop 0
	v_fma_f32 v44, -v40, v42, 1.0
	v_fma_f32 v42, v44, v42, v42
	v_mul_f32_e32 v40, v38, v42
	v_pk_mul_f32 v[34:35], v[40:41], v[34:35]
	v_and_b32_e32 v40, 0xffff0000, v39
	v_lshlrev_b32_e32 v41, 16, v39
	v_and_b32_sdwa v39, v37, v195 dst_sel:DWORD dst_unused:UNUSED_PAD src0_sel:WORD_1 src1_sel:DWORD
	v_mul_f32_e32 v38, 0xbfb8aa3b, v41
	v_add3_u32 v37, v37, v39, s33
	v_mul_f32_e32 v39, 0xbfb8aa3b, v40
	v_exp_f32_e32 v38, v38
	v_exp_f32_e32 v39, v39
	v_and_b32_sdwa v42, v36, v195 dst_sel:DWORD dst_unused:UNUSED_PAD src0_sel:WORD_1 src1_sel:DWORD
	v_add3_u32 v36, v36, v42, s33
	v_and_b32_e32 v37, 0xffff0000, v37
	v_pk_add_f32 v[38:39], v[38:39], 1.0 op_sel_hi:[1,0]
	v_and_b32_e32 v36, 0xffff0000, v36
	v_rcp_f32_e32 v42, v39
	s_nop 0
	s_nop 0
	v_fma_f32 v44, -v39, v42, 1.0
	v_fma_f32 v42, v44, v42, v42
	v_mul_f32_e32 v39, v40, v42
	v_rcp_f32_e32 v40, v38
	s_nop 0
	s_nop 0
	v_fma_f32 v43, -v38, v40, 1.0
	v_fma_f32 v40, v43, v40, v40
	v_mul_f32_e32 v38, v41, v40
	v_pk_mul_f32 v[36:37], v[38:39], v[36:37]
	v_bfe_u32 v40, v35, 16, 1
	v_bfe_u32 v38, v37, 16, 1
	v_bfe_u32 v39, v36, 16, 1
	v_bfe_u32 v41, v34, 16, 1
	v_add3_u32 v36, v36, v39, s33
	v_add3_u32 v37, v37, v38, s33
	v_add3_u32 v34, v34, v41, s33
	v_add3_u32 v38, v35, v40, s33
	v_perm_b32 v35, v37, v36, s27
	v_perm_b32 v34, v38, v34, s27
	global_store_dwordx2 v[62:63], v[34:35], off offset:224
	ds_bpermute_b32 v34, v161, v112
	s_waitcnt lgkmcnt(0)
	v_add_f32_e32 v34, v112, v34
	ds_bpermute_b32 v35, v163, v34
	s_waitcnt lgkmcnt(0)
	v_add_f32_e32 v34, v34, v35
	v_rcp_f32_e32 v35, v34
	s_nop 0
	s_nop 0
	v_fma_f32 v37, -v34, v35, 1.0
	v_fma_f32 v35, v37, v35, v35
	v_mad_i64_i32 v[36:37], s[0:1], v160, s2, v[66:67]
	v_lshl_add_u64 v[40:41], v[36:37], 0, s[20:21]
	v_mad_i64_i32 v[36:37], s[0:1], v160, s4, v[36:37]
	v_lshl_add_u64 v[40:41], v[40:41], 0, v[0:1]
	v_lshl_add_u64 v[38:39], v[36:37], 0, s[20:21]
	v_lshl_add_u64 v[36:37], v[40:41], 0, s[14:15]
	v_add_co_u32_e32 v40, vcc, s3, v40
	v_mov_b32_e32 v34, v35
	s_nop 0
	v_addc_co_u32_e32 v41, vcc, 0, v41, vcc
	global_load_dwordx2 v[40:41], v[40:41], off offset:128
	v_pk_mul_f32 v[30:31], v[30:31], v[34:35] op_sel_hi:[1,0]
	v_lshl_add_u64 v[38:39], v[38:39], 0, v[0:1]
	v_and_b32_sdwa v43, v31, v195 dst_sel:DWORD dst_unused:UNUSED_PAD src0_sel:WORD_1 src1_sel:DWORD
	v_add3_u32 v31, v31, v43, s33
	v_and_b32_sdwa v44, v30, v195 dst_sel:DWORD dst_unused:UNUSED_PAD src0_sel:WORD_1 src1_sel:DWORD
	v_add3_u32 v30, v30, v44, s33
	v_and_b32_e32 v31, 0xffff0000, v31
	v_and_b32_e32 v30, 0xffff0000, v30
	s_waitcnt vmcnt(0)
	v_and_b32_e32 v35, 0xffff0000, v40
	v_lshlrev_b32_e32 v40, 16, v40
	v_mul_f32_e32 v42, 0xbfb8aa3b, v40
	v_mul_f32_e32 v43, 0xbfb8aa3b, v35
	v_exp_f32_e32 v42, v42
	v_exp_f32_e32 v43, v43
	s_nop 0
	v_pk_add_f32 v[42:43], v[42:43], 1.0 op_sel_hi:[1,0]
	s_nop 0
	v_rcp_f32_e32 v44, v43
	s_nop 0
	s_nop 0
	v_fma_f32 v46, -v43, v44, 1.0
	v_fma_f32 v44, v46, v44, v44
	v_mul_f32_e32 v43, v35, v44
	v_rcp_f32_e32 v35, v42
	s_nop 0
	s_nop 0
	v_fma_f32 v45, -v42, v35, 1.0
	v_fma_f32 v35, v45, v35, v35
	v_mul_f32_e32 v42, v40, v35
	v_pk_mul_f32 v[32:33], v[32:33], v[34:35] op_sel_hi:[1,0]
	v_pk_mul_f32 v[30:31], v[42:43], v[30:31]
	v_and_b32_e32 v35, 0xffff0000, v41
	v_lshlrev_b32_e32 v42, 16, v41
	v_and_b32_sdwa v41, v33, v195 dst_sel:DWORD dst_unused:UNUSED_PAD src0_sel:WORD_1 src1_sel:DWORD
	v_mul_f32_e32 v40, 0xbfb8aa3b, v42
	v_add3_u32 v33, v33, v41, s33
	v_mul_f32_e32 v41, 0xbfb8aa3b, v35
	v_exp_f32_e32 v40, v40
	v_exp_f32_e32 v41, v41
	v_and_b32_sdwa v43, v32, v195 dst_sel:DWORD dst_unused:UNUSED_PAD src0_sel:WORD_1 src1_sel:DWORD
	v_add3_u32 v32, v32, v43, s33
	v_and_b32_e32 v33, 0xffff0000, v33
	v_pk_add_f32 v[40:41], v[40:41], 1.0 op_sel_hi:[1,0]
	v_and_b32_e32 v32, 0xffff0000, v32
	v_rcp_f32_e32 v43, v41
	s_nop 0
	s_nop 0
	v_fma_f32 v45, -v41, v43, 1.0
	v_fma_f32 v43, v45, v43, v43
	v_mul_f32_e32 v41, v35, v43
	v_rcp_f32_e32 v35, v40
	s_nop 0
	s_nop 0
	v_fma_f32 v44, -v40, v35, 1.0
	v_fma_f32 v35, v44, v35, v35
	v_mul_f32_e32 v40, v42, v35
	v_pk_mul_f32 v[32:33], v[40:41], v[32:33]
	v_bfe_u32 v41, v31, 16, 1
	v_bfe_u32 v35, v33, 16, 1
	v_bfe_u32 v40, v32, 16, 1
	v_bfe_u32 v42, v30, 16, 1
	v_add3_u32 v32, v32, v40, s33
	v_add3_u32 v33, v33, v35, s33
	v_add3_u32 v30, v30, v42, s33
	v_add3_u32 v31, v31, v41, s33
	v_perm_b32 v33, v33, v32, s27
	v_perm_b32 v32, v31, v30, s27
	v_lshl_add_u64 v[30:31], v[38:39], 0, s[16:17]
	v_add_co_u32_e32 v38, vcc, s5, v38
	v_pk_mul_f32 v[26:27], v[26:27], v[34:35] op_sel_hi:[1,0]
	s_nop 0
	v_addc_co_u32_e32 v39, vcc, 0, v39, vcc
	global_store_dwordx2 v[38:39], v[32:33], off offset:2048
	global_load_dwordx2 v[32:33], v[36:37], off offset:32
	v_and_b32_sdwa v39, v26, v195 dst_sel:DWORD dst_unused:UNUSED_PAD src0_sel:WORD_1 src1_sel:DWORD
	v_add3_u32 v26, v26, v39, s33
	v_and_b32_e32 v26, 0xffff0000, v26
	s_waitcnt vmcnt(0)
; DEVI float bf2f(u16 h) { return __uint_as_float(((unsigned)h) << 16); }
; DEVI float bfs(short h) { return __uint_as_float(((unsigned)(u16)h) << 16); }
; DEVI float silu_f(float x) { return x / (1.f + __expf(-x)); }
; template <int DQK, int QT, bool NA> ...
;     ...
;     for (int dt = 0; dt < 8; ++dt) {
;       int dv = dt * 16 + quad * 4;
;       bf16x4 g = *(const bf16x4*)(proj + (size_t)r * NP + gatecol + h * 128 + dv);
;       bf16x4 ov;
; #pragma unroll
;       for (int j = 0; j < 4; ++j) {
;         float y = bf2f(f2bf(o[dt][qt][j] * il));
;         ov[j] = (short)f2bf(y * silu_f(bfs(g[j])));
;       }
;       *(bf16x4*)(ys + (size_t)r * 2048 + ycol + h * 128 + dv) = ov;
;     }
	v_and_b32_e32 v0, 0xffff0000, v32
	v_lshlrev_b32_e32 v32, 16, v32
	v_mul_f32_e32 v35, 0xbfb8aa3b, v32
	v_exp_f32_e32 v38, v35
	v_and_b32_sdwa v35, v27, v195 dst_sel:DWORD dst_unused:UNUSED_PAD src0_sel:WORD_1 src1_sel:DWORD
	v_add3_u32 v27, v27, v35, s33
	v_mul_f32_e32 v35, 0xbfb8aa3b, v0
	v_exp_f32_e32 v39, v35
	v_and_b32_e32 v27, 0xffff0000, v27
	v_pk_add_f32 v[38:39], v[38:39], 1.0 op_sel_hi:[1,0]
	s_nop 0
	v_rcp_f32_e32 v35, v39
	s_nop 0
	s_nop 0
	v_fma_f32 v41, -v39, v35, 1.0
	v_fma_f32 v35, v41, v35, v35
	v_mul_f32_e32 v39, v0, v35
	v_rcp_f32_e32 v0, v38
	s_nop 0
	s_nop 0
	v_fma_f32 v40, -v38, v0, 1.0
	v_fma_f32 v0, v40, v0, v0
	v_pk_mul_f32 v[28:29], v[28:29], v[34:35] op_sel_hi:[1,0]
	v_mul_f32_e32 v38, v32, v0
	v_and_b32_e32 v0, 0xffff0000, v33
	v_lshlrev_b32_e32 v35, 16, v33
	v_and_b32_sdwa v33, v29, v195 dst_sel:DWORD dst_unused:UNUSED_PAD src0_sel:WORD_1 src1_sel:DWORD
	v_mul_f32_e32 v32, 0xbfb8aa3b, v35
	v_add3_u32 v29, v29, v33, s33
	v_mul_f32_e32 v33, 0xbfb8aa3b, v0
	v_exp_f32_e32 v32, v32
	v_exp_f32_e32 v33, v33
	v_pk_mul_f32 v[26:27], v[38:39], v[26:27]
	v_and_b32_sdwa v38, v28, v195 dst_sel:DWORD dst_unused:UNUSED_PAD src0_sel:WORD_1 src1_sel:DWORD
	v_add3_u32 v28, v28, v38, s33
	v_pk_add_f32 v[32:33], v[32:33], 1.0 op_sel_hi:[1,0]
	v_and_b32_e32 v29, 0xffff0000, v29
	v_rcp_f32_e32 v38, v33
	s_nop 0
	v_and_b32_e32 v28, 0xffff0000, v28
	v_fma_f32 v40, -v33, v38, 1.0
	v_fma_f32 v38, v40, v38, v38
	v_mul_f32_e32 v33, v0, v38
	v_rcp_f32_e32 v0, v32
	s_nop 0
	s_nop 0
	v_fma_f32 v39, -v32, v0, 1.0
	v_fma_f32 v0, v39, v0, v0
	v_mul_f32_e32 v32, v35, v0
	v_pk_mul_f32 v[28:29], v[32:33], v[28:29]
	v_bfe_u32 v33, v27, 16, 1
	v_bfe_u32 v0, v29, 16, 1
	v_bfe_u32 v32, v28, 16, 1
	v_bfe_u32 v35, v26, 16, 1
	v_add3_u32 v28, v28, v32, s33
	v_add3_u32 v0, v29, v0, s33
	v_add3_u32 v26, v26, v35, s33
	v_add3_u32 v29, v27, v33, s33
	v_perm_b32 v27, v0, v28, s27
	v_perm_b32 v26, v29, v26, s27
	global_store_dwordx2 v[30:31], v[26:27], off offset:32
	global_load_dwordx2 v[26:27], v[36:37], off offset:64
	v_pk_mul_f32 v[22:23], v[22:23], v[34:35] op_sel_hi:[1,0]
	s_waitcnt vmcnt(0)
	v_and_b32_e32 v0, 0xffff0000, v26
	v_lshlrev_b32_e32 v26, 16, v26
	v_and_b32_sdwa v29, v23, v195 dst_sel:DWORD dst_unused:UNUSED_PAD src0_sel:WORD_1 src1_sel:DWORD
	v_mul_f32_e32 v28, 0xbfb8aa3b, v26
	v_add3_u32 v23, v23, v29, s33
	v_mul_f32_e32 v29, 0xbfb8aa3b, v0
	v_exp_f32_e32 v28, v28
	v_exp_f32_e32 v29, v29
	v_and_b32_sdwa v32, v22, v195 dst_sel:DWORD dst_unused:UNUSED_PAD src0_sel:WORD_1 src1_sel:DWORD
	v_add3_u32 v22, v22, v32, s33
	v_and_b32_e32 v23, 0xffff0000, v23
	v_pk_add_f32 v[28:29], v[28:29], 1.0 op_sel_hi:[1,0]
	v_and_b32_e32 v22, 0xffff0000, v22
	v_rcp_f32_e32 v32, v29
	s_nop 0
	s_nop 0
	v_fma_f32 v35, -v29, v32, 1.0
	v_fma_f32 v32, v35, v32, v32
	v_mul_f32_e32 v29, v0, v32
	v_rcp_f32_e32 v0, v28
	s_nop 0
	s_nop 0
	v_fma_f32 v33, -v28, v0, 1.0
	v_fma_f32 v0, v33, v0, v0
	v_mul_f32_e32 v28, v26, v0
	v_pk_mul_f32 v[24:25], v[24:25], v[34:35] op_sel_hi:[1,0]
	v_pk_mul_f32 v[22:23], v[28:29], v[22:23]
	v_and_b32_e32 v0, 0xffff0000, v27
	v_lshlrev_b32_e32 v28, 16, v27
	v_and_b32_sdwa v27, v25, v195 dst_sel:DWORD dst_unused:UNUSED_PAD src0_sel:WORD_1 src1_sel:DWORD
	v_mul_f32_e32 v26, 0xbfb8aa3b, v28
	v_add3_u32 v25, v25, v27, s33
	v_mul_f32_e32 v27, 0xbfb8aa3b, v0
	v_exp_f32_e32 v26, v26
	v_exp_f32_e32 v27, v27
	v_and_b32_sdwa v29, v24, v195 dst_sel:DWORD dst_unused:UNUSED_PAD src0_sel:WORD_1 src1_sel:DWORD
	v_add3_u32 v24, v24, v29, s33
	v_and_b32_e32 v25, 0xffff0000, v25
	v_pk_add_f32 v[26:27], v[26:27], 1.0 op_sel_hi:[1,0]
	v_and_b32_e32 v24, 0xffff0000, v24
	v_rcp_f32_e32 v29, v27
	s_nop 0
	s_nop 0
	v_fma_f32 v33, -v27, v29, 1.0
	v_fma_f32 v29, v33, v29, v29
	v_mul_f32_e32 v27, v0, v29
	v_rcp_f32_e32 v0, v26
	s_nop 0
	s_nop 0
	v_fma_f32 v32, -v26, v0, 1.0
	v_fma_f32 v0, v32, v0, v0
	v_mul_f32_e32 v26, v28, v0
	v_pk_mul_f32 v[24:25], v[26:27], v[24:25]
	v_bfe_u32 v27, v23, 16, 1
	v_bfe_u32 v0, v25, 16, 1
	v_bfe_u32 v26, v24, 16, 1
	v_bfe_u32 v28, v22, 16, 1
	v_add3_u32 v24, v24, v26, s33
	v_add3_u32 v0, v25, v0, s33
	v_add3_u32 v22, v22, v28, s33
	v_add3_u32 v25, v23, v27, s33
	v_perm_b32 v23, v0, v24, s27
	v_perm_b32 v22, v25, v22, s27
	global_store_dwordx2 v[30:31], v[22:23], off offset:64
	global_load_dwordx2 v[22:23], v[36:37], off offset:96
	v_pk_mul_f32 v[18:19], v[18:19], v[34:35] op_sel_hi:[1,0]
	v_pk_mul_f32 v[20:21], v[20:21], v[34:35] op_sel_hi:[1,0]
	v_and_b32_sdwa v25, v19, v195 dst_sel:DWORD dst_unused:UNUSED_PAD src0_sel:WORD_1 src1_sel:DWORD
	v_add3_u32 v19, v19, v25, s33
	v_and_b32_sdwa v26, v18, v195 dst_sel:DWORD dst_unused:UNUSED_PAD src0_sel:WORD_1 src1_sel:DWORD
	v_add3_u32 v18, v18, v26, s33
	v_and_b32_e32 v19, 0xffff0000, v19
	v_and_b32_e32 v18, 0xffff0000, v18
	v_pk_mul_f32 v[14:15], v[14:15], v[34:35] op_sel_hi:[1,0]
	v_pk_mul_f32 v[16:17], v[16:17], v[34:35] op_sel_hi:[1,0]
	v_pk_mul_f32 v[10:11], v[10:11], v[34:35] op_sel_hi:[1,0]
	v_pk_mul_f32 v[12:13], v[12:13], v[34:35] op_sel_hi:[1,0]
	v_pk_mul_f32 v[6:7], v[6:7], v[34:35] op_sel_hi:[1,0]
	v_pk_mul_f32 v[8:9], v[8:9], v[34:35] op_sel_hi:[1,0]
	v_pk_mul_f32 v[2:3], v[2:3], v[34:35] op_sel_hi:[1,0]
	v_pk_mul_f32 v[4:5], v[4:5], v[34:35] op_sel_hi:[1,0]
	s_waitcnt vmcnt(0)
; DEVI float bf2f(u16 h) { return __uint_as_float(((unsigned)h) << 16); }
; DEVI float bfs(short h) { return __uint_as_float(((unsigned)(u16)h) << 16); }
; DEVI float silu_f(float x) { return x / (1.f + __expf(-x)); }
; template <int DQK, int QT, bool NA> ...
;     ...
;     for (int dt = 0; dt < 8; ++dt) {
;       int dv = dt * 16 + quad * 4;
;       bf16x4 g = *(const bf16x4*)(proj + (size_t)r * NP + gatecol + h * 128 + dv);
;       bf16x4 ov;
; #pragma unroll
;       for (int j = 0; j < 4; ++j) {
;         float y = bf2f(f2bf(o[dt][qt][j] * il));
;         ov[j] = (short)f2bf(y * silu_f(bfs(g[j])));
;       }
;       *(bf16x4*)(ys + (size_t)r * 2048 + ycol + h * 128 + dv) = ov;
;     }
	v_and_b32_e32 v0, 0xffff0000, v22
	v_lshlrev_b32_e32 v22, 16, v22
	v_mul_f32_e32 v24, 0xbfb8aa3b, v22
	v_mul_f32_e32 v25, 0xbfb8aa3b, v0
	v_exp_f32_e32 v24, v24
	v_exp_f32_e32 v25, v25
	s_nop 0
	v_pk_add_f32 v[24:25], v[24:25], 1.0 op_sel_hi:[1,0]
	s_nop 0
	v_rcp_f32_e32 v26, v25
	s_nop 0
	s_nop 0
	v_fma_f32 v28, -v25, v26, 1.0
	v_fma_f32 v26, v28, v26, v26
	v_mul_f32_e32 v25, v0, v26
	v_rcp_f32_e32 v0, v24
	s_nop 0
	s_nop 0
	v_fma_f32 v27, -v24, v0, 1.0
	v_fma_f32 v0, v27, v0, v0
	v_mul_f32_e32 v24, v22, v0
	v_pk_mul_f32 v[18:19], v[24:25], v[18:19]
	v_and_b32_e32 v0, 0xffff0000, v23
	v_lshlrev_b32_e32 v24, 16, v23
	v_and_b32_sdwa v23, v21, v195 dst_sel:DWORD dst_unused:UNUSED_PAD src0_sel:WORD_1 src1_sel:DWORD
	v_mul_f32_e32 v22, 0xbfb8aa3b, v24
	v_add3_u32 v21, v21, v23, s33
	v_mul_f32_e32 v23, 0xbfb8aa3b, v0
	v_exp_f32_e32 v22, v22
	v_exp_f32_e32 v23, v23
	v_and_b32_sdwa v25, v20, v195 dst_sel:DWORD dst_unused:UNUSED_PAD src0_sel:WORD_1 src1_sel:DWORD
	v_add3_u32 v20, v20, v25, s33
	v_and_b32_e32 v21, 0xffff0000, v21
	v_pk_add_f32 v[22:23], v[22:23], 1.0 op_sel_hi:[1,0]
	v_and_b32_e32 v20, 0xffff0000, v20
	v_rcp_f32_e32 v25, v23
	s_nop 0
	s_nop 0
	v_fma_f32 v27, -v23, v25, 1.0
	v_fma_f32 v25, v27, v25, v25
	v_mul_f32_e32 v23, v0, v25
	v_rcp_f32_e32 v0, v22
	s_nop 0
	s_nop 0
	v_fma_f32 v26, -v22, v0, 1.0
	v_fma_f32 v0, v26, v0, v0
	v_mul_f32_e32 v22, v24, v0
	v_pk_mul_f32 v[20:21], v[22:23], v[20:21]
	v_bfe_u32 v23, v19, 16, 1
	v_bfe_u32 v0, v21, 16, 1
	v_bfe_u32 v22, v20, 16, 1
	v_bfe_u32 v24, v18, 16, 1
	v_add3_u32 v20, v20, v22, s33
	v_add3_u32 v0, v21, v0, s33
	v_add3_u32 v18, v18, v24, s33
	v_add3_u32 v21, v19, v23, s33
	v_perm_b32 v19, v0, v20, s27
	v_perm_b32 v18, v21, v18, s27
	global_store_dwordx2 v[30:31], v[18:19], off offset:96
	global_load_dwordx2 v[18:19], v[36:37], off offset:128
	v_and_b32_sdwa v21, v15, v195 dst_sel:DWORD dst_unused:UNUSED_PAD src0_sel:WORD_1 src1_sel:DWORD
	v_add3_u32 v15, v15, v21, s33
	v_and_b32_sdwa v22, v14, v195 dst_sel:DWORD dst_unused:UNUSED_PAD src0_sel:WORD_1 src1_sel:DWORD
	v_add3_u32 v14, v14, v22, s33
	v_and_b32_e32 v15, 0xffff0000, v15
	v_and_b32_e32 v14, 0xffff0000, v14
	s_waitcnt vmcnt(0)
	v_and_b32_e32 v0, 0xffff0000, v18
	v_lshlrev_b32_e32 v18, 16, v18
	v_mul_f32_e32 v20, 0xbfb8aa3b, v18
	v_mul_f32_e32 v21, 0xbfb8aa3b, v0
	v_exp_f32_e32 v20, v20
	v_exp_f32_e32 v21, v21
	s_nop 0
	v_pk_add_f32 v[20:21], v[20:21], 1.0 op_sel_hi:[1,0]
	s_nop 0
	v_rcp_f32_e32 v22, v21
	s_nop 0
	s_nop 0
	v_fma_f32 v24, -v21, v22, 1.0
	v_fma_f32 v22, v24, v22, v22
	v_mul_f32_e32 v21, v0, v22
	v_rcp_f32_e32 v0, v20
	s_nop 0
	s_nop 0
	v_fma_f32 v23, -v20, v0, 1.0
	v_fma_f32 v0, v23, v0, v0
	v_mul_f32_e32 v20, v18, v0
	v_pk_mul_f32 v[14:15], v[20:21], v[14:15]
	v_and_b32_e32 v0, 0xffff0000, v19
	v_lshlrev_b32_e32 v20, 16, v19
	v_and_b32_sdwa v19, v17, v195 dst_sel:DWORD dst_unused:UNUSED_PAD src0_sel:WORD_1 src1_sel:DWORD
	v_mul_f32_e32 v18, 0xbfb8aa3b, v20
	v_add3_u32 v17, v17, v19, s33
	v_mul_f32_e32 v19, 0xbfb8aa3b, v0
	v_exp_f32_e32 v18, v18
	v_exp_f32_e32 v19, v19
	v_and_b32_sdwa v21, v16, v195 dst_sel:DWORD dst_unused:UNUSED_PAD src0_sel:WORD_1 src1_sel:DWORD
	v_add3_u32 v16, v16, v21, s33
	v_and_b32_e32 v17, 0xffff0000, v17
	v_pk_add_f32 v[18:19], v[18:19], 1.0 op_sel_hi:[1,0]
	v_and_b32_e32 v16, 0xffff0000, v16
	v_rcp_f32_e32 v21, v19
	s_nop 0
	s_nop 0
	v_fma_f32 v23, -v19, v21, 1.0
	v_fma_f32 v21, v23, v21, v21
	v_mul_f32_e32 v19, v0, v21
	v_rcp_f32_e32 v0, v18
	s_nop 0
	s_nop 0
	v_fma_f32 v22, -v18, v0, 1.0
	v_fma_f32 v0, v22, v0, v0
	v_mul_f32_e32 v18, v20, v0
	v_pk_mul_f32 v[16:17], v[18:19], v[16:17]
	v_bfe_u32 v19, v15, 16, 1
	v_bfe_u32 v0, v17, 16, 1
	v_bfe_u32 v18, v16, 16, 1
	v_bfe_u32 v20, v14, 16, 1
	v_add3_u32 v16, v16, v18, s33
	v_add3_u32 v0, v17, v0, s33
	v_add3_u32 v14, v14, v20, s33
	v_add3_u32 v17, v15, v19, s33
	v_perm_b32 v15, v0, v16, s27
	v_perm_b32 v14, v17, v14, s27
	global_store_dwordx2 v[30:31], v[14:15], off offset:128
	global_load_dwordx2 v[14:15], v[36:37], off offset:160
	v_and_b32_sdwa v17, v11, v195 dst_sel:DWORD dst_unused:UNUSED_PAD src0_sel:WORD_1 src1_sel:DWORD
	v_add3_u32 v11, v11, v17, s33
	v_and_b32_sdwa v18, v10, v195 dst_sel:DWORD dst_unused:UNUSED_PAD src0_sel:WORD_1 src1_sel:DWORD
	v_add3_u32 v10, v10, v18, s33
	v_and_b32_e32 v11, 0xffff0000, v11
	v_and_b32_e32 v10, 0xffff0000, v10
	s_waitcnt vmcnt(0)
; DEVI float bf2f(u16 h) { return __uint_as_float(((unsigned)h) << 16); }
; DEVI float bfs(short h) { return __uint_as_float(((unsigned)(u16)h) << 16); }
; DEVI float silu_f(float x) { return x / (1.f + __expf(-x)); }
; template <int DQK, int QT, bool NA> ...
;     ...
;     for (int dt = 0; dt < 8; ++dt) {
;       int dv = dt * 16 + quad * 4;
;       bf16x4 g = *(const bf16x4*)(proj + (size_t)r * NP + gatecol + h * 128 + dv);
;       bf16x4 ov;
; #pragma unroll
;       for (int j = 0; j < 4; ++j) {
;         float y = bf2f(f2bf(o[dt][qt][j] * il));
;         ov[j] = (short)f2bf(y * silu_f(bfs(g[j])));
;       }
;       *(bf16x4*)(ys + (size_t)r * 2048 + ycol + h * 128 + dv) = ov;
;     }
	v_and_b32_e32 v0, 0xffff0000, v14
	v_lshlrev_b32_e32 v14, 16, v14
	v_mul_f32_e32 v16, 0xbfb8aa3b, v14
	v_mul_f32_e32 v17, 0xbfb8aa3b, v0
	v_exp_f32_e32 v16, v16
	v_exp_f32_e32 v17, v17
	s_nop 0
	v_pk_add_f32 v[16:17], v[16:17], 1.0 op_sel_hi:[1,0]
	s_nop 0
	v_rcp_f32_e32 v18, v17
	s_nop 0
	s_nop 0
	v_fma_f32 v20, -v17, v18, 1.0
	v_fma_f32 v18, v20, v18, v18
	v_mul_f32_e32 v17, v0, v18
	v_rcp_f32_e32 v0, v16
	s_nop 0
	s_nop 0
	v_fma_f32 v19, -v16, v0, 1.0
	v_fma_f32 v0, v19, v0, v0
	v_mul_f32_e32 v16, v14, v0
	v_pk_mul_f32 v[10:11], v[16:17], v[10:11]
	v_and_b32_e32 v0, 0xffff0000, v15
	v_lshlrev_b32_e32 v16, 16, v15
	v_and_b32_sdwa v15, v13, v195 dst_sel:DWORD dst_unused:UNUSED_PAD src0_sel:WORD_1 src1_sel:DWORD
	v_mul_f32_e32 v14, 0xbfb8aa3b, v16
	v_add3_u32 v13, v13, v15, s33
	v_mul_f32_e32 v15, 0xbfb8aa3b, v0
	v_exp_f32_e32 v14, v14
	v_exp_f32_e32 v15, v15
	v_and_b32_sdwa v17, v12, v195 dst_sel:DWORD dst_unused:UNUSED_PAD src0_sel:WORD_1 src1_sel:DWORD
	v_add3_u32 v12, v12, v17, s33
	v_and_b32_e32 v13, 0xffff0000, v13
	v_pk_add_f32 v[14:15], v[14:15], 1.0 op_sel_hi:[1,0]
	v_and_b32_e32 v12, 0xffff0000, v12
	v_rcp_f32_e32 v17, v15
	s_nop 0
	s_nop 0
	v_fma_f32 v19, -v15, v17, 1.0
	v_fma_f32 v17, v19, v17, v17
	v_mul_f32_e32 v15, v0, v17
	v_rcp_f32_e32 v0, v14
	s_nop 0
	s_nop 0
	v_fma_f32 v18, -v14, v0, 1.0
	v_fma_f32 v0, v18, v0, v0
	v_mul_f32_e32 v14, v16, v0
	v_pk_mul_f32 v[12:13], v[14:15], v[12:13]
	v_bfe_u32 v15, v11, 16, 1
	v_bfe_u32 v0, v13, 16, 1
	v_bfe_u32 v14, v12, 16, 1
	v_bfe_u32 v16, v10, 16, 1
	v_add3_u32 v12, v12, v14, s33
	v_add3_u32 v0, v13, v0, s33
	v_add3_u32 v10, v10, v16, s33
	v_add3_u32 v13, v11, v15, s33
	v_perm_b32 v11, v0, v12, s27
	v_perm_b32 v10, v13, v10, s27
	global_store_dwordx2 v[30:31], v[10:11], off offset:160
	global_load_dwordx2 v[10:11], v[36:37], off offset:192
	v_and_b32_sdwa v13, v7, v195 dst_sel:DWORD dst_unused:UNUSED_PAD src0_sel:WORD_1 src1_sel:DWORD
	v_add3_u32 v7, v7, v13, s33
	v_and_b32_sdwa v14, v6, v195 dst_sel:DWORD dst_unused:UNUSED_PAD src0_sel:WORD_1 src1_sel:DWORD
	v_add3_u32 v6, v6, v14, s33
	v_and_b32_e32 v7, 0xffff0000, v7
	v_and_b32_e32 v6, 0xffff0000, v6
	s_waitcnt vmcnt(0)
	v_and_b32_e32 v0, 0xffff0000, v10
	v_lshlrev_b32_e32 v10, 16, v10
	v_mul_f32_e32 v12, 0xbfb8aa3b, v10
	v_mul_f32_e32 v13, 0xbfb8aa3b, v0
	v_exp_f32_e32 v12, v12
	v_exp_f32_e32 v13, v13
	s_nop 0
	v_pk_add_f32 v[12:13], v[12:13], 1.0 op_sel_hi:[1,0]
	s_nop 0
	v_rcp_f32_e32 v14, v13
	s_nop 0
	s_nop 0
	v_fma_f32 v16, -v13, v14, 1.0
	v_fma_f32 v14, v16, v14, v14
	v_mul_f32_e32 v13, v0, v14
	v_rcp_f32_e32 v0, v12
	s_nop 0
	s_nop 0
	v_fma_f32 v15, -v12, v0, 1.0
	v_fma_f32 v0, v15, v0, v0
	v_mul_f32_e32 v12, v10, v0
	v_pk_mul_f32 v[6:7], v[12:13], v[6:7]
	v_and_b32_e32 v0, 0xffff0000, v11
	v_lshlrev_b32_e32 v12, 16, v11
	v_and_b32_sdwa v11, v9, v195 dst_sel:DWORD dst_unused:UNUSED_PAD src0_sel:WORD_1 src1_sel:DWORD
	v_mul_f32_e32 v10, 0xbfb8aa3b, v12
	v_add3_u32 v9, v9, v11, s33
	v_mul_f32_e32 v11, 0xbfb8aa3b, v0
	v_exp_f32_e32 v10, v10
	v_exp_f32_e32 v11, v11
	v_and_b32_sdwa v13, v8, v195 dst_sel:DWORD dst_unused:UNUSED_PAD src0_sel:WORD_1 src1_sel:DWORD
	v_add3_u32 v8, v8, v13, s33
	v_and_b32_e32 v9, 0xffff0000, v9
	v_pk_add_f32 v[10:11], v[10:11], 1.0 op_sel_hi:[1,0]
	v_and_b32_e32 v8, 0xffff0000, v8
	v_rcp_f32_e32 v13, v11
	s_nop 0
	s_nop 0
	v_fma_f32 v15, -v11, v13, 1.0
	v_fma_f32 v13, v15, v13, v13
	v_mul_f32_e32 v11, v0, v13
	v_rcp_f32_e32 v0, v10
	s_nop 0
	s_nop 0
	v_fma_f32 v14, -v10, v0, 1.0
	v_fma_f32 v0, v14, v0, v0
	v_mul_f32_e32 v10, v12, v0
	v_pk_mul_f32 v[8:9], v[10:11], v[8:9]
	v_bfe_u32 v11, v7, 16, 1
	v_bfe_u32 v0, v9, 16, 1
	v_bfe_u32 v10, v8, 16, 1
	v_bfe_u32 v12, v6, 16, 1
	v_add3_u32 v8, v8, v10, s33
	v_add3_u32 v0, v9, v0, s33
	v_add3_u32 v6, v6, v12, s33
	v_add3_u32 v9, v7, v11, s33
	v_perm_b32 v7, v0, v8, s27
	v_perm_b32 v6, v9, v6, s27
	global_store_dwordx2 v[30:31], v[6:7], off offset:192
	global_load_dwordx2 v[6:7], v[36:37], off offset:224
	v_and_b32_sdwa v9, v3, v195 dst_sel:DWORD dst_unused:UNUSED_PAD src0_sel:WORD_1 src1_sel:DWORD
	v_add3_u32 v3, v3, v9, s33
	v_and_b32_sdwa v10, v2, v195 dst_sel:DWORD dst_unused:UNUSED_PAD src0_sel:WORD_1 src1_sel:DWORD
	v_add3_u32 v2, v2, v10, s33
	v_and_b32_e32 v3, 0xffff0000, v3
	v_and_b32_e32 v2, 0xffff0000, v2
	s_waitcnt vmcnt(0)
	v_and_b32_e32 v0, 0xffff0000, v6
	v_lshlrev_b32_e32 v6, 16, v6
	v_mul_f32_e32 v8, 0xbfb8aa3b, v6
	v_mul_f32_e32 v9, 0xbfb8aa3b, v0
	v_exp_f32_e32 v8, v8
	v_exp_f32_e32 v9, v9
	s_nop 0
	v_pk_add_f32 v[8:9], v[8:9], 1.0 op_sel_hi:[1,0]
	s_nop 0
	v_rcp_f32_e32 v10, v9
	s_nop 0
	s_nop 0
	v_fma_f32 v12, -v9, v10, 1.0
	v_fma_f32 v10, v12, v10, v10
	v_mul_f32_e32 v9, v0, v10
	v_rcp_f32_e32 v0, v8
	s_nop 0
	s_nop 0
	v_fma_f32 v11, -v8, v0, 1.0
	v_fma_f32 v0, v11, v0, v0
	v_mul_f32_e32 v8, v6, v0
	v_pk_mul_f32 v[2:3], v[8:9], v[2:3]
	v_and_b32_e32 v0, 0xffff0000, v7
	v_lshlrev_b32_e32 v8, 16, v7
	v_and_b32_sdwa v7, v5, v195 dst_sel:DWORD dst_unused:UNUSED_PAD src0_sel:WORD_1 src1_sel:DWORD
	v_mul_f32_e32 v6, 0xbfb8aa3b, v8
	v_add3_u32 v5, v5, v7, s33
	v_mul_f32_e32 v7, 0xbfb8aa3b, v0
	v_exp_f32_e32 v6, v6
	v_exp_f32_e32 v7, v7
	v_and_b32_sdwa v9, v4, v195 dst_sel:DWORD dst_unused:UNUSED_PAD src0_sel:WORD_1 src1_sel:DWORD
	v_add3_u32 v4, v4, v9, s33
	v_and_b32_e32 v5, 0xffff0000, v5
	v_pk_add_f32 v[6:7], v[6:7], 1.0 op_sel_hi:[1,0]
	v_and_b32_e32 v4, 0xffff0000, v4
	v_rcp_f32_e32 v9, v7
	s_nop 0
	s_nop 0
	v_fma_f32 v11, -v7, v9, 1.0
	v_fma_f32 v9, v11, v9, v9
	v_mul_f32_e32 v7, v0, v9
	v_rcp_f32_e32 v0, v6
	s_nop 0
	s_nop 0
	v_fma_f32 v10, -v6, v0, 1.0
	v_fma_f32 v0, v10, v0, v0
	v_mul_f32_e32 v6, v8, v0
	v_pk_mul_f32 v[4:5], v[6:7], v[4:5]
	v_bfe_u32 v7, v3, 16, 1
	v_bfe_u32 v0, v5, 16, 1
	v_bfe_u32 v6, v4, 16, 1
	v_bfe_u32 v8, v2, 16, 1
	v_add3_u32 v4, v4, v6, s33
	v_add3_u32 v0, v5, v0, s33
	v_add3_u32 v2, v2, v8, s33
	v_add3_u32 v5, v3, v7, s33
	v_perm_b32 v3, v0, v4, s27
	v_perm_b32 v2, v5, v2, s27
	global_store_dwordx2 v[30:31], v[2:3], off offset:224

; DEVI float bf2f(u16 h) { return __uint_as_float(((unsigned)h) << 16); }
; DEVI float bfs(short h) { return __uint_as_float(((unsigned)(u16)h) << 16); }
; DEVI float silu_f(float x) { return x / (1.f + __expf(-x)); }
; #define SHX(v, m) __int_as_float(__builtin_amdgcn_ds_bpermute(((LANE ^ (m)) << 2), __float_as_int(v)))
; template <int DQK, int QT, bool NA> ...
;     ...
;   for (int qt = 0; qt < QT; ++qt) {
;     float lt = lrun[qt];
;     lt += SHX(lt, 16);
;     lt += SHX(lt, 32);
;     float il = 1.f / lt;
;     int r = qrow0 + wid * 16 * QT + qt * 16 + l15;
; #pragma unroll
;     for (int dt = 0; dt < 8; ++dt) {
;       int dv = dt * 16 + quad * 4;
;       bf16x4 g = *(const bf16x4*)(proj + (size_t)r * NP + gatecol + h * 128 + dv);
;       bf16x4 ov;
; #pragma unroll
;       for (int j = 0; j < 4; ++j) {
;         float y = bf2f(f2bf(o[dt][qt][j] * il));
;         ov[j] = (short)f2bf(y * silu_f(bfs(g[j])));
;       }
;       *(bf16x4*)(ys + (size_t)r * 2048 + ycol + h * 128 + dv) = ov;
;     }
.LBB0_655:
	ds_bpermute_b32 v0, v90, v67
	s_add_u32 s0, s72, s0
	s_addc_u32 s1, s73, s1
	v_lshl_add_u64 v[14:15], s[0:1], 0, v[84:85]
	v_lshl_add_u64 v[16:17], v[14:15], 0, s[20:21]
	v_lshlrev_b64 v[14:15], 12, v[82:83]
	v_lshl_add_u64 v[14:15], s[0:1], 0, v[14:15]
	s_waitcnt lgkmcnt(0)
	v_add_f32_e32 v0, v67, v0
	v_lshl_add_u64 v[20:21], v[14:15], 0, s[20:21]
	ds_bpermute_b32 v14, v91, v0
	s_waitcnt lgkmcnt(0)
	v_add_f32_e32 v0, v0, v14
	v_rcp_f32_e32 v14, v0
	s_nop 0
	s_mov_b64 s[0:1], 0xa28ac00
	v_fma_f32 v18, -v0, v14, 1.0
	v_fma_f32 v14, v18, v14, v14
	v_mov_b32_e32 v14, v14
	v_lshlrev_b32_e32 v0, 1, v101
	v_lshl_add_u64 v[16:17], v[16:17], 0, v[0:1]
	v_lshl_add_u64 v[18:19], v[16:17], 0, s[0:1]
	s_mov_b32 s0, 0xa28a000
	v_add_co_u32_e32 v16, vcc, s0, v16
	v_pk_mul_f32 v[22:23], v[54:55], v[14:15] op_sel_hi:[1,0]
	s_nop 0
	v_addc_co_u32_e32 v17, vcc, 0, v17, vcc
	global_load_dwordx2 v[16:17], v[16:17], off offset:3072
	v_and_b32_sdwa v25, v23, v195 dst_sel:DWORD dst_unused:UNUSED_PAD src0_sel:WORD_1 src1_sel:DWORD
	v_add3_u32 v23, v23, v25, s33
	v_and_b32_sdwa v26, v22, v195 dst_sel:DWORD dst_unused:UNUSED_PAD src0_sel:WORD_1 src1_sel:DWORD
	v_add3_u32 v22, v22, v26, s33
	v_and_b32_e32 v23, 0xffff0000, v23
	v_and_b32_e32 v22, 0xffff0000, v22
	v_lshl_add_u64 v[20:21], v[20:21], 0, v[0:1]
	s_waitcnt vmcnt(0)
	v_and_b32_e32 v15, 0xffff0000, v16
	v_lshlrev_b32_e32 v16, 16, v16
	v_mul_f32_e32 v24, 0xbfb8aa3b, v16
	v_mul_f32_e32 v25, 0xbfb8aa3b, v15
	v_exp_f32_e32 v24, v24
	v_exp_f32_e32 v25, v25
	s_nop 0
	v_pk_add_f32 v[24:25], v[24:25], 1.0 op_sel_hi:[1,0]
	s_nop 0
	v_rcp_f32_e32 v26, v25
	s_nop 0
	s_nop 0
	v_fma_f32 v28, -v25, v26, 1.0
	v_fma_f32 v26, v28, v26, v26
	v_mul_f32_e32 v25, v15, v26
	v_rcp_f32_e32 v15, v24
	s_nop 0
	s_nop 0
	v_fma_f32 v27, -v24, v15, 1.0
	v_fma_f32 v15, v27, v15, v15
	v_mul_f32_e32 v24, v16, v15
	v_pk_mul_f32 v[22:23], v[24:25], v[22:23]
	v_pk_mul_f32 v[24:25], v[56:57], v[14:15] op_sel_hi:[1,0]
	v_and_b32_e32 v15, 0xffff0000, v17
	v_lshlrev_b32_e32 v26, 16, v17
	v_and_b32_sdwa v17, v25, v195 dst_sel:DWORD dst_unused:UNUSED_PAD src0_sel:WORD_1 src1_sel:DWORD
	v_add3_u32 v17, v25, v17, s33
	v_mul_f32_e32 v16, 0xbfb8aa3b, v26
	v_and_b32_e32 v25, 0xffff0000, v17
	v_mul_f32_e32 v17, 0xbfb8aa3b, v15
	v_exp_f32_e32 v16, v16
	v_exp_f32_e32 v17, v17
	v_and_b32_sdwa v27, v24, v195 dst_sel:DWORD dst_unused:UNUSED_PAD src0_sel:WORD_1 src1_sel:DWORD
	v_add3_u32 v24, v24, v27, s33
	v_and_b32_e32 v24, 0xffff0000, v24
	v_pk_add_f32 v[16:17], v[16:17], 1.0 op_sel_hi:[1,0]
	s_nop 0
	v_rcp_f32_e32 v27, v17
	s_nop 0
	s_nop 0
	v_fma_f32 v29, -v17, v27, 1.0
	v_fma_f32 v27, v29, v27, v27
	v_mul_f32_e32 v17, v15, v27
	v_rcp_f32_e32 v15, v16
	s_nop 0
	s_mov_b64 s[0:1], 0x2223c000
	v_fma_f32 v28, -v16, v15, 1.0
	v_fma_f32 v15, v28, v15, v15
	v_mul_f32_e32 v16, v26, v15
	v_pk_mul_f32 v[16:17], v[16:17], v[24:25]
	v_bfe_u32 v25, v23, 16, 1
	v_bfe_u32 v15, v17, 16, 1
	v_bfe_u32 v24, v16, 16, 1
	v_add3_u32 v16, v16, v24, s33
	v_add3_u32 v15, v17, v15, s33
	v_bfe_u32 v26, v22, 16, 1
	v_add3_u32 v25, v23, v25, s33
	v_perm_b32 v23, v15, v16, s27
	v_lshl_add_u64 v[16:17], v[20:21], 0, s[0:1]
	s_mov_b32 s0, 0x2223c000
	v_add3_u32 v22, v22, v26, s33
	v_add_co_u32_e32 v20, vcc, s0, v20
	v_perm_b32 v22, v25, v22, s27
	s_nop 0
	v_addc_co_u32_e32 v21, vcc, 0, v21, vcc
	global_store_dwordx2 v[20:21], v[22:23], off
	global_load_dwordx2 v[20:21], v[18:19], off offset:32
	v_pk_mul_f32 v[22:23], v[50:51], v[14:15] op_sel_hi:[1,0]
	s_waitcnt vmcnt(0)
	v_lshlrev_b32_e32 v15, 16, v20
	v_and_b32_e32 v0, 0xffff0000, v20
	v_mul_f32_e32 v20, 0xbfb8aa3b, v15
	v_exp_f32_e32 v24, v20
	v_and_b32_sdwa v20, v23, v195 dst_sel:DWORD dst_unused:UNUSED_PAD src0_sel:WORD_1 src1_sel:DWORD
	v_add3_u32 v20, v23, v20, s33
	v_and_b32_sdwa v25, v22, v195 dst_sel:DWORD dst_unused:UNUSED_PAD src0_sel:WORD_1 src1_sel:DWORD
	v_and_b32_e32 v23, 0xffff0000, v20
	v_mul_f32_e32 v20, 0xbfb8aa3b, v0
	v_add3_u32 v22, v22, v25, s33
	v_exp_f32_e32 v25, v20
	v_and_b32_e32 v22, 0xffff0000, v22
	v_pk_add_f32 v[24:25], v[24:25], 1.0 op_sel_hi:[1,0]
	s_nop 0
	v_rcp_f32_e32 v20, v25
	s_nop 0
	s_nop 0
	v_fma_f32 v27, -v25, v20, 1.0
	v_fma_f32 v20, v27, v20, v20
	v_mul_f32_e32 v25, v0, v20
	v_rcp_f32_e32 v0, v24
	s_nop 0
	s_nop 0
	v_fma_f32 v26, -v24, v0, 1.0
	v_fma_f32 v0, v26, v0, v0
	v_mul_f32_e32 v24, v15, v0
	v_pk_mul_f32 v[22:23], v[24:25], v[22:23]
	v_pk_mul_f32 v[24:25], v[52:53], v[14:15] op_sel_hi:[1,0]
	v_and_b32_e32 v0, 0xffff0000, v21
	v_lshlrev_b32_e32 v15, 16, v21
	v_and_b32_sdwa v21, v25, v195 dst_sel:DWORD dst_unused:UNUSED_PAD src0_sel:WORD_1 src1_sel:DWORD
	v_add3_u32 v21, v25, v21, s33
	v_mul_f32_e32 v20, 0xbfb8aa3b, v15
	v_and_b32_e32 v25, 0xffff0000, v21
	v_mul_f32_e32 v21, 0xbfb8aa3b, v0
	v_exp_f32_e32 v20, v20
	v_exp_f32_e32 v21, v21
	v_and_b32_sdwa v26, v24, v195 dst_sel:DWORD dst_unused:UNUSED_PAD src0_sel:WORD_1 src1_sel:DWORD
	v_add3_u32 v24, v24, v26, s33
	v_and_b32_e32 v24, 0xffff0000, v24
	v_pk_add_f32 v[20:21], v[20:21], 1.0 op_sel_hi:[1,0]
	s_nop 0
	v_rcp_f32_e32 v26, v21
	s_nop 0
	s_nop 0
	v_fma_f32 v28, -v21, v26, 1.0
	v_fma_f32 v26, v28, v26, v26
	v_mul_f32_e32 v21, v0, v26
	v_rcp_f32_e32 v0, v20
	s_nop 0
	s_nop 0
	v_fma_f32 v27, -v20, v0, 1.0
	v_fma_f32 v0, v27, v0, v0
	v_mul_f32_e32 v20, v15, v0
	v_pk_mul_f32 v[20:21], v[20:21], v[24:25]
	v_bfe_u32 v24, v23, 16, 1
	v_bfe_u32 v0, v21, 16, 1
	v_bfe_u32 v15, v20, 16, 1
	v_bfe_u32 v25, v22, 16, 1
	v_add3_u32 v22, v22, v25, s33
	v_add3_u32 v23, v23, v24, s33
	v_add3_u32 v15, v20, v15, s33
	v_add3_u32 v0, v21, v0, s33
	v_perm_b32 v21, v0, v15, s27
	v_perm_b32 v20, v23, v22, s27
	global_store_dwordx2 v[16:17], v[20:21], off offset:32
	global_load_dwordx2 v[20:21], v[18:19], off offset:64
	v_pk_mul_f32 v[22:23], v[38:39], v[14:15] op_sel_hi:[1,0]
	s_waitcnt vmcnt(0)
; DEVI float bf2f(u16 h) { return __uint_as_float(((unsigned)h) << 16); }
; DEVI float bfs(short h) { return __uint_as_float(((unsigned)(u16)h) << 16); }
; DEVI float silu_f(float x) { return x / (1.f + __expf(-x)); }
; template <int DQK, int QT, bool NA> ...
;     ...
;     for (int dt = 0; dt < 8; ++dt) {
;       int dv = dt * 16 + quad * 4;
;       bf16x4 g = *(const bf16x4*)(proj + (size_t)r * NP + gatecol + h * 128 + dv);
;       bf16x4 ov;
; #pragma unroll
;       for (int j = 0; j < 4; ++j) {
;         float y = bf2f(f2bf(o[dt][qt][j] * il));
;         ov[j] = (short)f2bf(y * silu_f(bfs(g[j])));
;       }
;       *(bf16x4*)(ys + (size_t)r * 2048 + ycol + h * 128 + dv) = ov;
;     }
	v_lshlrev_b32_e32 v15, 16, v20
	v_and_b32_e32 v0, 0xffff0000, v20
	v_mul_f32_e32 v20, 0xbfb8aa3b, v15
	v_exp_f32_e32 v24, v20
	v_and_b32_sdwa v20, v23, v195 dst_sel:DWORD dst_unused:UNUSED_PAD src0_sel:WORD_1 src1_sel:DWORD
	v_add3_u32 v20, v23, v20, s33
	v_and_b32_sdwa v25, v22, v195 dst_sel:DWORD dst_unused:UNUSED_PAD src0_sel:WORD_1 src1_sel:DWORD
	v_and_b32_e32 v23, 0xffff0000, v20
	v_mul_f32_e32 v20, 0xbfb8aa3b, v0
	v_add3_u32 v22, v22, v25, s33
	v_exp_f32_e32 v25, v20
	v_and_b32_e32 v22, 0xffff0000, v22
	v_pk_add_f32 v[24:25], v[24:25], 1.0 op_sel_hi:[1,0]
	s_nop 0
	v_rcp_f32_e32 v20, v25
	s_nop 0
	s_nop 0
	v_fma_f32 v27, -v25, v20, 1.0
	v_fma_f32 v20, v27, v20, v20
	v_mul_f32_e32 v25, v0, v20
	v_rcp_f32_e32 v0, v24
	s_nop 0
	s_nop 0
	v_fma_f32 v26, -v24, v0, 1.0
	v_fma_f32 v0, v26, v0, v0
	v_mul_f32_e32 v24, v15, v0
	v_pk_mul_f32 v[22:23], v[24:25], v[22:23]
	v_pk_mul_f32 v[24:25], v[40:41], v[14:15] op_sel_hi:[1,0]
	v_and_b32_e32 v0, 0xffff0000, v21
	v_lshlrev_b32_e32 v15, 16, v21
	v_and_b32_sdwa v21, v25, v195 dst_sel:DWORD dst_unused:UNUSED_PAD src0_sel:WORD_1 src1_sel:DWORD
	v_add3_u32 v21, v25, v21, s33
	v_mul_f32_e32 v20, 0xbfb8aa3b, v15
	v_and_b32_e32 v25, 0xffff0000, v21
	v_mul_f32_e32 v21, 0xbfb8aa3b, v0
	v_exp_f32_e32 v20, v20
	v_exp_f32_e32 v21, v21
	v_and_b32_sdwa v26, v24, v195 dst_sel:DWORD dst_unused:UNUSED_PAD src0_sel:WORD_1 src1_sel:DWORD
	v_add3_u32 v24, v24, v26, s33
	v_and_b32_e32 v24, 0xffff0000, v24
	v_pk_add_f32 v[20:21], v[20:21], 1.0 op_sel_hi:[1,0]
	s_nop 0
	v_rcp_f32_e32 v26, v21
	s_nop 0
	s_nop 0
	v_fma_f32 v28, -v21, v26, 1.0
	v_fma_f32 v26, v28, v26, v26
	v_mul_f32_e32 v21, v0, v26
	v_rcp_f32_e32 v0, v20
	s_nop 0
	s_nop 0
	v_fma_f32 v27, -v20, v0, 1.0
	v_fma_f32 v0, v27, v0, v0
	v_mul_f32_e32 v20, v15, v0
	v_pk_mul_f32 v[20:21], v[20:21], v[24:25]
	v_bfe_u32 v24, v23, 16, 1
	v_bfe_u32 v0, v21, 16, 1
	v_bfe_u32 v15, v20, 16, 1
	v_bfe_u32 v25, v22, 16, 1
	v_add3_u32 v22, v22, v25, s33
	v_add3_u32 v23, v23, v24, s33
	v_add3_u32 v15, v20, v15, s33
	v_add3_u32 v0, v21, v0, s33
	v_perm_b32 v21, v0, v15, s27
	v_perm_b32 v20, v23, v22, s27
	global_store_dwordx2 v[16:17], v[20:21], off offset:64
	global_load_dwordx2 v[20:21], v[18:19], off offset:96
	v_pk_mul_f32 v[22:23], v[34:35], v[14:15] op_sel_hi:[1,0]
	s_waitcnt vmcnt(0)
	v_lshlrev_b32_e32 v15, 16, v20
	v_and_b32_e32 v0, 0xffff0000, v20
	v_mul_f32_e32 v20, 0xbfb8aa3b, v15
	v_exp_f32_e32 v24, v20
	v_and_b32_sdwa v20, v23, v195 dst_sel:DWORD dst_unused:UNUSED_PAD src0_sel:WORD_1 src1_sel:DWORD
	v_add3_u32 v20, v23, v20, s33
	v_and_b32_sdwa v25, v22, v195 dst_sel:DWORD dst_unused:UNUSED_PAD src0_sel:WORD_1 src1_sel:DWORD
	v_and_b32_e32 v23, 0xffff0000, v20
	v_mul_f32_e32 v20, 0xbfb8aa3b, v0
	v_add3_u32 v22, v22, v25, s33
	v_exp_f32_e32 v25, v20
	v_and_b32_e32 v22, 0xffff0000, v22
	v_pk_add_f32 v[24:25], v[24:25], 1.0 op_sel_hi:[1,0]
	s_nop 0
	v_rcp_f32_e32 v20, v25
	s_nop 0
	s_nop 0
	v_fma_f32 v27, -v25, v20, 1.0
	v_fma_f32 v20, v27, v20, v20
	v_mul_f32_e32 v25, v0, v20
	v_rcp_f32_e32 v0, v24
	s_nop 0
	s_nop 0
	v_fma_f32 v26, -v24, v0, 1.0
	v_fma_f32 v0, v26, v0, v0
	v_mul_f32_e32 v24, v15, v0
	v_pk_mul_f32 v[22:23], v[24:25], v[22:23]
	v_pk_mul_f32 v[24:25], v[36:37], v[14:15] op_sel_hi:[1,0]
	v_and_b32_e32 v0, 0xffff0000, v21
	v_lshlrev_b32_e32 v15, 16, v21
	v_and_b32_sdwa v21, v25, v195 dst_sel:DWORD dst_unused:UNUSED_PAD src0_sel:WORD_1 src1_sel:DWORD
	v_add3_u32 v21, v25, v21, s33
	v_mul_f32_e32 v20, 0xbfb8aa3b, v15
	v_and_b32_e32 v25, 0xffff0000, v21
	v_mul_f32_e32 v21, 0xbfb8aa3b, v0
	v_exp_f32_e32 v20, v20
	v_exp_f32_e32 v21, v21
	v_and_b32_sdwa v26, v24, v195 dst_sel:DWORD dst_unused:UNUSED_PAD src0_sel:WORD_1 src1_sel:DWORD
	v_add3_u32 v24, v24, v26, s33
	v_and_b32_e32 v24, 0xffff0000, v24
	v_pk_add_f32 v[20:21], v[20:21], 1.0 op_sel_hi:[1,0]
	s_nop 0
	v_rcp_f32_e32 v26, v21
	s_nop 0
	s_nop 0
	v_fma_f32 v28, -v21, v26, 1.0
	v_fma_f32 v26, v28, v26, v26
	v_mul_f32_e32 v21, v0, v26
	v_rcp_f32_e32 v0, v20
	s_nop 0
	s_nop 0
	v_fma_f32 v27, -v20, v0, 1.0
	v_fma_f32 v0, v27, v0, v0
	v_mul_f32_e32 v20, v15, v0
	v_pk_mul_f32 v[20:21], v[20:21], v[24:25]
	v_bfe_u32 v24, v23, 16, 1
	v_bfe_u32 v0, v21, 16, 1
	v_bfe_u32 v15, v20, 16, 1
	v_bfe_u32 v25, v22, 16, 1
	v_add3_u32 v22, v22, v25, s33
	v_add3_u32 v23, v23, v24, s33
	v_add3_u32 v15, v20, v15, s33
	v_add3_u32 v0, v21, v0, s33
	v_perm_b32 v21, v0, v15, s27
	v_perm_b32 v20, v23, v22, s27
	global_store_dwordx2 v[16:17], v[20:21], off offset:96
	global_load_dwordx2 v[20:21], v[18:19], off offset:128
	v_pk_mul_f32 v[22:23], v[30:31], v[14:15] op_sel_hi:[1,0]
	s_waitcnt vmcnt(0)
; DEVI float bf2f(u16 h) { return __uint_as_float(((unsigned)h) << 16); }
; DEVI float bfs(short h) { return __uint_as_float(((unsigned)(u16)h) << 16); }
; DEVI float silu_f(float x) { return x / (1.f + __expf(-x)); }
; template <int DQK, int QT, bool NA> ...
;     ...
;     for (int dt = 0; dt < 8; ++dt) {
;       int dv = dt * 16 + quad * 4;
;       bf16x4 g = *(const bf16x4*)(proj + (size_t)r * NP + gatecol + h * 128 + dv);
;       bf16x4 ov;
; #pragma unroll
;       for (int j = 0; j < 4; ++j) {
;         float y = bf2f(f2bf(o[dt][qt][j] * il));
;         ov[j] = (short)f2bf(y * silu_f(bfs(g[j])));
;       }
;       *(bf16x4*)(ys + (size_t)r * 2048 + ycol + h * 128 + dv) = ov;
	v_lshlrev_b32_e32 v15, 16, v20
	v_and_b32_e32 v0, 0xffff0000, v20
	v_mul_f32_e32 v20, 0xbfb8aa3b, v15
	v_exp_f32_e32 v24, v20
	v_and_b32_sdwa v20, v23, v195 dst_sel:DWORD dst_unused:UNUSED_PAD src0_sel:WORD_1 src1_sel:DWORD
	v_add3_u32 v20, v23, v20, s33
	v_and_b32_sdwa v25, v22, v195 dst_sel:DWORD dst_unused:UNUSED_PAD src0_sel:WORD_1 src1_sel:DWORD
	v_and_b32_e32 v23, 0xffff0000, v20
	v_mul_f32_e32 v20, 0xbfb8aa3b, v0
	v_add3_u32 v22, v22, v25, s33
	v_exp_f32_e32 v25, v20
	v_and_b32_e32 v22, 0xffff0000, v22
	v_pk_add_f32 v[24:25], v[24:25], 1.0 op_sel_hi:[1,0]
	s_nop 0
	v_rcp_f32_e32 v20, v25
	s_nop 0
	s_nop 0
	v_fma_f32 v27, -v25, v20, 1.0
	v_fma_f32 v20, v27, v20, v20
	v_mul_f32_e32 v25, v0, v20
	v_rcp_f32_e32 v0, v24
	s_nop 0
	s_nop 0
	v_fma_f32 v26, -v24, v0, 1.0
	v_fma_f32 v0, v26, v0, v0
	v_mul_f32_e32 v24, v15, v0
	v_pk_mul_f32 v[22:23], v[24:25], v[22:23]
	v_pk_mul_f32 v[24:25], v[32:33], v[14:15] op_sel_hi:[1,0]
	v_and_b32_e32 v0, 0xffff0000, v21
	v_lshlrev_b32_e32 v15, 16, v21
	v_and_b32_sdwa v21, v25, v195 dst_sel:DWORD dst_unused:UNUSED_PAD src0_sel:WORD_1 src1_sel:DWORD
	v_add3_u32 v21, v25, v21, s33
	v_mul_f32_e32 v20, 0xbfb8aa3b, v15
	v_and_b32_e32 v25, 0xffff0000, v21
	v_mul_f32_e32 v21, 0xbfb8aa3b, v0
	v_exp_f32_e32 v20, v20
	v_exp_f32_e32 v21, v21
	v_and_b32_sdwa v26, v24, v195 dst_sel:DWORD dst_unused:UNUSED_PAD src0_sel:WORD_1 src1_sel:DWORD
	v_add3_u32 v24, v24, v26, s33
	v_and_b32_e32 v24, 0xffff0000, v24
	v_pk_add_f32 v[20:21], v[20:21], 1.0 op_sel_hi:[1,0]
	s_nop 0
	v_rcp_f32_e32 v26, v21
	s_nop 0
	s_nop 0
	v_fma_f32 v28, -v21, v26, 1.0
	v_fma_f32 v26, v28, v26, v26
	v_mul_f32_e32 v21, v0, v26
	v_rcp_f32_e32 v0, v20
	s_nop 0
	s_nop 0
	v_fma_f32 v27, -v20, v0, 1.0
	v_fma_f32 v0, v27, v0, v0
	v_mul_f32_e32 v20, v15, v0
	v_pk_mul_f32 v[20:21], v[20:21], v[24:25]
	v_bfe_u32 v24, v23, 16, 1
	v_bfe_u32 v0, v21, 16, 1
	v_bfe_u32 v15, v20, 16, 1
	v_bfe_u32 v25, v22, 16, 1
	v_add3_u32 v22, v22, v25, s33
	v_add3_u32 v23, v23, v24, s33
	v_add3_u32 v15, v20, v15, s33
	v_add3_u32 v0, v21, v0, s33
	v_perm_b32 v21, v0, v15, s27
	v_perm_b32 v20, v23, v22, s27
	global_store_dwordx2 v[16:17], v[20:21], off offset:128
	global_load_dwordx2 v[20:21], v[18:19], off offset:160
	v_pk_mul_f32 v[10:11], v[10:11], v[14:15] op_sel_hi:[1,0]
	s_waitcnt vmcnt(0)
	v_lshlrev_b32_e32 v15, 16, v20
	v_and_b32_e32 v0, 0xffff0000, v20
	v_mul_f32_e32 v20, 0xbfb8aa3b, v15
	v_exp_f32_e32 v22, v20
	v_and_b32_sdwa v20, v11, v195 dst_sel:DWORD dst_unused:UNUSED_PAD src0_sel:WORD_1 src1_sel:DWORD
	v_and_b32_sdwa v23, v10, v195 dst_sel:DWORD dst_unused:UNUSED_PAD src0_sel:WORD_1 src1_sel:DWORD
	v_add3_u32 v11, v11, v20, s33
	v_mul_f32_e32 v20, 0xbfb8aa3b, v0
	v_add3_u32 v10, v10, v23, s33
	v_exp_f32_e32 v23, v20
	v_pk_mul_f32 v[12:13], v[12:13], v[14:15] op_sel_hi:[1,0]
	v_and_b32_e32 v11, 0xffff0000, v11
	v_and_b32_e32 v10, 0xffff0000, v10
	v_pk_add_f32 v[22:23], v[22:23], 1.0 op_sel_hi:[1,0]
	s_nop 0
	v_rcp_f32_e32 v20, v23
	s_nop 0
	s_nop 0
	v_fma_f32 v25, -v23, v20, 1.0
	v_fma_f32 v20, v25, v20, v20
	v_mul_f32_e32 v23, v0, v20
	v_rcp_f32_e32 v0, v22
	s_nop 0
	s_nop 0
	v_fma_f32 v24, -v22, v0, 1.0
	v_fma_f32 v0, v24, v0, v0
	v_mul_f32_e32 v22, v15, v0
	v_and_b32_e32 v0, 0xffff0000, v21
	v_lshlrev_b32_e32 v15, 16, v21
	v_and_b32_sdwa v21, v13, v195 dst_sel:DWORD dst_unused:UNUSED_PAD src0_sel:WORD_1 src1_sel:DWORD
	v_mul_f32_e32 v20, 0xbfb8aa3b, v15
	v_add3_u32 v13, v13, v21, s33
	v_mul_f32_e32 v21, 0xbfb8aa3b, v0
	v_exp_f32_e32 v20, v20
	v_exp_f32_e32 v21, v21
	v_pk_mul_f32 v[10:11], v[22:23], v[10:11]
	v_and_b32_sdwa v22, v12, v195 dst_sel:DWORD dst_unused:UNUSED_PAD src0_sel:WORD_1 src1_sel:DWORD
	v_add3_u32 v12, v12, v22, s33
	v_pk_add_f32 v[20:21], v[20:21], 1.0 op_sel_hi:[1,0]
	v_and_b32_e32 v13, 0xffff0000, v13
	v_rcp_f32_e32 v22, v21
	s_nop 0
	v_and_b32_e32 v12, 0xffff0000, v12
	v_fma_f32 v24, -v21, v22, 1.0
	v_fma_f32 v22, v24, v22, v22
	v_mul_f32_e32 v21, v0, v22
	v_rcp_f32_e32 v0, v20
	s_nop 0
	s_nop 0
	v_fma_f32 v23, -v20, v0, 1.0
	v_fma_f32 v0, v23, v0, v0
	v_mul_f32_e32 v20, v15, v0
	v_pk_mul_f32 v[12:13], v[20:21], v[12:13]
	v_bfe_u32 v20, v11, 16, 1
	v_bfe_u32 v0, v13, 16, 1
	v_bfe_u32 v15, v12, 16, 1
	v_bfe_u32 v21, v10, 16, 1
	v_add3_u32 v10, v10, v21, s33
	v_add3_u32 v20, v11, v20, s33
	v_add3_u32 v11, v12, v15, s33
	v_add3_u32 v0, v13, v0, s33
	v_perm_b32 v11, v0, v11, s27
	v_perm_b32 v10, v20, v10, s27
	global_store_dwordx2 v[16:17], v[10:11], off offset:160
	global_load_dwordx2 v[10:11], v[18:19], off offset:192
	v_pk_mul_f32 v[6:7], v[6:7], v[14:15] op_sel_hi:[1,0]
	s_waitcnt vmcnt(0)
; DEVI float bf2f(u16 h) { return __uint_as_float(((unsigned)h) << 16); }
; DEVI float bfs(short h) { return __uint_as_float(((unsigned)(u16)h) << 16); }
; DEVI float silu_f(float x) { return x / (1.f + __expf(-x)); }
; template <int DQK, int QT, bool NA> ...
;     ...
;     for (int dt = 0; dt < 8; ++dt) {
;       int dv = dt * 16 + quad * 4;
;       bf16x4 g = *(const bf16x4*)(proj + (size_t)r * NP + gatecol + h * 128 + dv);
;       bf16x4 ov;
; #pragma unroll
;       for (int j = 0; j < 4; ++j) {
;         float y = bf2f(f2bf(o[dt][qt][j] * il));
;         ov[j] = (short)f2bf(y * silu_f(bfs(g[j])));
;       }
;       *(bf16x4*)(ys + (size_t)r * 2048 + ycol + h * 128 + dv) = ov;
	v_and_b32_e32 v0, 0xffff0000, v10
	v_lshlrev_b32_e32 v10, 16, v10
	v_and_b32_sdwa v13, v7, v195 dst_sel:DWORD dst_unused:UNUSED_PAD src0_sel:WORD_1 src1_sel:DWORD
	v_mul_f32_e32 v12, 0xbfb8aa3b, v10
	v_add3_u32 v7, v7, v13, s33
	v_mul_f32_e32 v13, 0xbfb8aa3b, v0
	v_exp_f32_e32 v12, v12
	v_exp_f32_e32 v13, v13
	v_and_b32_sdwa v15, v6, v195 dst_sel:DWORD dst_unused:UNUSED_PAD src0_sel:WORD_1 src1_sel:DWORD
	v_add3_u32 v6, v6, v15, s33
	v_and_b32_e32 v7, 0xffff0000, v7
	v_pk_add_f32 v[12:13], v[12:13], 1.0 op_sel_hi:[1,0]
	v_and_b32_e32 v6, 0xffff0000, v6
	v_rcp_f32_e32 v15, v13
	s_nop 0
	s_nop 0
	v_fma_f32 v21, -v13, v15, 1.0
	v_fma_f32 v15, v21, v15, v15
	v_mul_f32_e32 v13, v0, v15
	v_rcp_f32_e32 v0, v12
	s_nop 0
	s_nop 0
	v_fma_f32 v20, -v12, v0, 1.0
	v_fma_f32 v0, v20, v0, v0
	v_mul_f32_e32 v12, v10, v0
	v_pk_mul_f32 v[8:9], v[8:9], v[14:15] op_sel_hi:[1,0]
	v_pk_mul_f32 v[6:7], v[12:13], v[6:7]
	v_and_b32_e32 v0, 0xffff0000, v11
	v_lshlrev_b32_e32 v12, 16, v11
	v_and_b32_sdwa v11, v9, v195 dst_sel:DWORD dst_unused:UNUSED_PAD src0_sel:WORD_1 src1_sel:DWORD
	v_mul_f32_e32 v10, 0xbfb8aa3b, v12
	v_add3_u32 v9, v9, v11, s33
	v_mul_f32_e32 v11, 0xbfb8aa3b, v0
	v_exp_f32_e32 v10, v10
	v_exp_f32_e32 v11, v11
	v_and_b32_sdwa v13, v8, v195 dst_sel:DWORD dst_unused:UNUSED_PAD src0_sel:WORD_1 src1_sel:DWORD
	v_add3_u32 v8, v8, v13, s33
	v_and_b32_e32 v9, 0xffff0000, v9
	v_pk_add_f32 v[10:11], v[10:11], 1.0 op_sel_hi:[1,0]
	v_and_b32_e32 v8, 0xffff0000, v8
	v_rcp_f32_e32 v13, v11
	s_nop 0
	s_nop 0
	v_fma_f32 v20, -v11, v13, 1.0
	v_fma_f32 v13, v20, v13, v13
	v_mul_f32_e32 v11, v0, v13
	v_rcp_f32_e32 v0, v10
	s_nop 0
	s_nop 0
	v_fma_f32 v15, -v10, v0, 1.0
	v_fma_f32 v0, v15, v0, v0
	v_mul_f32_e32 v10, v12, v0
	v_pk_mul_f32 v[8:9], v[10:11], v[8:9]
	v_bfe_u32 v11, v7, 16, 1
	v_bfe_u32 v0, v9, 16, 1
	v_bfe_u32 v10, v8, 16, 1
	v_bfe_u32 v12, v6, 16, 1
	v_add3_u32 v6, v6, v12, s33
	v_add3_u32 v11, v7, v11, s33
	v_add3_u32 v7, v8, v10, s33
	v_add3_u32 v0, v9, v0, s33
	v_perm_b32 v7, v0, v7, s27
	v_perm_b32 v6, v11, v6, s27
	global_store_dwordx2 v[16:17], v[6:7], off offset:192
	global_load_dwordx2 v[6:7], v[18:19], off offset:224
	v_pk_mul_f32 v[2:3], v[2:3], v[14:15] op_sel_hi:[1,0]
	s_waitcnt vmcnt(0)
	v_and_b32_e32 v0, 0xffff0000, v6
	v_lshlrev_b32_e32 v6, 16, v6
	v_and_b32_sdwa v9, v3, v195 dst_sel:DWORD dst_unused:UNUSED_PAD src0_sel:WORD_1 src1_sel:DWORD
	v_mul_f32_e32 v8, 0xbfb8aa3b, v6
	v_add3_u32 v3, v3, v9, s33
	v_mul_f32_e32 v9, 0xbfb8aa3b, v0
	v_exp_f32_e32 v8, v8
	v_exp_f32_e32 v9, v9
	v_and_b32_sdwa v10, v2, v195 dst_sel:DWORD dst_unused:UNUSED_PAD src0_sel:WORD_1 src1_sel:DWORD
	v_add3_u32 v2, v2, v10, s33
	v_and_b32_e32 v3, 0xffff0000, v3
	v_pk_add_f32 v[8:9], v[8:9], 1.0 op_sel_hi:[1,0]
	v_and_b32_e32 v2, 0xffff0000, v2
	v_rcp_f32_e32 v10, v9
	s_nop 0
	s_nop 0
	v_fma_f32 v12, -v9, v10, 1.0
	v_fma_f32 v10, v12, v10, v10
	v_mul_f32_e32 v9, v0, v10
	v_rcp_f32_e32 v0, v8
	s_nop 0
	v_pk_mul_f32 v[4:5], v[4:5], v[14:15] op_sel_hi:[1,0]
	v_fma_f32 v11, -v8, v0, 1.0
	v_fma_f32 v0, v11, v0, v0
	v_mul_f32_e32 v8, v6, v0
	v_pk_mul_f32 v[2:3], v[8:9], v[2:3]
	v_and_b32_e32 v0, 0xffff0000, v7
	v_lshlrev_b32_e32 v8, 16, v7
	v_and_b32_sdwa v7, v5, v195 dst_sel:DWORD dst_unused:UNUSED_PAD src0_sel:WORD_1 src1_sel:DWORD
	v_mul_f32_e32 v6, 0xbfb8aa3b, v8
	v_add3_u32 v5, v5, v7, s33
	v_mul_f32_e32 v7, 0xbfb8aa3b, v0
	v_exp_f32_e32 v6, v6
	v_exp_f32_e32 v7, v7
	v_and_b32_sdwa v9, v4, v195 dst_sel:DWORD dst_unused:UNUSED_PAD src0_sel:WORD_1 src1_sel:DWORD
	v_add3_u32 v4, v4, v9, s33
	v_and_b32_e32 v5, 0xffff0000, v5
	v_pk_add_f32 v[6:7], v[6:7], 1.0 op_sel_hi:[1,0]
	v_and_b32_e32 v4, 0xffff0000, v4
	v_rcp_f32_e32 v9, v7
	s_nop 0
	s_nop 0
	v_fma_f32 v11, -v7, v9, 1.0
	v_fma_f32 v9, v11, v9, v9
	v_mul_f32_e32 v7, v0, v9
	v_rcp_f32_e32 v0, v6
	s_nop 0
	s_mov_b64 s[0:1], 0
	v_fma_f32 v10, -v6, v0, 1.0
	v_fma_f32 v0, v10, v0, v0
	v_mul_f32_e32 v6, v8, v0
	v_pk_mul_f32 v[4:5], v[6:7], v[4:5]
	v_bfe_u32 v7, v3, 16, 1
	v_bfe_u32 v0, v5, 16, 1
	v_bfe_u32 v6, v4, 16, 1
	v_bfe_u32 v8, v2, 16, 1
	v_add3_u32 v2, v2, v8, s33
	v_add3_u32 v7, v3, v7, s33
	v_add3_u32 v3, v4, v6, s33
	v_add3_u32 v0, v5, v0, s33
	v_perm_b32 v3, v0, v3, s27
	v_perm_b32 v2, v7, v2, s27
	global_store_dwordx2 v[16:17], v[2:3], off offset:224

; template <int DQK, int QT, bool NA> ...
;     ...
;         float mnew = fmaxf(mrun[qt], mx);
;         float alpha = __builtin_amdgcn_exp2f(mrun[qt] - mnew);
;         mrun[qt] = mnew;
;         float ls = 0.f;
; #pragma unroll
;         for (int kt = 0; kt < 4; ++kt)
; #pragma unroll
;           for (int j = 0; j < 4; ++j) {
;             float pv = __builtin_amdgcn_exp2f(s[kt][qt][j] - mnew);
;             ls += pv;
;             s[kt][qt][j] = pv;
;           }
;         lrun[qt] = lrun[qt] * alpha + ls;
;         if (__builtin_amdgcn_ballot_w64(alpha != 1.f)) {
; #pragma unroll
;           for (int dt = 0; dt < 8; ++dt)
; #pragma unroll
;             for (int j = 0; j < 4; ++j) o[dt][qt][j] *= alpha;
;         }
; #pragma unroll
;         for (int kk = 0; kk < 2; ++kk) {
;           union { bf16x8 v; unsigned u[4]; } cv;
;           cv.u[0] = pk2(s[2 * kk][qt][0], s[2 * kk][qt][1]);
;           cv.u[1] = pk2(s[2 * kk][qt][2], s[2 * kk][qt][3]);
;           cv.u[2] = pk2(s[2 * kk + 1][qt][0], s[2 * kk + 1][qt][1]);
;           cv.u[3] = pk2(s[2 * kk + 1][qt][2], s[2 * kk + 1][qt][3]);
;           pf[qt][kk] = cv.v;
;         }
;       }
;       {
;         const u16* vb0 = Vs + l15 * 72 + quad * 4;
;         bf16x4 n0 = *(const bf16x4*)vb0, n1 = *(const bf16x4*)(vb0 + 16);
; #pragma unroll
;         for (int idx = 0; idx < 16; ++idx) {
;           const int kk = idx >> 3, dt = idx & 7;
;           bf16x8 va = {n0[0], n0[1], n0[2], n0[3], n1[0], n1[1], n1[2], n1[3]};
;           if (idx + 1 < 16) {
;             const int kk2 = (idx + 1) >> 3, dt2 = (idx + 1) & 7;
;             const u16* vb = Vs + (dt2 * 16 + l15) * 72 + kk2 * 32 + quad * 4;
;             n0 = *(const bf16x4*)vb;
;             n1 = *(const bf16x4*)(vb + 16);
;           }
; #pragma unroll
;           for (int qt = 0; qt < QT; ++qt) o[dt][qt] = __builtin_amdgcn_mfma_f32_16x16x32_bf16(va, pf[qt][kk], o[dt][qt], 0, 0, 0);
;         }
.LBB0_672:
	v_sub_f32_e32 v2, v7, v35
	v_exp_f32_e32 v42, v2
	v_sub_f32_e32 v2, v6, v35
	v_exp_f32_e32 v43, v2
	v_sub_f32_e32 v2, v9, v35
	v_exp_f32_e32 v44, v2
	v_sub_f32_e32 v2, v8, v35
	v_exp_f32_e32 v45, v2
	v_sub_f32_e32 v2, v24, v35
	v_exp_f32_e32 v24, v2
	v_sub_f32_e32 v2, v11, v35
	v_exp_f32_e32 v11, v2
	v_sub_f32_e32 v2, v26, v35
	v_exp_f32_e32 v26, v2
	v_sub_f32_e32 v2, v25, v35
	v_exp_f32_e32 v25, v2
	v_sub_f32_e32 v2, v28, v35
	v_exp_f32_e32 v28, v2
	v_sub_f32_e32 v2, v27, v35
	v_exp_f32_e32 v27, v2
	v_sub_f32_e32 v2, v30, v35
	v_exp_f32_e32 v30, v2
	v_sub_f32_e32 v2, v29, v35
	v_exp_f32_e32 v29, v2
	v_sub_f32_e32 v2, v32, v35
	v_sub_f32_e32 v41, v41, v18
	v_exp_f32_e32 v32, v2
	v_sub_f32_e32 v2, v31, v35
	v_exp_f32_e32 v41, v41
	v_sub_f32_e32 v40, v40, v18
	v_exp_f32_e32 v31, v2
	v_sub_f32_e32 v2, v34, v35
	v_exp_f32_e32 v40, v40
	v_sub_f32_e32 v39, v39, v18
	v_exp_f32_e32 v34, v2
	v_sub_f32_e32 v2, v33, v35
	v_exp_f32_e32 v39, v39
	v_sub_f32_e32 v38, v38, v18
	v_exp_f32_e32 v33, v2
	v_add_f32_e32 v2, 0, v163
	v_exp_f32_e32 v38, v38
	v_sub_f32_e32 v37, v37, v18
	v_add_f32_e32 v2, v164, v2
	v_add_f32_e32 v46, 0, v41
	v_exp_f32_e32 v37, v37
	v_sub_f32_e32 v36, v36, v18
	v_add_f32_e32 v2, v165, v2
	v_add_f32_e32 v46, v40, v46
	v_exp_f32_e32 v36, v36
	v_sub_f32_e32 v23, v23, v18
	v_add_f32_e32 v2, v182, v2
	v_add_f32_e32 v46, v39, v46
	v_exp_f32_e32 v23, v23
	v_sub_f32_e32 v22, v22, v18
	v_add_f32_e32 v2, v183, v2
	v_add_f32_e32 v46, v38, v46
	v_exp_f32_e32 v22, v22
	v_sub_f32_e32 v21, v21, v18
	v_add_f32_e32 v2, v184, v2
	v_add_f32_e32 v46, v37, v46
	v_exp_f32_e32 v21, v21
	v_sub_f32_e32 v20, v20, v18
	v_add_f32_e32 v2, v185, v2
	v_add_f32_e32 v46, v36, v46
	v_exp_f32_e32 v20, v20
	v_sub_f32_e32 v19, v19, v18
	v_add_f32_e32 v2, v186, v2
	v_add_f32_e32 v46, v23, v46
	v_exp_f32_e32 v19, v19
	v_sub_f32_e32 v17, v17, v18
	v_add_f32_e32 v2, v187, v2
	v_add_f32_e32 v46, v22, v46
	v_exp_f32_e32 v17, v17
	v_sub_f32_e32 v16, v16, v18
	v_add_f32_e32 v2, v188, v2
	v_add_f32_e32 v46, v21, v46
	v_exp_f32_e32 v16, v16
	v_sub_f32_e32 v15, v15, v18
	v_add_f32_e32 v2, v189, v2
	v_add_f32_e32 v46, v20, v46
	v_exp_f32_e32 v15, v15
	v_sub_f32_e32 v14, v14, v18
	v_add_f32_e32 v2, v190, v2
	v_add_f32_e32 v46, v19, v46
	v_exp_f32_e32 v14, v14
	v_sub_f32_e32 v13, v13, v18
	v_add_f32_e32 v2, v191, v2
	v_add_f32_e32 v46, v17, v46
	v_exp_f32_e32 v18, v13
	v_add_f32_e32 v2, v192, v2
	v_add_f32_e32 v46, v16, v46
	v_add_f32_e32 v2, v193, v2
	v_add_f32_e32 v46, v15, v46
	v_add_f32_e32 v35, v204, v2
	v_add_f32_e32 v46, v14, v46
	v_fmac_f32_e32 v35, v181, v140
	v_add_f32_e32 v128, v18, v46
	v_fmac_f32_e32 v128, v35, v12
	v_add_f32_e32 v12, 0, v141
	v_add_f32_e32 v12, v142, v12
	v_add_f32_e32 v12, v143, v12
	v_add_f32_e32 v12, v144, v12
	v_add_f32_e32 v12, v145, v12
	v_add_f32_e32 v12, v146, v12
	v_add_f32_e32 v12, v147, v12
	v_add_f32_e32 v12, v148, v12
	v_add_f32_e32 v12, v149, v12
	v_add_f32_e32 v12, v150, v12
	v_add_f32_e32 v12, v151, v12
	v_add_f32_e32 v12, v156, v12
	v_add_f32_e32 v12, v157, v12
	v_add_f32_e32 v12, v158, v12
	v_add_f32_e32 v12, v159, v12
	v_add_f32_e32 v12, v160, v12
	v_fmac_f32_e32 v12, v180, v0
	v_add_f32_e32 v0, 0, v42
	v_add_f32_e32 v0, v43, v0
	v_add_f32_e32 v0, v44, v0
	v_add_f32_e32 v0, v45, v0
	v_add_f32_e32 v0, v24, v0
	v_add_f32_e32 v0, v11, v0
	v_add_f32_e32 v0, v26, v0
	v_add_f32_e32 v0, v25, v0
	v_add_f32_e32 v0, v28, v0
	v_add_f32_e32 v0, v27, v0
	v_add_f32_e32 v0, v30, v0
	v_add_f32_e32 v0, v29, v0
	v_add_f32_e32 v0, v32, v0
	v_add_f32_e32 v0, v31, v0
	v_add_f32_e32 v0, v34, v0
	v_cvt_pk_bf16_f32 v9, v26, v25
	v_cvt_pk_bf16_f32 v2, v28, v27
	v_cvt_pk_bf16_f32 v3, v30, v29
	v_cvt_pk_bf16_f32 v4, v32, v31
	v_cvt_pk_bf16_f32 v5, v34, v33
	v_add_f32_e32 v0, v33, v0
	v_cvt_pk_bf16_f32 v124, v21, v20
	v_cvt_pk_bf16_f32 v125, v19, v17
	v_cvt_pk_bf16_f32 v126, v16, v15
	v_cvt_pk_bf16_f32 v127, v14, v18
	ds_read2_b64 v[14:17], v168 offset0:128 offset1:132
	ds_read2_b64 v[18:21], v173 offset0:160 offset1:164
	ds_read2_b64 v[26:29], v169 offset0:192 offset1:196
	ds_read2_b64 v[30:33], v172 offset0:224 offset1:228
	v_cvt_pk_bf16_f32 v6, v42, v43
	v_cvt_pk_bf16_f32 v7, v44, v45
	v_cvt_pk_bf16_f32 v8, v24, v11
	v_fmac_f32_e32 v0, v12, v10
	v_cvt_pk_bf16_f32 v10, v41, v40
	v_cvt_pk_bf16_f32 v11, v39, v38
	v_cvt_pk_bf16_f32 v12, v37, v36
	v_cvt_pk_bf16_f32 v13, v23, v22
	s_waitcnt lgkmcnt(1)
	v_mfma_f32_16x16x32_bf16 v[38:41], v[26:29], v[6:9], v[104:107]
	s_add_u32 s0, s72, s0
	s_addc_u32 s1, s73, s1
	s_movk_i32 s3, 0x3a00
	v_mfma_f32_16x16x32_bf16 v[42:45], v[26:29], v[10:13], v[100:103]
	ds_read2_b64 v[26:29], v174 offset1:4
	s_lshl_b32 s20, s2, 8
	s_mov_b32 s2, 0xa28c000
	s_waitcnt lgkmcnt(1)
	v_mfma_f32_16x16x32_bf16 v[46:49], v[30:33], v[6:9], v[96:99]
	v_mfma_f32_16x16x32_bf16 v[92:95], v[30:33], v[10:13], v[92:95]
	ds_read2_b64 v[30:33], v175 offset0:32 offset1:36
	s_waitcnt lgkmcnt(1)
	v_mfma_f32_16x16x32_bf16 v[88:91], v[26:29], v[6:9], v[88:91]
	v_mfma_f32_16x16x32_bf16 v[84:87], v[26:29], v[10:13], v[84:87]
	ds_read2_b64 v[26:29], v176 offset0:64 offset1:68
	s_waitcnt lgkmcnt(1)
	v_mfma_f32_16x16x32_bf16 v[80:83], v[30:33], v[6:9], v[80:83]
	v_mfma_f32_16x16x32_bf16 v[76:79], v[30:33], v[10:13], v[76:79]
	ds_read2_b64 v[30:33], v177 offset0:96 offset1:100
	v_mfma_f32_16x16x32_bf16 v[22:25], v[14:17], v[6:9], v[120:123]
	v_mfma_f32_16x16x32_bf16 v[34:37], v[18:21], v[6:9], v[112:115]
	s_waitcnt lgkmcnt(1)
	v_mfma_f32_16x16x32_bf16 v[72:75], v[26:29], v[6:9], v[72:75]
	v_mfma_f32_16x16x32_bf16 v[68:71], v[26:29], v[10:13], v[68:71]
	ds_read2_b64 v[26:29], v168 offset0:136 offset1:140
	s_waitcnt lgkmcnt(1)
; DEVI float bf2f(u16 h) { return __uint_as_float(((unsigned)h) << 16); }
; DEVI float bfs(short h) { return __uint_as_float(((unsigned)(u16)h) << 16); }
; DEVI float silu_f(float x) { return x / (1.f + __expf(-x)); }
; #define SHX(v, m) __int_as_float(__builtin_amdgcn_ds_bpermute(((LANE ^ (m)) << 2), __float_as_int(v)))
; template <int DQK, int QT, bool NA> ...
;     ...
;       {
;         const u16* vb0 = Vs + l15 * 72 + quad * 4;
;         bf16x4 n0 = *(const bf16x4*)vb0, n1 = *(const bf16x4*)(vb0 + 16);
; #pragma unroll
;         for (int idx = 0; idx < 16; ++idx) {
;           const int kk = idx >> 3, dt = idx & 7;
;           bf16x8 va = {n0[0], n0[1], n0[2], n0[3], n1[0], n1[1], n1[2], n1[3]};
;           if (idx + 1 < 16) {
;             const int kk2 = (idx + 1) >> 3, dt2 = (idx + 1) & 7;
;             const u16* vb = Vs + (dt2 * 16 + l15) * 72 + kk2 * 32 + quad * 4;
;             n0 = *(const bf16x4*)vb;
;             n1 = *(const bf16x4*)(vb + 16);
;           }
; #pragma unroll
;           for (int qt = 0; qt < QT; ++qt) o[dt][qt] = __builtin_amdgcn_mfma_f32_16x16x32_bf16(va, pf[qt][kk], o[dt][qt], 0, 0, 0);
;         }
;     ...
;   const u16* proj = (const u16*)(ws + O_PROJ);
;   u16* ys = (u16*)(ws + O_YS);
; #pragma unroll
;   for (int qt = 0; qt < QT; ++qt) {
;     float lt = lrun[qt];
;     lt += SHX(lt, 16);
;     lt += SHX(lt, 32);
;     float il = 1.f / lt;
;     int r = qrow0 + wid * 16 * QT + qt * 16 + l15;
; #pragma unroll
;     for (int dt = 0; dt < 8; ++dt) {
;       int dv = dt * 16 + quad * 4;
;       bf16x4 g = *(const bf16x4*)(proj + (size_t)r * NP + gatecol + h * 128 + dv);
;       bf16x4 ov;
; #pragma unroll
;       for (int j = 0; j < 4; ++j) {
;         float y = bf2f(f2bf(o[dt][qt][j] * il));
;         ov[j] = (short)f2bf(y * silu_f(bfs(g[j])));
;       }
;       *(bf16x4*)(ys + (size_t)r * 2048 + ycol + h * 128 + dv) = ov;
;     }
;   }
	v_mfma_f32_16x16x32_bf16 v[96:99], v[30:33], v[6:9], v[64:67]
	ds_read2_b64 v[6:9], v173 offset0:168 offset1:172
	v_mfma_f32_16x16x32_bf16 v[14:17], v[14:17], v[10:13], v[116:119]
	s_nop 0
	ds_bpermute_b32 v66, v153, v0
	s_waitcnt lgkmcnt(0)
	v_add_f32_e32 v0, v0, v66
	v_mfma_f32_16x16x32_bf16 v[18:21], v[18:21], v[10:13], v[108:111]
	ds_bpermute_b32 v66, v155, v0
	s_waitcnt lgkmcnt(0)
	v_add_f32_e32 v0, v0, v66
	v_mfma_f32_16x16x32_bf16 v[100:103], v[30:33], v[10:13], v[60:63]
	ds_read2_b64 v[10:13], v169 offset0:200 offset1:204
	v_rcp_f32_e32 v66, v0
	v_mfma_f32_16x16x32_bf16 v[62:65], v[26:29], v[2:5], v[22:25]
	s_nop 0
	s_movk_i32 s4, 0xd600
	s_mov_b32 s5, 0x2223c000
	v_mfma_f32_16x16x32_bf16 v[30:33], v[26:29], v[124:127], v[14:17]
	v_mfma_f32_16x16x32_bf16 v[58:61], v[6:9], v[2:5], v[34:37]
	v_mfma_f32_16x16x32_bf16 v[26:29], v[6:9], v[124:127], v[18:21]
	ds_read2_b64 v[6:9], v172 offset0:232 offset1:236
	s_nop 0
	ds_read2_b64 v[34:37], v176 offset0:72 offset1:76
	s_waitcnt lgkmcnt(2)
	v_mfma_f32_16x16x32_bf16 v[54:57], v[10:13], v[2:5], v[38:41]
	v_mfma_f32_16x16x32_bf16 v[22:25], v[10:13], v[124:127], v[42:45]
	ds_read2_b64 v[10:13], v174 offset0:8 offset1:12
	s_waitcnt lgkmcnt(2)
	v_mfma_f32_16x16x32_bf16 v[50:53], v[6:9], v[2:5], v[46:49]
	v_mfma_f32_16x16x32_bf16 v[18:21], v[6:9], v[124:127], v[92:95]
	ds_read2_b64 v[6:9], v175 offset0:40 offset1:44
	s_waitcnt lgkmcnt(1)
	v_mfma_f32_16x16x32_bf16 v[46:49], v[10:13], v[2:5], v[88:91]
	v_mfma_f32_16x16x32_bf16 v[14:17], v[10:13], v[124:127], v[84:87]
	s_waitcnt lgkmcnt(0)
	v_mfma_f32_16x16x32_bf16 v[42:45], v[6:9], v[2:5], v[80:83]
	v_mfma_f32_16x16x32_bf16 v[10:13], v[6:9], v[124:127], v[76:79]
	v_mfma_f32_16x16x32_bf16 v[6:9], v[34:37], v[124:127], v[68:71]
	s_nop 1
	ds_read2_b64 v[76:79], v177 offset0:104 offset1:108
	s_waitcnt lgkmcnt(0)
	s_barrier
	v_mfma_f32_16x16x32_bf16 v[38:41], v[34:37], v[2:5], v[72:75]
	v_fma_f32 v68, -v0, v66, 1.0
	v_fma_f32 v66, v68, v66, v66
	v_mov_b32_e32 v68, v66
	v_mov_b64_e32 v[66:67], s[0:1]
	v_mad_i64_i32 v[70:71], s[0:1], v154, s3, v[66:67]
	v_lshl_add_u64 v[74:75], v[70:71], 0, s[20:21]
	v_lshlrev_b32_e32 v0, 1, v166
	v_mad_i64_i32 v[70:71], s[0:1], v154, s4, v[70:71]
	v_lshl_add_u64 v[74:75], v[74:75], 0, v[0:1]
	v_lshl_add_u64 v[72:73], v[70:71], 0, s[20:21]
	v_lshl_add_u64 v[70:71], v[74:75], 0, s[14:15]
	v_add_co_u32_e32 v74, vcc, s2, v74
	v_pk_mul_f32 v[62:63], v[62:63], v[68:69] op_sel_hi:[1,0]
	s_nop 0
	v_addc_co_u32_e32 v75, vcc, 0, v75, vcc
	global_load_dwordx2 v[74:75], v[74:75], off offset:128
	s_waitcnt lgkmcnt(0)
	v_mfma_f32_16x16x32_bf16 v[34:37], v[76:79], v[2:5], v[96:99]
	v_lshl_add_u64 v[72:73], v[72:73], 0, v[0:1]
	s_waitcnt vmcnt(0)
	v_and_b32_e32 v69, 0xffff0000, v74
	v_mfma_f32_16x16x32_bf16 v[2:5], v[76:79], v[124:127], v[100:103]
	v_lshlrev_b32_e32 v74, 16, v74
	v_and_b32_sdwa v77, v63, v195 dst_sel:DWORD dst_unused:UNUSED_PAD src0_sel:WORD_1 src1_sel:DWORD
	v_mul_f32_e32 v76, 0xbfb8aa3b, v74
	v_add3_u32 v63, v63, v77, s33
	v_mul_f32_e32 v77, 0xbfb8aa3b, v69
	v_exp_f32_e32 v76, v76
	v_exp_f32_e32 v77, v77
	v_and_b32_sdwa v78, v62, v195 dst_sel:DWORD dst_unused:UNUSED_PAD src0_sel:WORD_1 src1_sel:DWORD
	v_add3_u32 v62, v62, v78, s33
	v_and_b32_e32 v63, 0xffff0000, v63
	v_pk_add_f32 v[76:77], v[76:77], 1.0 op_sel_hi:[1,0]
	v_and_b32_e32 v62, 0xffff0000, v62
	v_rcp_f32_e32 v78, v77
	s_nop 0
	s_nop 0
	v_fma_f32 v80, -v77, v78, 1.0
	v_fma_f32 v78, v80, v78, v78
	v_mul_f32_e32 v77, v69, v78
	v_rcp_f32_e32 v69, v76
	s_nop 0
	s_nop 0
	v_fma_f32 v79, -v76, v69, 1.0
	v_fma_f32 v69, v79, v69, v69
	v_mul_f32_e32 v76, v74, v69
	v_pk_mul_f32 v[64:65], v[64:65], v[68:69] op_sel_hi:[1,0]
	v_pk_mul_f32 v[62:63], v[76:77], v[62:63]
	v_and_b32_e32 v69, 0xffff0000, v75
	v_lshlrev_b32_e32 v76, 16, v75
	v_and_b32_sdwa v75, v65, v195 dst_sel:DWORD dst_unused:UNUSED_PAD src0_sel:WORD_1 src1_sel:DWORD
	v_mul_f32_e32 v74, 0xbfb8aa3b, v76
	v_add3_u32 v65, v65, v75, s33
	v_mul_f32_e32 v75, 0xbfb8aa3b, v69
	v_exp_f32_e32 v74, v74
	v_exp_f32_e32 v75, v75
	v_and_b32_sdwa v77, v64, v195 dst_sel:DWORD dst_unused:UNUSED_PAD src0_sel:WORD_1 src1_sel:DWORD
	v_add3_u32 v64, v64, v77, s33
	v_and_b32_e32 v65, 0xffff0000, v65
	v_pk_add_f32 v[74:75], v[74:75], 1.0 op_sel_hi:[1,0]
	v_and_b32_e32 v64, 0xffff0000, v64
	v_rcp_f32_e32 v77, v75
	s_nop 0
	s_nop 0
	v_fma_f32 v79, -v75, v77, 1.0
	v_fma_f32 v77, v79, v77, v77
	v_mul_f32_e32 v75, v69, v77
	v_rcp_f32_e32 v69, v74
	s_nop 0
	s_nop 0
	v_fma_f32 v78, -v74, v69, 1.0
	v_fma_f32 v69, v78, v69, v69
	v_mul_f32_e32 v74, v76, v69
	v_pk_mul_f32 v[64:65], v[74:75], v[64:65]
	v_bfe_u32 v75, v63, 16, 1
	v_bfe_u32 v69, v65, 16, 1
	v_bfe_u32 v74, v64, 16, 1
	v_bfe_u32 v76, v62, 16, 1
	v_add3_u32 v64, v64, v74, s33
	v_add3_u32 v65, v65, v69, s33
	v_add3_u32 v62, v62, v76, s33
	v_add3_u32 v63, v63, v75, s33
	v_perm_b32 v65, v65, v64, s27
	v_perm_b32 v64, v63, v62, s27
	v_lshl_add_u64 v[62:63], v[72:73], 0, s[16:17]
	v_add_co_u32_e32 v72, vcc, s5, v72
	v_pk_mul_f32 v[58:59], v[58:59], v[68:69] op_sel_hi:[1,0]
	s_nop 0
	v_addc_co_u32_e32 v73, vcc, 0, v73, vcc
	global_store_dwordx2 v[72:73], v[64:65], off offset:2048
	global_load_dwordx2 v[64:65], v[70:71], off offset:32
	v_and_b32_sdwa v73, v59, v195 dst_sel:DWORD dst_unused:UNUSED_PAD src0_sel:WORD_1 src1_sel:DWORD
	v_add3_u32 v59, v59, v73, s33
	v_and_b32_sdwa v74, v58, v195 dst_sel:DWORD dst_unused:UNUSED_PAD src0_sel:WORD_1 src1_sel:DWORD
	v_add3_u32 v58, v58, v74, s33
	v_and_b32_e32 v59, 0xffff0000, v59
	v_and_b32_e32 v58, 0xffff0000, v58
	s_waitcnt vmcnt(0)
; DEVI float bf2f(u16 h) { return __uint_as_float(((unsigned)h) << 16); }
; DEVI float bfs(short h) { return __uint_as_float(((unsigned)(u16)h) << 16); }
; DEVI float silu_f(float x) { return x / (1.f + __expf(-x)); }
; template <int DQK, int QT, bool NA> ...
;     ...
;     for (int dt = 0; dt < 8; ++dt) {
;       int dv = dt * 16 + quad * 4;
;       bf16x4 g = *(const bf16x4*)(proj + (size_t)r * NP + gatecol + h * 128 + dv);
;       bf16x4 ov;
; #pragma unroll
;       for (int j = 0; j < 4; ++j) {
;         float y = bf2f(f2bf(o[dt][qt][j] * il));
;         ov[j] = (short)f2bf(y * silu_f(bfs(g[j])));
;       }
;       *(bf16x4*)(ys + (size_t)r * 2048 + ycol + h * 128 + dv) = ov;
	v_and_b32_e32 v69, 0xffff0000, v64
	v_lshlrev_b32_e32 v64, 16, v64
	v_mul_f32_e32 v72, 0xbfb8aa3b, v64
	v_mul_f32_e32 v73, 0xbfb8aa3b, v69
	v_exp_f32_e32 v72, v72
	v_exp_f32_e32 v73, v73
	s_nop 0
	v_pk_add_f32 v[72:73], v[72:73], 1.0 op_sel_hi:[1,0]
	s_nop 0
	v_rcp_f32_e32 v74, v73
	s_nop 0
	s_nop 0
	v_fma_f32 v76, -v73, v74, 1.0
	v_fma_f32 v74, v76, v74, v74
	v_mul_f32_e32 v73, v69, v74
	v_rcp_f32_e32 v69, v72
	s_nop 0
	s_nop 0
	v_fma_f32 v75, -v72, v69, 1.0
	v_fma_f32 v69, v75, v69, v69
	v_mul_f32_e32 v72, v64, v69
	v_pk_mul_f32 v[60:61], v[60:61], v[68:69] op_sel_hi:[1,0]
	v_pk_mul_f32 v[58:59], v[72:73], v[58:59]
	v_and_b32_e32 v69, 0xffff0000, v65
	v_lshlrev_b32_e32 v72, 16, v65
	v_and_b32_sdwa v65, v61, v195 dst_sel:DWORD dst_unused:UNUSED_PAD src0_sel:WORD_1 src1_sel:DWORD
	v_mul_f32_e32 v64, 0xbfb8aa3b, v72
	v_add3_u32 v61, v61, v65, s33
	v_mul_f32_e32 v65, 0xbfb8aa3b, v69
	v_exp_f32_e32 v64, v64
	v_exp_f32_e32 v65, v65
	v_and_b32_sdwa v73, v60, v195 dst_sel:DWORD dst_unused:UNUSED_PAD src0_sel:WORD_1 src1_sel:DWORD
	v_add3_u32 v60, v60, v73, s33
	v_and_b32_e32 v61, 0xffff0000, v61
	v_pk_add_f32 v[64:65], v[64:65], 1.0 op_sel_hi:[1,0]
	v_and_b32_e32 v60, 0xffff0000, v60
	v_rcp_f32_e32 v73, v65
	s_nop 0
	s_nop 0
	v_fma_f32 v75, -v65, v73, 1.0
	v_fma_f32 v73, v75, v73, v73
	v_mul_f32_e32 v65, v69, v73
	v_rcp_f32_e32 v69, v64
	s_nop 0
	s_nop 0
	v_fma_f32 v74, -v64, v69, 1.0
	v_fma_f32 v69, v74, v69, v69
	v_mul_f32_e32 v64, v72, v69
	v_pk_mul_f32 v[60:61], v[64:65], v[60:61]
	v_bfe_u32 v69, v59, 16, 1
	v_bfe_u32 v64, v61, 16, 1
	v_bfe_u32 v65, v60, 16, 1
	v_bfe_u32 v72, v58, 16, 1
	v_add3_u32 v60, v60, v65, s33
	v_add3_u32 v61, v61, v64, s33
	v_add3_u32 v58, v58, v72, s33
	v_add3_u32 v64, v59, v69, s33
	v_perm_b32 v59, v61, v60, s27
	v_perm_b32 v58, v64, v58, s27
	global_store_dwordx2 v[62:63], v[58:59], off offset:32
	global_load_dwordx2 v[58:59], v[70:71], off offset:64
	v_pk_mul_f32 v[54:55], v[54:55], v[68:69] op_sel_hi:[1,0]
	s_waitcnt vmcnt(0)
	v_and_b32_e32 v64, 0xffff0000, v58
	v_lshlrev_b32_e32 v58, 16, v58
	v_and_b32_sdwa v61, v55, v195 dst_sel:DWORD dst_unused:UNUSED_PAD src0_sel:WORD_1 src1_sel:DWORD
	v_mul_f32_e32 v60, 0xbfb8aa3b, v58
	v_add3_u32 v55, v55, v61, s33
	v_mul_f32_e32 v61, 0xbfb8aa3b, v64
	v_exp_f32_e32 v60, v60
	v_exp_f32_e32 v61, v61
	v_and_b32_sdwa v65, v54, v195 dst_sel:DWORD dst_unused:UNUSED_PAD src0_sel:WORD_1 src1_sel:DWORD
	v_add3_u32 v54, v54, v65, s33
	v_and_b32_e32 v55, 0xffff0000, v55
	v_pk_add_f32 v[60:61], v[60:61], 1.0 op_sel_hi:[1,0]
	v_and_b32_e32 v54, 0xffff0000, v54
	v_rcp_f32_e32 v65, v61
	s_nop 0
	s_nop 0
	v_fma_f32 v72, -v61, v65, 1.0
	v_fma_f32 v65, v72, v65, v65
	v_mul_f32_e32 v61, v64, v65
	v_rcp_f32_e32 v64, v60
	s_nop 0
	s_nop 0
	v_fma_f32 v69, -v60, v64, 1.0
	v_fma_f32 v64, v69, v64, v64
	v_mul_f32_e32 v60, v58, v64
	v_pk_mul_f32 v[56:57], v[56:57], v[68:69] op_sel_hi:[1,0]
	v_pk_mul_f32 v[54:55], v[60:61], v[54:55]
	v_and_b32_e32 v60, 0xffff0000, v59
	v_lshlrev_b32_e32 v61, 16, v59
	v_and_b32_sdwa v59, v57, v195 dst_sel:DWORD dst_unused:UNUSED_PAD src0_sel:WORD_1 src1_sel:DWORD
	v_mul_f32_e32 v58, 0xbfb8aa3b, v61
	v_add3_u32 v57, v57, v59, s33
	v_mul_f32_e32 v59, 0xbfb8aa3b, v60
	v_exp_f32_e32 v58, v58
	v_exp_f32_e32 v59, v59
	v_and_b32_sdwa v64, v56, v195 dst_sel:DWORD dst_unused:UNUSED_PAD src0_sel:WORD_1 src1_sel:DWORD
	v_add3_u32 v56, v56, v64, s33
	v_and_b32_e32 v57, 0xffff0000, v57
	v_pk_add_f32 v[58:59], v[58:59], 1.0 op_sel_hi:[1,0]
	v_and_b32_e32 v56, 0xffff0000, v56
	v_rcp_f32_e32 v64, v59
	s_nop 0
	s_nop 0
	v_fma_f32 v69, -v59, v64, 1.0
	v_fma_f32 v64, v69, v64, v64
	v_mul_f32_e32 v59, v60, v64
	v_rcp_f32_e32 v60, v58
	s_nop 0
	s_nop 0
	v_fma_f32 v65, -v58, v60, 1.0
	v_fma_f32 v60, v65, v60, v60
	v_mul_f32_e32 v58, v61, v60
	v_pk_mul_f32 v[56:57], v[58:59], v[56:57]
	v_bfe_u32 v60, v55, 16, 1
	v_bfe_u32 v58, v57, 16, 1
	v_bfe_u32 v59, v56, 16, 1
	v_bfe_u32 v61, v54, 16, 1
	v_add3_u32 v56, v56, v59, s33
	v_add3_u32 v57, v57, v58, s33
	v_add3_u32 v54, v54, v61, s33
	v_add3_u32 v58, v55, v60, s33
	v_perm_b32 v55, v57, v56, s27
	v_perm_b32 v54, v58, v54, s27
	global_store_dwordx2 v[62:63], v[54:55], off offset:64
	global_load_dwordx2 v[54:55], v[70:71], off offset:96
	v_pk_mul_f32 v[50:51], v[50:51], v[68:69] op_sel_hi:[1,0]
	v_pk_mul_f32 v[52:53], v[52:53], v[68:69] op_sel_hi:[1,0]
	v_and_b32_sdwa v57, v51, v195 dst_sel:DWORD dst_unused:UNUSED_PAD src0_sel:WORD_1 src1_sel:DWORD
	v_add3_u32 v51, v51, v57, s33
	v_and_b32_sdwa v59, v50, v195 dst_sel:DWORD dst_unused:UNUSED_PAD src0_sel:WORD_1 src1_sel:DWORD
	v_add3_u32 v50, v50, v59, s33
	v_and_b32_e32 v51, 0xffff0000, v51
	v_and_b32_e32 v50, 0xffff0000, v50
	v_pk_mul_f32 v[46:47], v[46:47], v[68:69] op_sel_hi:[1,0]
	v_pk_mul_f32 v[48:49], v[48:49], v[68:69] op_sel_hi:[1,0]
	v_pk_mul_f32 v[42:43], v[42:43], v[68:69] op_sel_hi:[1,0]
	v_pk_mul_f32 v[44:45], v[44:45], v[68:69] op_sel_hi:[1,0]
	v_pk_mul_f32 v[38:39], v[38:39], v[68:69] op_sel_hi:[1,0]
	v_pk_mul_f32 v[40:41], v[40:41], v[68:69] op_sel_hi:[1,0]
	v_pk_mul_f32 v[34:35], v[34:35], v[68:69] op_sel_hi:[1,0]
	v_pk_mul_f32 v[36:37], v[36:37], v[68:69] op_sel_hi:[1,0]
	s_waitcnt vmcnt(0)
; DEVI float bf2f(u16 h) { return __uint_as_float(((unsigned)h) << 16); }
; DEVI float bfs(short h) { return __uint_as_float(((unsigned)(u16)h) << 16); }
; DEVI float silu_f(float x) { return x / (1.f + __expf(-x)); }
; template <int DQK, int QT, bool NA> ...
;     ...
;     for (int dt = 0; dt < 8; ++dt) {
;       int dv = dt * 16 + quad * 4;
;       bf16x4 g = *(const bf16x4*)(proj + (size_t)r * NP + gatecol + h * 128 + dv);
;       bf16x4 ov;
; #pragma unroll
;       for (int j = 0; j < 4; ++j) {
;         float y = bf2f(f2bf(o[dt][qt][j] * il));
;         ov[j] = (short)f2bf(y * silu_f(bfs(g[j])));
;       }
;       *(bf16x4*)(ys + (size_t)r * 2048 + ycol + h * 128 + dv) = ov;
	v_and_b32_e32 v58, 0xffff0000, v54
	v_lshlrev_b32_e32 v54, 16, v54
	v_mul_f32_e32 v56, 0xbfb8aa3b, v54
	v_mul_f32_e32 v57, 0xbfb8aa3b, v58
	v_exp_f32_e32 v56, v56
	v_exp_f32_e32 v57, v57
	s_nop 0
	v_pk_add_f32 v[56:57], v[56:57], 1.0 op_sel_hi:[1,0]
	s_nop 0
	v_rcp_f32_e32 v59, v57
	s_nop 0
	s_nop 0
	v_fma_f32 v61, -v57, v59, 1.0
	v_fma_f32 v59, v61, v59, v59
	v_mul_f32_e32 v57, v58, v59
	v_rcp_f32_e32 v58, v56
	s_nop 0
	s_nop 0
	v_fma_f32 v60, -v56, v58, 1.0
	v_fma_f32 v58, v60, v58, v58
	v_mul_f32_e32 v56, v54, v58
	v_pk_mul_f32 v[50:51], v[56:57], v[50:51]
	v_and_b32_e32 v56, 0xffff0000, v55
	v_lshlrev_b32_e32 v57, 16, v55
	v_and_b32_sdwa v55, v53, v195 dst_sel:DWORD dst_unused:UNUSED_PAD src0_sel:WORD_1 src1_sel:DWORD
	v_mul_f32_e32 v54, 0xbfb8aa3b, v57
	v_add3_u32 v53, v53, v55, s33
	v_mul_f32_e32 v55, 0xbfb8aa3b, v56
	v_exp_f32_e32 v54, v54
	v_exp_f32_e32 v55, v55
	v_and_b32_sdwa v58, v52, v195 dst_sel:DWORD dst_unused:UNUSED_PAD src0_sel:WORD_1 src1_sel:DWORD
	v_add3_u32 v52, v52, v58, s33
	v_and_b32_e32 v53, 0xffff0000, v53
	v_pk_add_f32 v[54:55], v[54:55], 1.0 op_sel_hi:[1,0]
	v_and_b32_e32 v52, 0xffff0000, v52
	v_rcp_f32_e32 v58, v55
	s_nop 0
	s_nop 0
	v_fma_f32 v60, -v55, v58, 1.0
	v_fma_f32 v58, v60, v58, v58
	v_mul_f32_e32 v55, v56, v58
	v_rcp_f32_e32 v56, v54
	s_nop 0
	s_nop 0
	v_fma_f32 v59, -v54, v56, 1.0
	v_fma_f32 v56, v59, v56, v56
	v_mul_f32_e32 v54, v57, v56
	v_pk_mul_f32 v[52:53], v[54:55], v[52:53]
	v_bfe_u32 v56, v51, 16, 1
	v_bfe_u32 v54, v53, 16, 1
	v_bfe_u32 v55, v52, 16, 1
	v_bfe_u32 v57, v50, 16, 1
	v_add3_u32 v52, v52, v55, s33
	v_add3_u32 v53, v53, v54, s33
	v_add3_u32 v50, v50, v57, s33
	v_add3_u32 v54, v51, v56, s33
	v_perm_b32 v51, v53, v52, s27
	v_perm_b32 v50, v54, v50, s27
	global_store_dwordx2 v[62:63], v[50:51], off offset:96
	global_load_dwordx2 v[50:51], v[70:71], off offset:128
	v_and_b32_sdwa v53, v47, v195 dst_sel:DWORD dst_unused:UNUSED_PAD src0_sel:WORD_1 src1_sel:DWORD
	v_add3_u32 v47, v47, v53, s33
	v_and_b32_sdwa v55, v46, v195 dst_sel:DWORD dst_unused:UNUSED_PAD src0_sel:WORD_1 src1_sel:DWORD
	v_add3_u32 v46, v46, v55, s33
	v_and_b32_e32 v47, 0xffff0000, v47
	v_and_b32_e32 v46, 0xffff0000, v46
	s_waitcnt vmcnt(0)
	v_and_b32_e32 v54, 0xffff0000, v50
	v_lshlrev_b32_e32 v50, 16, v50
	v_mul_f32_e32 v52, 0xbfb8aa3b, v50
	v_mul_f32_e32 v53, 0xbfb8aa3b, v54
	v_exp_f32_e32 v52, v52
	v_exp_f32_e32 v53, v53
	s_nop 0
	v_pk_add_f32 v[52:53], v[52:53], 1.0 op_sel_hi:[1,0]
	s_nop 0
	v_rcp_f32_e32 v55, v53
	s_nop 0
	s_nop 0
	v_fma_f32 v57, -v53, v55, 1.0
	v_fma_f32 v55, v57, v55, v55
	v_mul_f32_e32 v53, v54, v55
	v_rcp_f32_e32 v54, v52
	s_nop 0
	s_nop 0
	v_fma_f32 v56, -v52, v54, 1.0
	v_fma_f32 v54, v56, v54, v54
	v_mul_f32_e32 v52, v50, v54
	v_pk_mul_f32 v[46:47], v[52:53], v[46:47]
	v_and_b32_e32 v52, 0xffff0000, v51
	v_lshlrev_b32_e32 v53, 16, v51
	v_and_b32_sdwa v51, v49, v195 dst_sel:DWORD dst_unused:UNUSED_PAD src0_sel:WORD_1 src1_sel:DWORD
	v_mul_f32_e32 v50, 0xbfb8aa3b, v53
	v_add3_u32 v49, v49, v51, s33
	v_mul_f32_e32 v51, 0xbfb8aa3b, v52
	v_exp_f32_e32 v50, v50
	v_exp_f32_e32 v51, v51
	v_and_b32_sdwa v54, v48, v195 dst_sel:DWORD dst_unused:UNUSED_PAD src0_sel:WORD_1 src1_sel:DWORD
	v_add3_u32 v48, v48, v54, s33
	v_and_b32_e32 v49, 0xffff0000, v49
	v_pk_add_f32 v[50:51], v[50:51], 1.0 op_sel_hi:[1,0]
	v_and_b32_e32 v48, 0xffff0000, v48
	v_rcp_f32_e32 v54, v51
	s_nop 0
	s_nop 0
	v_fma_f32 v56, -v51, v54, 1.0
	v_fma_f32 v54, v56, v54, v54
	v_mul_f32_e32 v51, v52, v54
	v_rcp_f32_e32 v52, v50
	s_nop 0
	s_nop 0
	v_fma_f32 v55, -v50, v52, 1.0
	v_fma_f32 v52, v55, v52, v52
	v_mul_f32_e32 v50, v53, v52
	v_pk_mul_f32 v[48:49], v[50:51], v[48:49]
	v_bfe_u32 v52, v47, 16, 1
	v_bfe_u32 v50, v49, 16, 1
	v_bfe_u32 v51, v48, 16, 1
	v_bfe_u32 v53, v46, 16, 1
	v_add3_u32 v48, v48, v51, s33
	v_add3_u32 v49, v49, v50, s33
	v_add3_u32 v46, v46, v53, s33
	v_add3_u32 v50, v47, v52, s33
	v_perm_b32 v47, v49, v48, s27
	v_perm_b32 v46, v50, v46, s27
	global_store_dwordx2 v[62:63], v[46:47], off offset:128
	global_load_dwordx2 v[46:47], v[70:71], off offset:160
	v_and_b32_sdwa v49, v43, v195 dst_sel:DWORD dst_unused:UNUSED_PAD src0_sel:WORD_1 src1_sel:DWORD
	v_add3_u32 v43, v43, v49, s33
	v_and_b32_sdwa v51, v42, v195 dst_sel:DWORD dst_unused:UNUSED_PAD src0_sel:WORD_1 src1_sel:DWORD
	v_add3_u32 v42, v42, v51, s33
	v_and_b32_e32 v43, 0xffff0000, v43
	v_and_b32_e32 v42, 0xffff0000, v42
	s_waitcnt vmcnt(0)
	v_and_b32_e32 v50, 0xffff0000, v46
	v_lshlrev_b32_e32 v46, 16, v46
	v_mul_f32_e32 v48, 0xbfb8aa3b, v46
	v_mul_f32_e32 v49, 0xbfb8aa3b, v50
	v_exp_f32_e32 v48, v48
	v_exp_f32_e32 v49, v49
	s_nop 0
	v_pk_add_f32 v[48:49], v[48:49], 1.0 op_sel_hi:[1,0]
	s_nop 0
	v_rcp_f32_e32 v51, v49
	s_nop 0
	s_nop 0
	v_fma_f32 v53, -v49, v51, 1.0
	v_fma_f32 v51, v53, v51, v51
	v_mul_f32_e32 v49, v50, v51
	v_rcp_f32_e32 v50, v48
	s_nop 0
	s_nop 0
	v_fma_f32 v52, -v48, v50, 1.0
	v_fma_f32 v50, v52, v50, v50
	v_mul_f32_e32 v48, v46, v50
	v_pk_mul_f32 v[42:43], v[48:49], v[42:43]
	v_and_b32_e32 v48, 0xffff0000, v47
	v_lshlrev_b32_e32 v49, 16, v47
	v_and_b32_sdwa v47, v45, v195 dst_sel:DWORD dst_unused:UNUSED_PAD src0_sel:WORD_1 src1_sel:DWORD
	v_mul_f32_e32 v46, 0xbfb8aa3b, v49
	v_add3_u32 v45, v45, v47, s33
	v_mul_f32_e32 v47, 0xbfb8aa3b, v48
	v_exp_f32_e32 v46, v46
	v_exp_f32_e32 v47, v47
	v_and_b32_sdwa v50, v44, v195 dst_sel:DWORD dst_unused:UNUSED_PAD src0_sel:WORD_1 src1_sel:DWORD
	v_add3_u32 v44, v44, v50, s33
	v_and_b32_e32 v45, 0xffff0000, v45
	v_pk_add_f32 v[46:47], v[46:47], 1.0 op_sel_hi:[1,0]
	v_and_b32_e32 v44, 0xffff0000, v44
	v_rcp_f32_e32 v50, v47
	s_nop 0
	s_nop 0
	v_fma_f32 v52, -v47, v50, 1.0
	v_fma_f32 v50, v52, v50, v50
	v_mul_f32_e32 v47, v48, v50
	v_rcp_f32_e32 v48, v46
	s_nop 0
	s_nop 0
	v_fma_f32 v51, -v46, v48, 1.0
	v_fma_f32 v48, v51, v48, v48
	v_mul_f32_e32 v46, v49, v48
	v_pk_mul_f32 v[44:45], v[46:47], v[44:45]
	v_bfe_u32 v48, v43, 16, 1
	v_bfe_u32 v46, v45, 16, 1
	v_bfe_u32 v47, v44, 16, 1
	v_bfe_u32 v49, v42, 16, 1
	v_add3_u32 v44, v44, v47, s33
	v_add3_u32 v45, v45, v46, s33
	v_add3_u32 v42, v42, v49, s33
	v_add3_u32 v46, v43, v48, s33
	v_perm_b32 v43, v45, v44, s27
	v_perm_b32 v42, v46, v42, s27
	global_store_dwordx2 v[62:63], v[42:43], off offset:160
	global_load_dwordx2 v[42:43], v[70:71], off offset:192
	v_and_b32_sdwa v45, v39, v195 dst_sel:DWORD dst_unused:UNUSED_PAD src0_sel:WORD_1 src1_sel:DWORD
	v_add3_u32 v39, v39, v45, s33
	v_and_b32_sdwa v47, v38, v195 dst_sel:DWORD dst_unused:UNUSED_PAD src0_sel:WORD_1 src1_sel:DWORD
	v_add3_u32 v38, v38, v47, s33
	v_and_b32_e32 v39, 0xffff0000, v39
	v_and_b32_e32 v38, 0xffff0000, v38
	s_waitcnt vmcnt(0)
; DEVI float bf2f(u16 h) { return __uint_as_float(((unsigned)h) << 16); }
; DEVI float bfs(short h) { return __uint_as_float(((unsigned)(u16)h) << 16); }
; DEVI float silu_f(float x) { return x / (1.f + __expf(-x)); }
; #define SHX(v, m) __int_as_float(__builtin_amdgcn_ds_bpermute(((LANE ^ (m)) << 2), __float_as_int(v)))
; template <int DQK, int QT, bool NA> ...
;     ...
;     float lt = lrun[qt];
;     lt += SHX(lt, 16);
;     lt += SHX(lt, 32);
;     float il = 1.f / lt;
;     int r = qrow0 + wid * 16 * QT + qt * 16 + l15;
; #pragma unroll
;     for (int dt = 0; dt < 8; ++dt) {
;       int dv = dt * 16 + quad * 4;
;       bf16x4 g = *(const bf16x4*)(proj + (size_t)r * NP + gatecol + h * 128 + dv);
;       bf16x4 ov;
; #pragma unroll
;       for (int j = 0; j < 4; ++j) {
;         float y = bf2f(f2bf(o[dt][qt][j] * il));
;         ov[j] = (short)f2bf(y * silu_f(bfs(g[j])));
;       }
;       *(bf16x4*)(ys + (size_t)r * 2048 + ycol + h * 128 + dv) = ov;
	v_and_b32_e32 v46, 0xffff0000, v42
	v_lshlrev_b32_e32 v42, 16, v42
	v_mul_f32_e32 v44, 0xbfb8aa3b, v42
	v_mul_f32_e32 v45, 0xbfb8aa3b, v46
	v_exp_f32_e32 v44, v44
	v_exp_f32_e32 v45, v45
	s_nop 0
	v_pk_add_f32 v[44:45], v[44:45], 1.0 op_sel_hi:[1,0]
	s_nop 0
	v_rcp_f32_e32 v47, v45
	s_nop 0
	s_nop 0
	v_fma_f32 v49, -v45, v47, 1.0
	v_fma_f32 v47, v49, v47, v47
	v_mul_f32_e32 v45, v46, v47
	v_rcp_f32_e32 v46, v44
	s_nop 0
	s_nop 0
	v_fma_f32 v48, -v44, v46, 1.0
	v_fma_f32 v46, v48, v46, v46
	v_mul_f32_e32 v44, v42, v46
	v_pk_mul_f32 v[38:39], v[44:45], v[38:39]
	v_and_b32_e32 v44, 0xffff0000, v43
	v_lshlrev_b32_e32 v45, 16, v43
	v_and_b32_sdwa v43, v41, v195 dst_sel:DWORD dst_unused:UNUSED_PAD src0_sel:WORD_1 src1_sel:DWORD
	v_mul_f32_e32 v42, 0xbfb8aa3b, v45
	v_add3_u32 v41, v41, v43, s33
	v_mul_f32_e32 v43, 0xbfb8aa3b, v44
	v_exp_f32_e32 v42, v42
	v_exp_f32_e32 v43, v43
	v_and_b32_sdwa v46, v40, v195 dst_sel:DWORD dst_unused:UNUSED_PAD src0_sel:WORD_1 src1_sel:DWORD
	v_add3_u32 v40, v40, v46, s33
	v_and_b32_e32 v41, 0xffff0000, v41
	v_pk_add_f32 v[42:43], v[42:43], 1.0 op_sel_hi:[1,0]
	v_and_b32_e32 v40, 0xffff0000, v40
	v_rcp_f32_e32 v46, v43
	s_nop 0
	s_nop 0
	v_fma_f32 v48, -v43, v46, 1.0
	v_fma_f32 v46, v48, v46, v46
	v_mul_f32_e32 v43, v44, v46
	v_rcp_f32_e32 v44, v42
	s_nop 0
	s_nop 0
	v_fma_f32 v47, -v42, v44, 1.0
	v_fma_f32 v44, v47, v44, v44
	v_mul_f32_e32 v42, v45, v44
	v_pk_mul_f32 v[40:41], v[42:43], v[40:41]
	v_bfe_u32 v44, v39, 16, 1
	v_bfe_u32 v42, v41, 16, 1
	v_bfe_u32 v43, v40, 16, 1
	v_bfe_u32 v45, v38, 16, 1
	v_add3_u32 v40, v40, v43, s33
	v_add3_u32 v41, v41, v42, s33
	v_add3_u32 v38, v38, v45, s33
	v_add3_u32 v42, v39, v44, s33
	v_perm_b32 v39, v41, v40, s27
	v_perm_b32 v38, v42, v38, s27
	global_store_dwordx2 v[62:63], v[38:39], off offset:192
	global_load_dwordx2 v[38:39], v[70:71], off offset:224
	v_and_b32_sdwa v41, v35, v195 dst_sel:DWORD dst_unused:UNUSED_PAD src0_sel:WORD_1 src1_sel:DWORD
	v_add3_u32 v35, v35, v41, s33
	v_and_b32_sdwa v43, v34, v195 dst_sel:DWORD dst_unused:UNUSED_PAD src0_sel:WORD_1 src1_sel:DWORD
	v_add3_u32 v34, v34, v43, s33
	v_and_b32_e32 v35, 0xffff0000, v35
	v_and_b32_e32 v34, 0xffff0000, v34
	s_waitcnt vmcnt(0)
	v_and_b32_e32 v42, 0xffff0000, v38
	v_lshlrev_b32_e32 v38, 16, v38
	v_mul_f32_e32 v40, 0xbfb8aa3b, v38
	v_mul_f32_e32 v41, 0xbfb8aa3b, v42
	v_exp_f32_e32 v40, v40
	v_exp_f32_e32 v41, v41
	s_nop 0
	v_pk_add_f32 v[40:41], v[40:41], 1.0 op_sel_hi:[1,0]
	s_nop 0
	v_rcp_f32_e32 v43, v41
	s_nop 0
	s_nop 0
	v_fma_f32 v45, -v41, v43, 1.0
	v_fma_f32 v43, v45, v43, v43
	v_mul_f32_e32 v41, v42, v43
	v_rcp_f32_e32 v42, v40
	s_nop 0
	s_nop 0
	v_fma_f32 v44, -v40, v42, 1.0
	v_fma_f32 v42, v44, v42, v42
	v_mul_f32_e32 v40, v38, v42
	v_pk_mul_f32 v[34:35], v[40:41], v[34:35]
	v_and_b32_e32 v40, 0xffff0000, v39
	v_lshlrev_b32_e32 v41, 16, v39
	v_and_b32_sdwa v39, v37, v195 dst_sel:DWORD dst_unused:UNUSED_PAD src0_sel:WORD_1 src1_sel:DWORD
	v_mul_f32_e32 v38, 0xbfb8aa3b, v41
	v_add3_u32 v37, v37, v39, s33
	v_mul_f32_e32 v39, 0xbfb8aa3b, v40
	v_exp_f32_e32 v38, v38
	v_exp_f32_e32 v39, v39
	v_and_b32_sdwa v42, v36, v195 dst_sel:DWORD dst_unused:UNUSED_PAD src0_sel:WORD_1 src1_sel:DWORD
	v_add3_u32 v36, v36, v42, s33
	v_and_b32_e32 v37, 0xffff0000, v37
	v_pk_add_f32 v[38:39], v[38:39], 1.0 op_sel_hi:[1,0]
	v_and_b32_e32 v36, 0xffff0000, v36
	v_rcp_f32_e32 v42, v39
	s_nop 0
	s_nop 0
	v_fma_f32 v44, -v39, v42, 1.0
	v_fma_f32 v42, v44, v42, v42
	v_mul_f32_e32 v39, v40, v42
	v_rcp_f32_e32 v40, v38
	s_nop 0
	s_nop 0
	v_fma_f32 v43, -v38, v40, 1.0
	v_fma_f32 v40, v43, v40, v40
	v_mul_f32_e32 v38, v41, v40
	v_pk_mul_f32 v[36:37], v[38:39], v[36:37]
	v_bfe_u32 v40, v35, 16, 1
	v_bfe_u32 v38, v37, 16, 1
	v_bfe_u32 v39, v36, 16, 1
	v_bfe_u32 v41, v34, 16, 1
	v_add3_u32 v36, v36, v39, s33
	v_add3_u32 v37, v37, v38, s33
	v_add3_u32 v34, v34, v41, s33
	v_add3_u32 v38, v35, v40, s33
	v_perm_b32 v35, v37, v36, s27
	v_perm_b32 v34, v38, v34, s27
	global_store_dwordx2 v[62:63], v[34:35], off offset:224
	ds_bpermute_b32 v34, v153, v128
	s_waitcnt lgkmcnt(0)
	v_add_f32_e32 v34, v128, v34
	ds_bpermute_b32 v35, v155, v34
	s_waitcnt lgkmcnt(0)
	v_add_f32_e32 v34, v34, v35
	v_rcp_f32_e32 v35, v34
	s_nop 0
	s_nop 0
	v_fma_f32 v37, -v34, v35, 1.0
	v_fma_f32 v35, v37, v35, v35
	v_mad_i64_i32 v[36:37], s[0:1], v152, s3, v[66:67]
	v_lshl_add_u64 v[40:41], v[36:37], 0, s[20:21]
	v_mad_i64_i32 v[36:37], s[0:1], v152, s4, v[36:37]
	v_lshl_add_u64 v[40:41], v[40:41], 0, v[0:1]
	v_lshl_add_u64 v[38:39], v[36:37], 0, s[20:21]
	v_lshl_add_u64 v[36:37], v[40:41], 0, s[14:15]
	v_add_co_u32_e32 v40, vcc, s2, v40
	v_mov_b32_e32 v34, v35
	s_nop 0
	v_addc_co_u32_e32 v41, vcc, 0, v41, vcc
	global_load_dwordx2 v[40:41], v[40:41], off offset:128
	v_pk_mul_f32 v[30:31], v[30:31], v[34:35] op_sel_hi:[1,0]
	v_lshl_add_u64 v[38:39], v[38:39], 0, v[0:1]
	v_and_b32_sdwa v43, v31, v195 dst_sel:DWORD dst_unused:UNUSED_PAD src0_sel:WORD_1 src1_sel:DWORD
	v_add3_u32 v31, v31, v43, s33
	v_and_b32_sdwa v44, v30, v195 dst_sel:DWORD dst_unused:UNUSED_PAD src0_sel:WORD_1 src1_sel:DWORD
	v_add3_u32 v30, v30, v44, s33
	v_and_b32_e32 v31, 0xffff0000, v31
	v_and_b32_e32 v30, 0xffff0000, v30
	s_waitcnt vmcnt(0)
; DEVI float bf2f(u16 h) { return __uint_as_float(((unsigned)h) << 16); }
; DEVI float bfs(short h) { return __uint_as_float(((unsigned)(u16)h) << 16); }
; DEVI float silu_f(float x) { return x / (1.f + __expf(-x)); }
; template <int DQK, int QT, bool NA> ...
;     ...
;     for (int dt = 0; dt < 8; ++dt) {
;       int dv = dt * 16 + quad * 4;
;       bf16x4 g = *(const bf16x4*)(proj + (size_t)r * NP + gatecol + h * 128 + dv);
;       bf16x4 ov;
; #pragma unroll
;       for (int j = 0; j < 4; ++j) {
;         float y = bf2f(f2bf(o[dt][qt][j] * il));
;         ov[j] = (short)f2bf(y * silu_f(bfs(g[j])));
;       }
;       *(bf16x4*)(ys + (size_t)r * 2048 + ycol + h * 128 + dv) = ov;
	v_and_b32_e32 v35, 0xffff0000, v40
	v_lshlrev_b32_e32 v40, 16, v40
	v_mul_f32_e32 v42, 0xbfb8aa3b, v40
	v_mul_f32_e32 v43, 0xbfb8aa3b, v35
	v_exp_f32_e32 v42, v42
	v_exp_f32_e32 v43, v43
	s_nop 0
	v_pk_add_f32 v[42:43], v[42:43], 1.0 op_sel_hi:[1,0]
	s_nop 0
	v_rcp_f32_e32 v44, v43
	s_nop 0
	s_nop 0
	v_fma_f32 v46, -v43, v44, 1.0
	v_fma_f32 v44, v46, v44, v44
	v_mul_f32_e32 v43, v35, v44
	v_rcp_f32_e32 v35, v42
	s_nop 0
	s_nop 0
	v_fma_f32 v45, -v42, v35, 1.0
	v_fma_f32 v35, v45, v35, v35
	v_mul_f32_e32 v42, v40, v35
	v_pk_mul_f32 v[32:33], v[32:33], v[34:35] op_sel_hi:[1,0]
	v_pk_mul_f32 v[30:31], v[42:43], v[30:31]
	v_and_b32_e32 v35, 0xffff0000, v41
	v_lshlrev_b32_e32 v42, 16, v41
	v_and_b32_sdwa v41, v33, v195 dst_sel:DWORD dst_unused:UNUSED_PAD src0_sel:WORD_1 src1_sel:DWORD
	v_mul_f32_e32 v40, 0xbfb8aa3b, v42
	v_add3_u32 v33, v33, v41, s33
	v_mul_f32_e32 v41, 0xbfb8aa3b, v35
	v_exp_f32_e32 v40, v40
	v_exp_f32_e32 v41, v41
	v_and_b32_sdwa v43, v32, v195 dst_sel:DWORD dst_unused:UNUSED_PAD src0_sel:WORD_1 src1_sel:DWORD
	v_add3_u32 v32, v32, v43, s33
	v_and_b32_e32 v33, 0xffff0000, v33
	v_pk_add_f32 v[40:41], v[40:41], 1.0 op_sel_hi:[1,0]
	v_and_b32_e32 v32, 0xffff0000, v32
	v_rcp_f32_e32 v43, v41
	s_nop 0
	s_nop 0
	v_fma_f32 v45, -v41, v43, 1.0
	v_fma_f32 v43, v45, v43, v43
	v_mul_f32_e32 v41, v35, v43
	v_rcp_f32_e32 v35, v40
	s_nop 0
	s_nop 0
	v_fma_f32 v44, -v40, v35, 1.0
	v_fma_f32 v35, v44, v35, v35
	v_mul_f32_e32 v40, v42, v35
	v_pk_mul_f32 v[32:33], v[40:41], v[32:33]
	v_bfe_u32 v41, v31, 16, 1
	v_bfe_u32 v35, v33, 16, 1
	v_bfe_u32 v40, v32, 16, 1
	v_bfe_u32 v42, v30, 16, 1
	v_add3_u32 v32, v32, v40, s33
	v_add3_u32 v33, v33, v35, s33
	v_add3_u32 v30, v30, v42, s33
	v_add3_u32 v31, v31, v41, s33
	v_perm_b32 v33, v33, v32, s27
	v_perm_b32 v32, v31, v30, s27
	v_lshl_add_u64 v[30:31], v[38:39], 0, s[16:17]
	v_add_co_u32_e32 v38, vcc, s5, v38
	v_pk_mul_f32 v[26:27], v[26:27], v[34:35] op_sel_hi:[1,0]
	s_nop 0
	v_addc_co_u32_e32 v39, vcc, 0, v39, vcc
	global_store_dwordx2 v[38:39], v[32:33], off offset:2048
	global_load_dwordx2 v[32:33], v[36:37], off offset:32
	v_and_b32_sdwa v39, v26, v195 dst_sel:DWORD dst_unused:UNUSED_PAD src0_sel:WORD_1 src1_sel:DWORD
	v_add3_u32 v26, v26, v39, s33
	v_and_b32_e32 v26, 0xffff0000, v26
	s_waitcnt vmcnt(0)
	v_and_b32_e32 v0, 0xffff0000, v32
	v_lshlrev_b32_e32 v32, 16, v32
	v_mul_f32_e32 v35, 0xbfb8aa3b, v32
	v_exp_f32_e32 v38, v35
	v_and_b32_sdwa v35, v27, v195 dst_sel:DWORD dst_unused:UNUSED_PAD src0_sel:WORD_1 src1_sel:DWORD
	v_add3_u32 v27, v27, v35, s33
	v_mul_f32_e32 v35, 0xbfb8aa3b, v0
	v_exp_f32_e32 v39, v35
	v_and_b32_e32 v27, 0xffff0000, v27
	v_pk_add_f32 v[38:39], v[38:39], 1.0 op_sel_hi:[1,0]
	s_nop 0
	v_rcp_f32_e32 v35, v39
	s_nop 0
	s_nop 0
	v_fma_f32 v41, -v39, v35, 1.0
	v_fma_f32 v35, v41, v35, v35
	v_mul_f32_e32 v39, v0, v35
	v_rcp_f32_e32 v0, v38
	s_nop 0
	s_nop 0
	v_fma_f32 v40, -v38, v0, 1.0
	v_fma_f32 v0, v40, v0, v0
	v_pk_mul_f32 v[28:29], v[28:29], v[34:35] op_sel_hi:[1,0]
	v_mul_f32_e32 v38, v32, v0
	v_and_b32_e32 v0, 0xffff0000, v33
	v_lshlrev_b32_e32 v35, 16, v33
	v_and_b32_sdwa v33, v29, v195 dst_sel:DWORD dst_unused:UNUSED_PAD src0_sel:WORD_1 src1_sel:DWORD
	v_mul_f32_e32 v32, 0xbfb8aa3b, v35
	v_add3_u32 v29, v29, v33, s33
	v_mul_f32_e32 v33, 0xbfb8aa3b, v0
	v_exp_f32_e32 v32, v32
	v_exp_f32_e32 v33, v33
	v_pk_mul_f32 v[26:27], v[38:39], v[26:27]
	v_and_b32_sdwa v38, v28, v195 dst_sel:DWORD dst_unused:UNUSED_PAD src0_sel:WORD_1 src1_sel:DWORD
	v_add3_u32 v28, v28, v38, s33
	v_pk_add_f32 v[32:33], v[32:33], 1.0 op_sel_hi:[1,0]
	v_and_b32_e32 v29, 0xffff0000, v29
	v_rcp_f32_e32 v38, v33
	s_nop 0
	v_and_b32_e32 v28, 0xffff0000, v28
	v_fma_f32 v40, -v33, v38, 1.0
	v_fma_f32 v38, v40, v38, v38
	v_mul_f32_e32 v33, v0, v38
	v_rcp_f32_e32 v0, v32
	s_nop 0
	s_nop 0
	v_fma_f32 v39, -v32, v0, 1.0
	v_fma_f32 v0, v39, v0, v0
	v_mul_f32_e32 v32, v35, v0
	v_pk_mul_f32 v[28:29], v[32:33], v[28:29]
	v_bfe_u32 v33, v27, 16, 1
	v_bfe_u32 v0, v29, 16, 1
	v_bfe_u32 v32, v28, 16, 1
	v_bfe_u32 v35, v26, 16, 1
	v_add3_u32 v28, v28, v32, s33
	v_add3_u32 v0, v29, v0, s33
	v_add3_u32 v26, v26, v35, s33
	v_add3_u32 v29, v27, v33, s33
	v_perm_b32 v27, v0, v28, s27
	v_perm_b32 v26, v29, v26, s27
	global_store_dwordx2 v[30:31], v[26:27], off offset:32
	global_load_dwordx2 v[26:27], v[36:37], off offset:64
	v_pk_mul_f32 v[22:23], v[22:23], v[34:35] op_sel_hi:[1,0]
	s_waitcnt vmcnt(0)
; DEVI float bf2f(u16 h) { return __uint_as_float(((unsigned)h) << 16); }
; DEVI float bfs(short h) { return __uint_as_float(((unsigned)(u16)h) << 16); }
; DEVI float silu_f(float x) { return x / (1.f + __expf(-x)); }
; template <int DQK, int QT, bool NA> ...
;     ...
;     for (int dt = 0; dt < 8; ++dt) {
;       int dv = dt * 16 + quad * 4;
;       bf16x4 g = *(const bf16x4*)(proj + (size_t)r * NP + gatecol + h * 128 + dv);
;       bf16x4 ov;
; #pragma unroll
;       for (int j = 0; j < 4; ++j) {
;         float y = bf2f(f2bf(o[dt][qt][j] * il));
;         ov[j] = (short)f2bf(y * silu_f(bfs(g[j])));
;       }
;       *(bf16x4*)(ys + (size_t)r * 2048 + ycol + h * 128 + dv) = ov;
	v_and_b32_e32 v0, 0xffff0000, v26
	v_lshlrev_b32_e32 v26, 16, v26
	v_and_b32_sdwa v29, v23, v195 dst_sel:DWORD dst_unused:UNUSED_PAD src0_sel:WORD_1 src1_sel:DWORD
	v_mul_f32_e32 v28, 0xbfb8aa3b, v26
	v_add3_u32 v23, v23, v29, s33
	v_mul_f32_e32 v29, 0xbfb8aa3b, v0
	v_exp_f32_e32 v28, v28
	v_exp_f32_e32 v29, v29
	v_and_b32_sdwa v32, v22, v195 dst_sel:DWORD dst_unused:UNUSED_PAD src0_sel:WORD_1 src1_sel:DWORD
	v_add3_u32 v22, v22, v32, s33
	v_and_b32_e32 v23, 0xffff0000, v23
	v_pk_add_f32 v[28:29], v[28:29], 1.0 op_sel_hi:[1,0]
	v_and_b32_e32 v22, 0xffff0000, v22
	v_rcp_f32_e32 v32, v29
	s_nop 0
	s_nop 0
	v_fma_f32 v35, -v29, v32, 1.0
	v_fma_f32 v32, v35, v32, v32
	v_mul_f32_e32 v29, v0, v32
	v_rcp_f32_e32 v0, v28
	s_nop 0
	s_nop 0
	v_fma_f32 v33, -v28, v0, 1.0
	v_fma_f32 v0, v33, v0, v0
	v_mul_f32_e32 v28, v26, v0
	v_pk_mul_f32 v[24:25], v[24:25], v[34:35] op_sel_hi:[1,0]
	v_pk_mul_f32 v[22:23], v[28:29], v[22:23]
	v_and_b32_e32 v0, 0xffff0000, v27
	v_lshlrev_b32_e32 v28, 16, v27
	v_and_b32_sdwa v27, v25, v195 dst_sel:DWORD dst_unused:UNUSED_PAD src0_sel:WORD_1 src1_sel:DWORD
	v_mul_f32_e32 v26, 0xbfb8aa3b, v28
	v_add3_u32 v25, v25, v27, s33
	v_mul_f32_e32 v27, 0xbfb8aa3b, v0
	v_exp_f32_e32 v26, v26
	v_exp_f32_e32 v27, v27
	v_and_b32_sdwa v29, v24, v195 dst_sel:DWORD dst_unused:UNUSED_PAD src0_sel:WORD_1 src1_sel:DWORD
	v_add3_u32 v24, v24, v29, s33
	v_and_b32_e32 v25, 0xffff0000, v25
	v_pk_add_f32 v[26:27], v[26:27], 1.0 op_sel_hi:[1,0]
	v_and_b32_e32 v24, 0xffff0000, v24
	v_rcp_f32_e32 v29, v27
	s_nop 0
	s_nop 0
	v_fma_f32 v33, -v27, v29, 1.0
	v_fma_f32 v29, v33, v29, v29
	v_mul_f32_e32 v27, v0, v29
	v_rcp_f32_e32 v0, v26
	s_nop 0
	s_nop 0
	v_fma_f32 v32, -v26, v0, 1.0
	v_fma_f32 v0, v32, v0, v0
	v_mul_f32_e32 v26, v28, v0
	v_pk_mul_f32 v[24:25], v[26:27], v[24:25]
	v_bfe_u32 v27, v23, 16, 1
	v_bfe_u32 v0, v25, 16, 1
	v_bfe_u32 v26, v24, 16, 1
	v_bfe_u32 v28, v22, 16, 1
	v_add3_u32 v24, v24, v26, s33
	v_add3_u32 v0, v25, v0, s33
	v_add3_u32 v22, v22, v28, s33
	v_add3_u32 v25, v23, v27, s33
	v_perm_b32 v23, v0, v24, s27
	v_perm_b32 v22, v25, v22, s27
	global_store_dwordx2 v[30:31], v[22:23], off offset:64
	global_load_dwordx2 v[22:23], v[36:37], off offset:96
	v_pk_mul_f32 v[18:19], v[18:19], v[34:35] op_sel_hi:[1,0]
	v_pk_mul_f32 v[20:21], v[20:21], v[34:35] op_sel_hi:[1,0]
	v_and_b32_sdwa v25, v19, v195 dst_sel:DWORD dst_unused:UNUSED_PAD src0_sel:WORD_1 src1_sel:DWORD
	v_add3_u32 v19, v19, v25, s33
	v_and_b32_sdwa v26, v18, v195 dst_sel:DWORD dst_unused:UNUSED_PAD src0_sel:WORD_1 src1_sel:DWORD
	v_add3_u32 v18, v18, v26, s33
	v_and_b32_e32 v19, 0xffff0000, v19
	v_and_b32_e32 v18, 0xffff0000, v18
	v_pk_mul_f32 v[14:15], v[14:15], v[34:35] op_sel_hi:[1,0]
	v_pk_mul_f32 v[16:17], v[16:17], v[34:35] op_sel_hi:[1,0]
	v_pk_mul_f32 v[10:11], v[10:11], v[34:35] op_sel_hi:[1,0]
	v_pk_mul_f32 v[12:13], v[12:13], v[34:35] op_sel_hi:[1,0]
	v_pk_mul_f32 v[6:7], v[6:7], v[34:35] op_sel_hi:[1,0]
	v_pk_mul_f32 v[8:9], v[8:9], v[34:35] op_sel_hi:[1,0]
	v_pk_mul_f32 v[2:3], v[2:3], v[34:35] op_sel_hi:[1,0]
	v_pk_mul_f32 v[4:5], v[4:5], v[34:35] op_sel_hi:[1,0]
	s_waitcnt vmcnt(0)
	v_and_b32_e32 v0, 0xffff0000, v22
	v_lshlrev_b32_e32 v22, 16, v22
	v_mul_f32_e32 v24, 0xbfb8aa3b, v22
	v_mul_f32_e32 v25, 0xbfb8aa3b, v0
	v_exp_f32_e32 v24, v24
	v_exp_f32_e32 v25, v25
	s_nop 0
	v_pk_add_f32 v[24:25], v[24:25], 1.0 op_sel_hi:[1,0]
	s_nop 0
	v_rcp_f32_e32 v26, v25
	s_nop 0
	s_nop 0
	v_fma_f32 v28, -v25, v26, 1.0
	v_fma_f32 v26, v28, v26, v26
	v_mul_f32_e32 v25, v0, v26
	v_rcp_f32_e32 v0, v24
	s_nop 0
	s_nop 0
	v_fma_f32 v27, -v24, v0, 1.0
	v_fma_f32 v0, v27, v0, v0
	v_mul_f32_e32 v24, v22, v0
	v_pk_mul_f32 v[18:19], v[24:25], v[18:19]
	v_and_b32_e32 v0, 0xffff0000, v23
	v_lshlrev_b32_e32 v24, 16, v23
	v_and_b32_sdwa v23, v21, v195 dst_sel:DWORD dst_unused:UNUSED_PAD src0_sel:WORD_1 src1_sel:DWORD
	v_mul_f32_e32 v22, 0xbfb8aa3b, v24
	v_add3_u32 v21, v21, v23, s33
	v_mul_f32_e32 v23, 0xbfb8aa3b, v0
	v_exp_f32_e32 v22, v22
	v_exp_f32_e32 v23, v23
	v_and_b32_sdwa v25, v20, v195 dst_sel:DWORD dst_unused:UNUSED_PAD src0_sel:WORD_1 src1_sel:DWORD
	v_add3_u32 v20, v20, v25, s33
	v_and_b32_e32 v21, 0xffff0000, v21
	v_pk_add_f32 v[22:23], v[22:23], 1.0 op_sel_hi:[1,0]
	v_and_b32_e32 v20, 0xffff0000, v20
	v_rcp_f32_e32 v25, v23
	s_nop 0
	s_nop 0
	v_fma_f32 v27, -v23, v25, 1.0
	v_fma_f32 v25, v27, v25, v25
	v_mul_f32_e32 v23, v0, v25
	v_rcp_f32_e32 v0, v22
	s_nop 0
	s_nop 0
	v_fma_f32 v26, -v22, v0, 1.0
	v_fma_f32 v0, v26, v0, v0
	v_mul_f32_e32 v22, v24, v0
	v_pk_mul_f32 v[20:21], v[22:23], v[20:21]
	v_bfe_u32 v23, v19, 16, 1
	v_bfe_u32 v0, v21, 16, 1
	v_bfe_u32 v22, v20, 16, 1
	v_bfe_u32 v24, v18, 16, 1
	v_add3_u32 v20, v20, v22, s33
	v_add3_u32 v0, v21, v0, s33
	v_add3_u32 v18, v18, v24, s33
	v_add3_u32 v21, v19, v23, s33
	v_perm_b32 v19, v0, v20, s27
	v_perm_b32 v18, v21, v18, s27
	global_store_dwordx2 v[30:31], v[18:19], off offset:96
	global_load_dwordx2 v[18:19], v[36:37], off offset:128
	v_and_b32_sdwa v21, v15, v195 dst_sel:DWORD dst_unused:UNUSED_PAD src0_sel:WORD_1 src1_sel:DWORD
	v_add3_u32 v15, v15, v21, s33
	v_and_b32_sdwa v22, v14, v195 dst_sel:DWORD dst_unused:UNUSED_PAD src0_sel:WORD_1 src1_sel:DWORD
	v_add3_u32 v14, v14, v22, s33
	v_and_b32_e32 v15, 0xffff0000, v15
	v_and_b32_e32 v14, 0xffff0000, v14
	s_waitcnt vmcnt(0)
; DEVI float bf2f(u16 h) { return __uint_as_float(((unsigned)h) << 16); }
; DEVI float bfs(short h) { return __uint_as_float(((unsigned)(u16)h) << 16); }
; DEVI float silu_f(float x) { return x / (1.f + __expf(-x)); }
; template <int DQK, int QT, bool NA> ...
;     ...
;     for (int dt = 0; dt < 8; ++dt) {
;       int dv = dt * 16 + quad * 4;
;       bf16x4 g = *(const bf16x4*)(proj + (size_t)r * NP + gatecol + h * 128 + dv);
;       bf16x4 ov;
; #pragma unroll
;       for (int j = 0; j < 4; ++j) {
;         float y = bf2f(f2bf(o[dt][qt][j] * il));
;         ov[j] = (short)f2bf(y * silu_f(bfs(g[j])));
;       }
;       *(bf16x4*)(ys + (size_t)r * 2048 + ycol + h * 128 + dv) = ov;
	v_and_b32_e32 v0, 0xffff0000, v18
	v_lshlrev_b32_e32 v18, 16, v18
	v_mul_f32_e32 v20, 0xbfb8aa3b, v18
	v_mul_f32_e32 v21, 0xbfb8aa3b, v0
	v_exp_f32_e32 v20, v20
	v_exp_f32_e32 v21, v21
	s_nop 0
	v_pk_add_f32 v[20:21], v[20:21], 1.0 op_sel_hi:[1,0]
	s_nop 0
	v_rcp_f32_e32 v22, v21
	s_nop 0
	s_nop 0
	v_fma_f32 v24, -v21, v22, 1.0
	v_fma_f32 v22, v24, v22, v22
	v_mul_f32_e32 v21, v0, v22
	v_rcp_f32_e32 v0, v20
	s_nop 0
	s_nop 0
	v_fma_f32 v23, -v20, v0, 1.0
	v_fma_f32 v0, v23, v0, v0
	v_mul_f32_e32 v20, v18, v0
	v_pk_mul_f32 v[14:15], v[20:21], v[14:15]
	v_and_b32_e32 v0, 0xffff0000, v19
	v_lshlrev_b32_e32 v20, 16, v19
	v_and_b32_sdwa v19, v17, v195 dst_sel:DWORD dst_unused:UNUSED_PAD src0_sel:WORD_1 src1_sel:DWORD
	v_mul_f32_e32 v18, 0xbfb8aa3b, v20
	v_add3_u32 v17, v17, v19, s33
	v_mul_f32_e32 v19, 0xbfb8aa3b, v0
	v_exp_f32_e32 v18, v18
	v_exp_f32_e32 v19, v19
	v_and_b32_sdwa v21, v16, v195 dst_sel:DWORD dst_unused:UNUSED_PAD src0_sel:WORD_1 src1_sel:DWORD
	v_add3_u32 v16, v16, v21, s33
	v_and_b32_e32 v17, 0xffff0000, v17
	v_pk_add_f32 v[18:19], v[18:19], 1.0 op_sel_hi:[1,0]
	v_and_b32_e32 v16, 0xffff0000, v16
	v_rcp_f32_e32 v21, v19
	s_nop 0
	s_nop 0
	v_fma_f32 v23, -v19, v21, 1.0
	v_fma_f32 v21, v23, v21, v21
	v_mul_f32_e32 v19, v0, v21
	v_rcp_f32_e32 v0, v18
	s_nop 0
	s_nop 0
	v_fma_f32 v22, -v18, v0, 1.0
	v_fma_f32 v0, v22, v0, v0
	v_mul_f32_e32 v18, v20, v0
	v_pk_mul_f32 v[16:17], v[18:19], v[16:17]
	v_bfe_u32 v19, v15, 16, 1
	v_bfe_u32 v0, v17, 16, 1
	v_bfe_u32 v18, v16, 16, 1
	v_bfe_u32 v20, v14, 16, 1
	v_add3_u32 v16, v16, v18, s33
	v_add3_u32 v0, v17, v0, s33
	v_add3_u32 v14, v14, v20, s33
	v_add3_u32 v17, v15, v19, s33
	v_perm_b32 v15, v0, v16, s27
	v_perm_b32 v14, v17, v14, s27
	global_store_dwordx2 v[30:31], v[14:15], off offset:128
	global_load_dwordx2 v[14:15], v[36:37], off offset:160
	v_and_b32_sdwa v17, v11, v195 dst_sel:DWORD dst_unused:UNUSED_PAD src0_sel:WORD_1 src1_sel:DWORD
	v_add3_u32 v11, v11, v17, s33
	v_and_b32_sdwa v18, v10, v195 dst_sel:DWORD dst_unused:UNUSED_PAD src0_sel:WORD_1 src1_sel:DWORD
	v_add3_u32 v10, v10, v18, s33
	v_and_b32_e32 v11, 0xffff0000, v11
	v_and_b32_e32 v10, 0xffff0000, v10
	s_waitcnt vmcnt(0)
	v_and_b32_e32 v0, 0xffff0000, v14
	v_lshlrev_b32_e32 v14, 16, v14
	v_mul_f32_e32 v16, 0xbfb8aa3b, v14
	v_mul_f32_e32 v17, 0xbfb8aa3b, v0
	v_exp_f32_e32 v16, v16
	v_exp_f32_e32 v17, v17
	s_nop 0
	v_pk_add_f32 v[16:17], v[16:17], 1.0 op_sel_hi:[1,0]
	s_nop 0
	v_rcp_f32_e32 v18, v17
	s_nop 0
	s_nop 0
	v_fma_f32 v20, -v17, v18, 1.0
	v_fma_f32 v18, v20, v18, v18
	v_mul_f32_e32 v17, v0, v18
	v_rcp_f32_e32 v0, v16
	s_nop 0
	s_nop 0
	v_fma_f32 v19, -v16, v0, 1.0
	v_fma_f32 v0, v19, v0, v0
	v_mul_f32_e32 v16, v14, v0
	v_pk_mul_f32 v[10:11], v[16:17], v[10:11]
	v_and_b32_e32 v0, 0xffff0000, v15
	v_lshlrev_b32_e32 v16, 16, v15
	v_and_b32_sdwa v15, v13, v195 dst_sel:DWORD dst_unused:UNUSED_PAD src0_sel:WORD_1 src1_sel:DWORD
	v_mul_f32_e32 v14, 0xbfb8aa3b, v16
	v_add3_u32 v13, v13, v15, s33
	v_mul_f32_e32 v15, 0xbfb8aa3b, v0
	v_exp_f32_e32 v14, v14
	v_exp_f32_e32 v15, v15
	v_and_b32_sdwa v17, v12, v195 dst_sel:DWORD dst_unused:UNUSED_PAD src0_sel:WORD_1 src1_sel:DWORD
	v_add3_u32 v12, v12, v17, s33
	v_and_b32_e32 v13, 0xffff0000, v13
	v_pk_add_f32 v[14:15], v[14:15], 1.0 op_sel_hi:[1,0]
	v_and_b32_e32 v12, 0xffff0000, v12
	v_rcp_f32_e32 v17, v15
	s_nop 0
	s_nop 0
	v_fma_f32 v19, -v15, v17, 1.0
	v_fma_f32 v17, v19, v17, v17
	v_mul_f32_e32 v15, v0, v17
	v_rcp_f32_e32 v0, v14
	s_nop 0
	s_nop 0
	v_fma_f32 v18, -v14, v0, 1.0
	v_fma_f32 v0, v18, v0, v0
	v_mul_f32_e32 v14, v16, v0
	v_pk_mul_f32 v[12:13], v[14:15], v[12:13]
	v_bfe_u32 v15, v11, 16, 1
	v_bfe_u32 v0, v13, 16, 1
	v_bfe_u32 v14, v12, 16, 1
	v_bfe_u32 v16, v10, 16, 1
	v_add3_u32 v12, v12, v14, s33
	v_add3_u32 v0, v13, v0, s33
	v_add3_u32 v10, v10, v16, s33
	v_add3_u32 v13, v11, v15, s33
	v_perm_b32 v11, v0, v12, s27
	v_perm_b32 v10, v13, v10, s27
	global_store_dwordx2 v[30:31], v[10:11], off offset:160
	global_load_dwordx2 v[10:11], v[36:37], off offset:192
	v_and_b32_sdwa v13, v7, v195 dst_sel:DWORD dst_unused:UNUSED_PAD src0_sel:WORD_1 src1_sel:DWORD
	v_add3_u32 v7, v7, v13, s33
	v_and_b32_sdwa v14, v6, v195 dst_sel:DWORD dst_unused:UNUSED_PAD src0_sel:WORD_1 src1_sel:DWORD
	v_add3_u32 v6, v6, v14, s33
	v_and_b32_e32 v7, 0xffff0000, v7
	v_and_b32_e32 v6, 0xffff0000, v6
	s_waitcnt vmcnt(0)
; DEVI float bf2f(u16 h) { return __uint_as_float(((unsigned)h) << 16); }
; DEVI float bfs(short h) { return __uint_as_float(((unsigned)(u16)h) << 16); }
; DEVI float silu_f(float x) { return x / (1.f + __expf(-x)); }
; template <int DQK, int QT, bool NA> ...
;     ...
;     for (int dt = 0; dt < 8; ++dt) {
;       int dv = dt * 16 + quad * 4;
;       bf16x4 g = *(const bf16x4*)(proj + (size_t)r * NP + gatecol + h * 128 + dv);
;       bf16x4 ov;
; #pragma unroll
;       for (int j = 0; j < 4; ++j) {
;         float y = bf2f(f2bf(o[dt][qt][j] * il));
;         ov[j] = (short)f2bf(y * silu_f(bfs(g[j])));
;       }
;       *(bf16x4*)(ys + (size_t)r * 2048 + ycol + h * 128 + dv) = ov;
	v_and_b32_e32 v0, 0xffff0000, v10
	v_lshlrev_b32_e32 v10, 16, v10
	v_mul_f32_e32 v12, 0xbfb8aa3b, v10
	v_mul_f32_e32 v13, 0xbfb8aa3b, v0
	v_exp_f32_e32 v12, v12
	v_exp_f32_e32 v13, v13
	s_nop 0
	v_pk_add_f32 v[12:13], v[12:13], 1.0 op_sel_hi:[1,0]
	s_nop 0
	v_rcp_f32_e32 v14, v13
	s_nop 0
	s_nop 0
	v_fma_f32 v16, -v13, v14, 1.0
	v_fma_f32 v14, v16, v14, v14
	v_mul_f32_e32 v13, v0, v14
	v_rcp_f32_e32 v0, v12
	s_nop 0
	s_nop 0
	v_fma_f32 v15, -v12, v0, 1.0
	v_fma_f32 v0, v15, v0, v0
	v_mul_f32_e32 v12, v10, v0
	v_pk_mul_f32 v[6:7], v[12:13], v[6:7]
	v_and_b32_e32 v0, 0xffff0000, v11
	v_lshlrev_b32_e32 v12, 16, v11
	v_and_b32_sdwa v11, v9, v195 dst_sel:DWORD dst_unused:UNUSED_PAD src0_sel:WORD_1 src1_sel:DWORD
	v_mul_f32_e32 v10, 0xbfb8aa3b, v12
	v_add3_u32 v9, v9, v11, s33
	v_mul_f32_e32 v11, 0xbfb8aa3b, v0
	v_exp_f32_e32 v10, v10
	v_exp_f32_e32 v11, v11
	v_and_b32_sdwa v13, v8, v195 dst_sel:DWORD dst_unused:UNUSED_PAD src0_sel:WORD_1 src1_sel:DWORD
	v_add3_u32 v8, v8, v13, s33
	v_and_b32_e32 v9, 0xffff0000, v9
	v_pk_add_f32 v[10:11], v[10:11], 1.0 op_sel_hi:[1,0]
	v_and_b32_e32 v8, 0xffff0000, v8
	v_rcp_f32_e32 v13, v11
	s_nop 0
	s_nop 0
	v_fma_f32 v15, -v11, v13, 1.0
	v_fma_f32 v13, v15, v13, v13
	v_mul_f32_e32 v11, v0, v13
	v_rcp_f32_e32 v0, v10
	s_nop 0
	s_nop 0
	v_fma_f32 v14, -v10, v0, 1.0
	v_fma_f32 v0, v14, v0, v0
	v_mul_f32_e32 v10, v12, v0
	v_pk_mul_f32 v[8:9], v[10:11], v[8:9]
	v_bfe_u32 v11, v7, 16, 1
	v_bfe_u32 v0, v9, 16, 1
	v_bfe_u32 v10, v8, 16, 1
	v_bfe_u32 v12, v6, 16, 1
	v_add3_u32 v8, v8, v10, s33
	v_add3_u32 v0, v9, v0, s33
	v_add3_u32 v6, v6, v12, s33
	v_add3_u32 v9, v7, v11, s33
	v_perm_b32 v7, v0, v8, s27
	v_perm_b32 v6, v9, v6, s27
	global_store_dwordx2 v[30:31], v[6:7], off offset:192
	global_load_dwordx2 v[6:7], v[36:37], off offset:224
	v_and_b32_sdwa v9, v3, v195 dst_sel:DWORD dst_unused:UNUSED_PAD src0_sel:WORD_1 src1_sel:DWORD
	v_add3_u32 v3, v3, v9, s33
	v_and_b32_sdwa v10, v2, v195 dst_sel:DWORD dst_unused:UNUSED_PAD src0_sel:WORD_1 src1_sel:DWORD
	v_add3_u32 v2, v2, v10, s33
	v_and_b32_e32 v3, 0xffff0000, v3
	v_and_b32_e32 v2, 0xffff0000, v2
	s_waitcnt vmcnt(0)
	v_and_b32_e32 v0, 0xffff0000, v6
	v_lshlrev_b32_e32 v6, 16, v6
	v_mul_f32_e32 v8, 0xbfb8aa3b, v6
	v_mul_f32_e32 v9, 0xbfb8aa3b, v0
	v_exp_f32_e32 v8, v8
	v_exp_f32_e32 v9, v9
	s_nop 0
	v_pk_add_f32 v[8:9], v[8:9], 1.0 op_sel_hi:[1,0]
	s_nop 0
	v_rcp_f32_e32 v10, v9
	s_nop 0
	s_nop 0
	v_fma_f32 v12, -v9, v10, 1.0
	v_fma_f32 v10, v12, v10, v10
	v_mul_f32_e32 v9, v0, v10
	v_rcp_f32_e32 v0, v8
	s_nop 0
	s_nop 0
	v_fma_f32 v11, -v8, v0, 1.0
	v_fma_f32 v0, v11, v0, v0
	v_mul_f32_e32 v8, v6, v0
	v_pk_mul_f32 v[2:3], v[8:9], v[2:3]
	v_and_b32_e32 v0, 0xffff0000, v7
	v_lshlrev_b32_e32 v8, 16, v7
	v_and_b32_sdwa v7, v5, v195 dst_sel:DWORD dst_unused:UNUSED_PAD src0_sel:WORD_1 src1_sel:DWORD
	v_mul_f32_e32 v6, 0xbfb8aa3b, v8
	v_add3_u32 v5, v5, v7, s33
	v_mul_f32_e32 v7, 0xbfb8aa3b, v0
	v_exp_f32_e32 v6, v6
	v_exp_f32_e32 v7, v7
	v_and_b32_sdwa v9, v4, v195 dst_sel:DWORD dst_unused:UNUSED_PAD src0_sel:WORD_1 src1_sel:DWORD
	v_add3_u32 v4, v4, v9, s33
	v_and_b32_e32 v5, 0xffff0000, v5
	v_pk_add_f32 v[6:7], v[6:7], 1.0 op_sel_hi:[1,0]
	v_and_b32_e32 v4, 0xffff0000, v4
	v_rcp_f32_e32 v9, v7
	s_nop 0
	s_nop 0
	v_fma_f32 v11, -v7, v9, 1.0
	v_fma_f32 v9, v11, v9, v9
	v_mul_f32_e32 v7, v0, v9
	v_rcp_f32_e32 v0, v6
	s_nop 0
	s_nop 0
	v_fma_f32 v10, -v6, v0, 1.0
	v_fma_f32 v0, v10, v0, v0
	v_mul_f32_e32 v6, v8, v0
	v_pk_mul_f32 v[4:5], v[6:7], v[4:5]
	v_bfe_u32 v7, v3, 16, 1
	v_bfe_u32 v0, v5, 16, 1
	v_bfe_u32 v6, v4, 16, 1
	v_bfe_u32 v8, v2, 16, 1
	v_add3_u32 v4, v4, v6, s33
	v_add3_u32 v0, v5, v0, s33
	v_add3_u32 v2, v2, v8, s33
	v_add3_u32 v5, v3, v7, s33
	v_perm_b32 v3, v0, v4, s27
	v_perm_b32 v2, v5, v2, s27
	global_store_dwordx2 v[30:31], v[2:3], off offset:224

; DEVI float bf2f(u16 h) { return __uint_as_float(((unsigned)h) << 16); }
; DEVI float bfs(short h) { return __uint_as_float(((unsigned)(u16)h) << 16); }
; DEVI float silu_f(float x) { return x / (1.f + __expf(-x)); }
; #define SHX(v, m) __int_as_float(__builtin_amdgcn_ds_bpermute(((LANE ^ (m)) << 2), __float_as_int(v)))
; template <int DQK, int QT, bool NA> ...
;     ...
;     float lt = lrun[qt];
;     lt += SHX(lt, 16);
;     lt += SHX(lt, 32);
;     float il = 1.f / lt;
;     int r = qrow0 + wid * 16 * QT + qt * 16 + l15;
; #pragma unroll
;     for (int dt = 0; dt < 8; ++dt) {
;       int dv = dt * 16 + quad * 4;
;       bf16x4 g = *(const bf16x4*)(proj + (size_t)r * NP + gatecol + h * 128 + dv);
;       bf16x4 ov;
; #pragma unroll
;       for (int j = 0; j < 4; ++j) {
;         float y = bf2f(f2bf(o[dt][qt][j] * il));
;         ov[j] = (short)f2bf(y * silu_f(bfs(g[j])));
;       }
;       *(bf16x4*)(ys + (size_t)r * 2048 + ycol + h * 128 + dv) = ov;
.LBB0_776:
	s_lshl_b32 s0, s74, 7
	s_movk_i32 s1, 0x3a00
	v_readlane_b32 s68, v249, 42
	v_mad_i64_i32 v[14:15], s[2:3], v82, s1, 0
	v_readlane_b32 s72, v249, 46
	v_readlane_b32 s73, v249, 47
	s_add_u32 s2, s72, s66
	s_addc_u32 s3, s73, s67
	ds_bpermute_b32 v0, v107, v132
	v_lshl_add_u64 v[14:15], s[2:3], 0, v[14:15]
	s_lshl_b32 s20, s0, 1
	v_ashrrev_i32_e32 v83, 31, v82
	v_lshl_add_u64 v[14:15], v[14:15], 0, s[20:21]
	s_mov_b64 s[0:1], 0xa28ac00
	v_lshl_add_u64 v[22:23], v[14:15], 0, s[0:1]
	v_lshlrev_b64 v[14:15], 12, v[82:83]
	v_lshl_add_u64 v[14:15], s[2:3], 0, v[14:15]
	v_lshl_add_u64 v[14:15], v[14:15], 0, s[20:21]
	s_mov_b64 s[0:1], 0x2223c000
	s_waitcnt lgkmcnt(0)
	v_add_f32_e32 v0, v132, v0
	v_lshl_add_u64 v[20:21], v[14:15], 0, s[0:1]
	ds_bpermute_b32 v14, v108, v0
	v_mov_b32_e32 v97, v1
	v_readlane_b32 s52, v249, 26
	v_readlane_b32 s69, v249, 43
	v_readlane_b32 s70, v249, 44
	s_waitcnt lgkmcnt(0)
	v_add_f32_e32 v0, v0, v14
	v_rcp_f32_e32 v14, v0
	s_nop 0
	v_readlane_b32 s71, v249, 45
	v_readlane_b32 s74, v249, 48
	v_readlane_b32 s53, v249, 27
	v_fma_f32 v16, -v0, v14, 1.0
	v_fma_f32 v14, v16, v14, v14
	v_mov_b32_e32 v14, v14
	v_lshlrev_b32_e32 v0, 1, v93
	v_lshl_add_u64 v[16:17], v[22:23], 0, v[0:1]
	global_load_dwordx2 v[24:25], v[16:17], off
	v_pk_mul_f32 v[18:19], v[62:63], v[14:15] op_sel_hi:[1,0]
	v_mov_b32_e32 v93, v1
	v_and_b32_sdwa v27, v19, v195 dst_sel:DWORD dst_unused:UNUSED_PAD src0_sel:WORD_1 src1_sel:DWORD
	v_add3_u32 v19, v19, v27, s33
	v_and_b32_sdwa v28, v18, v195 dst_sel:DWORD dst_unused:UNUSED_PAD src0_sel:WORD_1 src1_sel:DWORD
	v_add3_u32 v18, v18, v28, s33
	v_and_b32_e32 v19, 0xffff0000, v19
	v_and_b32_e32 v18, 0xffff0000, v18
	v_readlane_b32 s56, v249, 30
	v_readlane_b32 s57, v249, 31
	v_readlane_b32 s60, v249, 34
	v_readlane_b32 s61, v249, 35
	v_readlane_b32 s95, v249, 52
	v_readlane_b32 s75, v249, 49
	v_readlane_b32 s54, v249, 28
	v_readlane_b32 s55, v249, 29
	v_readlane_b32 s58, v249, 32
	v_readlane_b32 s59, v249, 33
	v_readlane_b32 s62, v249, 36
	v_readlane_b32 s63, v249, 37
	v_readlane_b32 s64, v249, 38
	v_readlane_b32 s65, v249, 39
	v_readlane_b32 s66, v249, 40
	v_readlane_b32 s67, v249, 41
	s_waitcnt vmcnt(0)
	v_and_b32_e32 v15, 0xffff0000, v24
	v_lshlrev_b32_e32 v24, 16, v24
	v_mul_f32_e32 v26, 0xbfb8aa3b, v24
	v_mul_f32_e32 v27, 0xbfb8aa3b, v15
	v_exp_f32_e32 v26, v26
	v_exp_f32_e32 v27, v27
	s_nop 0
	v_pk_add_f32 v[26:27], v[26:27], 1.0 op_sel_hi:[1,0]
	s_nop 0
	v_rcp_f32_e32 v28, v27
	s_nop 0
	s_nop 0
	v_fma_f32 v30, -v27, v28, 1.0
	v_fma_f32 v28, v30, v28, v28
	v_mul_f32_e32 v27, v15, v28
	v_rcp_f32_e32 v15, v26
	s_nop 0
	s_nop 0
	v_fma_f32 v29, -v26, v15, 1.0
	v_fma_f32 v15, v29, v15, v15
	v_mul_f32_e32 v26, v24, v15
	v_lshlrev_b32_e32 v30, 16, v25
	v_pk_mul_f32 v[18:19], v[26:27], v[18:19]
	v_pk_mul_f32 v[26:27], v[64:65], v[14:15] op_sel_hi:[1,0]
	v_mul_f32_e32 v24, 0xbfb8aa3b, v30
	v_and_b32_e32 v15, 0xffff0000, v25
	v_exp_f32_e32 v28, v24
	v_and_b32_sdwa v24, v27, v195 dst_sel:DWORD dst_unused:UNUSED_PAD src0_sel:WORD_1 src1_sel:DWORD
	v_and_b32_sdwa v25, v26, v195 dst_sel:DWORD dst_unused:UNUSED_PAD src0_sel:WORD_1 src1_sel:DWORD
	v_add3_u32 v24, v27, v24, s33
	v_add3_u32 v26, v26, v25, s33
	v_and_b32_e32 v25, 0xffff0000, v24
	v_and_b32_e32 v24, 0xffff0000, v26
	v_mul_f32_e32 v26, 0xbfb8aa3b, v15
	v_exp_f32_e32 v29, v26
	s_nop 0
	v_pk_add_f32 v[26:27], v[28:29], 1.0 op_sel_hi:[1,0]
	s_nop 0
	v_rcp_f32_e32 v28, v27
	s_nop 0
	s_nop 0
	v_fma_f32 v31, -v27, v28, 1.0
	v_fma_f32 v28, v31, v28, v28
	v_mul_f32_e32 v27, v15, v28
	v_rcp_f32_e32 v15, v26
	s_nop 0
	s_nop 0
	v_fma_f32 v29, -v26, v15, 1.0
	v_fma_f32 v15, v29, v15, v15
	v_mul_f32_e32 v26, v30, v15
	v_pk_mul_f32 v[24:25], v[26:27], v[24:25]
	v_bfe_u32 v27, v19, 16, 1
	v_bfe_u32 v15, v25, 16, 1
	v_bfe_u32 v26, v24, 16, 1
	v_bfe_u32 v28, v18, 16, 1
	v_add3_u32 v18, v18, v28, s33
	v_add3_u32 v19, v19, v27, s33
	v_add3_u32 v24, v24, v26, s33
	v_add3_u32 v15, v25, v15, s33
	v_perm_b32 v25, v15, v24, s27
	v_perm_b32 v24, v19, v18, s27
	v_lshl_add_u64 v[18:19], v[20:21], 0, v[0:1]
	global_store_dwordx2 v[18:19], v[24:25], off
	v_lshlrev_b64 v[24:25], 1, v[96:97]
	v_lshl_add_u64 v[26:27], v[22:23], 0, v[24:25]
	global_load_dwordx2 v[28:29], v[26:27], off
	v_pk_mul_f32 v[26:27], v[58:59], v[14:15] op_sel_hi:[1,0]
	v_lshl_add_u64 v[24:25], v[20:21], 0, v[24:25]
	v_and_b32_sdwa v31, v26, v195 dst_sel:DWORD dst_unused:UNUSED_PAD src0_sel:WORD_1 src1_sel:DWORD
	v_add3_u32 v26, v26, v31, s33
	v_and_b32_e32 v26, 0xffff0000, v26
	s_waitcnt vmcnt(0)
; DEVI float bf2f(u16 h) { return __uint_as_float(((unsigned)h) << 16); }
; DEVI float bfs(short h) { return __uint_as_float(((unsigned)(u16)h) << 16); }
; DEVI float silu_f(float x) { return x / (1.f + __expf(-x)); }
; template <int DQK, int QT, bool NA> ...
;     ...
;     for (int dt = 0; dt < 8; ++dt) {
;       int dv = dt * 16 + quad * 4;
;       bf16x4 g = *(const bf16x4*)(proj + (size_t)r * NP + gatecol + h * 128 + dv);
;       bf16x4 ov;
; #pragma unroll
;       for (int j = 0; j < 4; ++j) {
;         float y = bf2f(f2bf(o[dt][qt][j] * il));
;         ov[j] = (short)f2bf(y * silu_f(bfs(g[j])));
;       }
;       *(bf16x4*)(ys + (size_t)r * 2048 + ycol + h * 128 + dv) = ov;
	v_lshlrev_b32_e32 v15, 16, v28
	v_and_b32_e32 v0, 0xffff0000, v28
	v_mul_f32_e32 v28, 0xbfb8aa3b, v15
	v_exp_f32_e32 v30, v28
	v_and_b32_sdwa v28, v27, v195 dst_sel:DWORD dst_unused:UNUSED_PAD src0_sel:WORD_1 src1_sel:DWORD
	v_add3_u32 v27, v27, v28, s33
	v_mul_f32_e32 v28, 0xbfb8aa3b, v0
	v_exp_f32_e32 v31, v28
	v_and_b32_e32 v27, 0xffff0000, v27
	v_pk_add_f32 v[30:31], v[30:31], 1.0 op_sel_hi:[1,0]
	s_nop 0
	v_rcp_f32_e32 v28, v31
	s_nop 0
	s_nop 0
	v_fma_f32 v33, -v31, v28, 1.0
	v_fma_f32 v28, v33, v28, v28
	v_mul_f32_e32 v31, v0, v28
	v_rcp_f32_e32 v0, v30
	s_nop 0
	s_nop 0
	v_fma_f32 v32, -v30, v0, 1.0
	v_fma_f32 v0, v32, v0, v0
	v_mul_f32_e32 v30, v15, v0
	v_pk_mul_f32 v[26:27], v[30:31], v[26:27]
	v_pk_mul_f32 v[30:31], v[60:61], v[14:15] op_sel_hi:[1,0]
	v_lshlrev_b32_e32 v15, 16, v29
	v_mul_f32_e32 v28, 0xbfb8aa3b, v15
	v_and_b32_e32 v0, 0xffff0000, v29
	v_exp_f32_e32 v32, v28
	v_and_b32_sdwa v28, v31, v195 dst_sel:DWORD dst_unused:UNUSED_PAD src0_sel:WORD_1 src1_sel:DWORD
	v_and_b32_sdwa v29, v30, v195 dst_sel:DWORD dst_unused:UNUSED_PAD src0_sel:WORD_1 src1_sel:DWORD
	v_add3_u32 v28, v31, v28, s33
	v_add3_u32 v30, v30, v29, s33
	v_and_b32_e32 v29, 0xffff0000, v28
	v_and_b32_e32 v28, 0xffff0000, v30
	v_mul_f32_e32 v30, 0xbfb8aa3b, v0
	v_exp_f32_e32 v33, v30
	s_nop 0
	v_pk_add_f32 v[30:31], v[32:33], 1.0 op_sel_hi:[1,0]
	s_nop 0
	v_rcp_f32_e32 v32, v31
	s_nop 0
	s_nop 0
	v_fma_f32 v38, -v31, v32, 1.0
	v_fma_f32 v32, v38, v32, v32
	v_mul_f32_e32 v31, v0, v32
	v_rcp_f32_e32 v0, v30
	s_nop 0
	s_nop 0
	v_fma_f32 v33, -v30, v0, 1.0
	v_fma_f32 v0, v33, v0, v0
	v_mul_f32_e32 v30, v15, v0
	v_pk_mul_f32 v[28:29], v[30:31], v[28:29]
	v_bfe_u32 v30, v27, 16, 1
	v_bfe_u32 v0, v29, 16, 1
	v_bfe_u32 v15, v28, 16, 1
	v_bfe_u32 v31, v26, 16, 1
	v_add3_u32 v26, v26, v31, s33
	v_add3_u32 v30, v27, v30, s33
	v_add3_u32 v15, v28, v15, s33
	v_add3_u32 v0, v29, v0, s33
	v_perm_b32 v27, v0, v15, s27
	v_perm_b32 v26, v30, v26, s27
	global_store_dwordx2 v[24:25], v[26:27], off
	v_lshlrev_b64 v[24:25], 1, v[92:93]
	v_lshl_add_u64 v[22:23], v[22:23], 0, v[24:25]
	global_load_dwordx2 v[26:27], v[22:23], off
	v_pk_mul_f32 v[22:23], v[54:55], v[14:15] op_sel_hi:[1,0]
	v_lshl_add_u64 v[20:21], v[20:21], 0, v[24:25]
	v_and_b32_sdwa v29, v22, v195 dst_sel:DWORD dst_unused:UNUSED_PAD src0_sel:WORD_1 src1_sel:DWORD
	v_add3_u32 v22, v22, v29, s33
	v_and_b32_e32 v22, 0xffff0000, v22
	s_waitcnt vmcnt(0)
	v_lshlrev_b32_e32 v15, 16, v26
	v_and_b32_e32 v0, 0xffff0000, v26
	v_mul_f32_e32 v26, 0xbfb8aa3b, v15
	v_exp_f32_e32 v28, v26
	v_and_b32_sdwa v26, v23, v195 dst_sel:DWORD dst_unused:UNUSED_PAD src0_sel:WORD_1 src1_sel:DWORD
	v_add3_u32 v23, v23, v26, s33
	v_mul_f32_e32 v26, 0xbfb8aa3b, v0
	v_exp_f32_e32 v29, v26
	v_and_b32_e32 v23, 0xffff0000, v23
	v_pk_add_f32 v[28:29], v[28:29], 1.0 op_sel_hi:[1,0]
	s_nop 0
	v_rcp_f32_e32 v26, v29
	s_nop 0
	s_nop 0
	v_fma_f32 v31, -v29, v26, 1.0
	v_fma_f32 v26, v31, v26, v26
	v_mul_f32_e32 v29, v0, v26
	v_rcp_f32_e32 v0, v28
	s_nop 0
	s_nop 0
	v_fma_f32 v30, -v28, v0, 1.0
	v_fma_f32 v0, v30, v0, v0
	v_mul_f32_e32 v28, v15, v0
	v_pk_mul_f32 v[22:23], v[28:29], v[22:23]
	v_pk_mul_f32 v[28:29], v[56:57], v[14:15] op_sel_hi:[1,0]
	v_lshlrev_b32_e32 v15, 16, v27
	v_mul_f32_e32 v26, 0xbfb8aa3b, v15
	v_and_b32_e32 v0, 0xffff0000, v27
	v_exp_f32_e32 v30, v26
	v_and_b32_sdwa v26, v29, v195 dst_sel:DWORD dst_unused:UNUSED_PAD src0_sel:WORD_1 src1_sel:DWORD
	v_and_b32_sdwa v27, v28, v195 dst_sel:DWORD dst_unused:UNUSED_PAD src0_sel:WORD_1 src1_sel:DWORD
	v_add3_u32 v26, v29, v26, s33
	v_add3_u32 v28, v28, v27, s33
	v_and_b32_e32 v27, 0xffff0000, v26
	v_and_b32_e32 v26, 0xffff0000, v28
	v_mul_f32_e32 v28, 0xbfb8aa3b, v0
	v_exp_f32_e32 v31, v28
	s_nop 0
	v_pk_add_f32 v[28:29], v[30:31], 1.0 op_sel_hi:[1,0]
	s_nop 0
	v_rcp_f32_e32 v30, v29
	s_nop 0
	s_nop 0
	v_fma_f32 v32, -v29, v30, 1.0
	v_fma_f32 v30, v32, v30, v30
	v_mul_f32_e32 v29, v0, v30
	v_rcp_f32_e32 v0, v28
	s_nop 0
	s_nop 0
	v_fma_f32 v31, -v28, v0, 1.0
	v_fma_f32 v0, v31, v0, v0
	v_mul_f32_e32 v28, v15, v0
	v_pk_mul_f32 v[26:27], v[28:29], v[26:27]
	v_bfe_u32 v28, v23, 16, 1
	v_bfe_u32 v0, v27, 16, 1
	v_bfe_u32 v15, v26, 16, 1
	v_bfe_u32 v29, v22, 16, 1
	v_add3_u32 v22, v22, v29, s33
	v_add3_u32 v28, v23, v28, s33
	v_add3_u32 v15, v26, v15, s33
	v_add3_u32 v0, v27, v0, s33
	v_perm_b32 v23, v0, v15, s27
	v_perm_b32 v22, v28, v22, s27
	global_store_dwordx2 v[20:21], v[22:23], off
	global_load_dwordx2 v[20:21], v[16:17], off offset:96
	v_pk_mul_f32 v[22:23], v[50:51], v[14:15] op_sel_hi:[1,0]
	s_waitcnt vmcnt(0)
; DEVI float bf2f(u16 h) { return __uint_as_float(((unsigned)h) << 16); }
; DEVI float bfs(short h) { return __uint_as_float(((unsigned)(u16)h) << 16); }
; DEVI float silu_f(float x) { return x / (1.f + __expf(-x)); }
; template <int DQK, int QT, bool NA> ...
;     ...
;     for (int dt = 0; dt < 8; ++dt) {
;       int dv = dt * 16 + quad * 4;
;       bf16x4 g = *(const bf16x4*)(proj + (size_t)r * NP + gatecol + h * 128 + dv);
;       bf16x4 ov;
; #pragma unroll
;       for (int j = 0; j < 4; ++j) {
;         float y = bf2f(f2bf(o[dt][qt][j] * il));
;         ov[j] = (short)f2bf(y * silu_f(bfs(g[j])));
;       }
;       *(bf16x4*)(ys + (size_t)r * 2048 + ycol + h * 128 + dv) = ov;
	v_lshlrev_b32_e32 v15, 16, v20
	v_and_b32_e32 v0, 0xffff0000, v20
	v_mul_f32_e32 v20, 0xbfb8aa3b, v15
	v_exp_f32_e32 v24, v20
	v_and_b32_sdwa v20, v23, v195 dst_sel:DWORD dst_unused:UNUSED_PAD src0_sel:WORD_1 src1_sel:DWORD
	v_add3_u32 v20, v23, v20, s33
	v_and_b32_sdwa v25, v22, v195 dst_sel:DWORD dst_unused:UNUSED_PAD src0_sel:WORD_1 src1_sel:DWORD
	v_and_b32_e32 v23, 0xffff0000, v20
	v_mul_f32_e32 v20, 0xbfb8aa3b, v0
	v_add3_u32 v22, v22, v25, s33
	v_exp_f32_e32 v25, v20
	v_and_b32_e32 v22, 0xffff0000, v22
	v_pk_add_f32 v[24:25], v[24:25], 1.0 op_sel_hi:[1,0]
	s_nop 0
	v_rcp_f32_e32 v20, v25
	s_nop 0
	s_nop 0
	v_fma_f32 v27, -v25, v20, 1.0
	v_fma_f32 v20, v27, v20, v20
	v_mul_f32_e32 v25, v0, v20
	v_rcp_f32_e32 v0, v24
	s_nop 0
	s_nop 0
	v_fma_f32 v26, -v24, v0, 1.0
	v_fma_f32 v0, v26, v0, v0
	v_mul_f32_e32 v24, v15, v0
	v_pk_mul_f32 v[22:23], v[24:25], v[22:23]
	v_pk_mul_f32 v[24:25], v[52:53], v[14:15] op_sel_hi:[1,0]
	v_and_b32_e32 v0, 0xffff0000, v21
	v_lshlrev_b32_e32 v15, 16, v21
	v_and_b32_sdwa v21, v25, v195 dst_sel:DWORD dst_unused:UNUSED_PAD src0_sel:WORD_1 src1_sel:DWORD
	v_add3_u32 v21, v25, v21, s33
	v_mul_f32_e32 v20, 0xbfb8aa3b, v15
	v_and_b32_e32 v25, 0xffff0000, v21
	v_mul_f32_e32 v21, 0xbfb8aa3b, v0
	v_exp_f32_e32 v20, v20
	v_exp_f32_e32 v21, v21
	v_and_b32_sdwa v26, v24, v195 dst_sel:DWORD dst_unused:UNUSED_PAD src0_sel:WORD_1 src1_sel:DWORD
	v_add3_u32 v24, v24, v26, s33
	v_and_b32_e32 v24, 0xffff0000, v24
	v_pk_add_f32 v[20:21], v[20:21], 1.0 op_sel_hi:[1,0]
	s_nop 0
	v_rcp_f32_e32 v26, v21
	s_nop 0
	s_nop 0
	v_fma_f32 v28, -v21, v26, 1.0
	v_fma_f32 v26, v28, v26, v26
	v_mul_f32_e32 v21, v0, v26
	v_rcp_f32_e32 v0, v20
	s_nop 0
	s_nop 0
	v_fma_f32 v27, -v20, v0, 1.0
	v_fma_f32 v0, v27, v0, v0
	v_mul_f32_e32 v20, v15, v0
	v_pk_mul_f32 v[20:21], v[20:21], v[24:25]
	v_bfe_u32 v24, v23, 16, 1
	v_bfe_u32 v0, v21, 16, 1
	v_bfe_u32 v15, v20, 16, 1
	v_bfe_u32 v25, v22, 16, 1
	v_add3_u32 v22, v22, v25, s33
	v_add3_u32 v23, v23, v24, s33
	v_add3_u32 v15, v20, v15, s33
	v_add3_u32 v0, v21, v0, s33
	v_perm_b32 v21, v0, v15, s27
	v_perm_b32 v20, v23, v22, s27
	global_store_dwordx2 v[18:19], v[20:21], off offset:96
	global_load_dwordx2 v[20:21], v[16:17], off offset:128
	v_pk_mul_f32 v[22:23], v[34:35], v[14:15] op_sel_hi:[1,0]
	s_waitcnt vmcnt(0)
	v_lshlrev_b32_e32 v15, 16, v20
	v_and_b32_e32 v0, 0xffff0000, v20
	v_mul_f32_e32 v20, 0xbfb8aa3b, v15
	v_exp_f32_e32 v24, v20
	v_and_b32_sdwa v20, v23, v195 dst_sel:DWORD dst_unused:UNUSED_PAD src0_sel:WORD_1 src1_sel:DWORD
	v_add3_u32 v20, v23, v20, s33
	v_and_b32_sdwa v25, v22, v195 dst_sel:DWORD dst_unused:UNUSED_PAD src0_sel:WORD_1 src1_sel:DWORD
	v_and_b32_e32 v23, 0xffff0000, v20
	v_mul_f32_e32 v20, 0xbfb8aa3b, v0
	v_add3_u32 v22, v22, v25, s33
	v_exp_f32_e32 v25, v20
	v_and_b32_e32 v22, 0xffff0000, v22
	v_pk_add_f32 v[24:25], v[24:25], 1.0 op_sel_hi:[1,0]
	s_nop 0
	v_rcp_f32_e32 v20, v25
	s_nop 0
	s_nop 0
	v_fma_f32 v27, -v25, v20, 1.0
	v_fma_f32 v20, v27, v20, v20
	v_mul_f32_e32 v25, v0, v20
	v_rcp_f32_e32 v0, v24
	s_nop 0
	s_nop 0
	v_fma_f32 v26, -v24, v0, 1.0
	v_fma_f32 v0, v26, v0, v0
	v_mul_f32_e32 v24, v15, v0
	v_pk_mul_f32 v[22:23], v[24:25], v[22:23]
	v_pk_mul_f32 v[24:25], v[36:37], v[14:15] op_sel_hi:[1,0]
	v_and_b32_e32 v0, 0xffff0000, v21
	v_lshlrev_b32_e32 v15, 16, v21
	v_and_b32_sdwa v21, v25, v195 dst_sel:DWORD dst_unused:UNUSED_PAD src0_sel:WORD_1 src1_sel:DWORD
	v_add3_u32 v21, v25, v21, s33
	v_mul_f32_e32 v20, 0xbfb8aa3b, v15
	v_and_b32_e32 v25, 0xffff0000, v21
	v_mul_f32_e32 v21, 0xbfb8aa3b, v0
	v_exp_f32_e32 v20, v20
	v_exp_f32_e32 v21, v21
	v_and_b32_sdwa v26, v24, v195 dst_sel:DWORD dst_unused:UNUSED_PAD src0_sel:WORD_1 src1_sel:DWORD
	v_add3_u32 v24, v24, v26, s33
	v_and_b32_e32 v24, 0xffff0000, v24
	v_pk_add_f32 v[20:21], v[20:21], 1.0 op_sel_hi:[1,0]
	s_nop 0
	v_rcp_f32_e32 v26, v21
	s_nop 0
	s_nop 0
	v_fma_f32 v28, -v21, v26, 1.0
	v_fma_f32 v26, v28, v26, v26
	v_mul_f32_e32 v21, v0, v26
	v_rcp_f32_e32 v0, v20
	s_nop 0
	s_nop 0
	v_fma_f32 v27, -v20, v0, 1.0
	v_fma_f32 v0, v27, v0, v0
	v_mul_f32_e32 v20, v15, v0
	v_pk_mul_f32 v[20:21], v[20:21], v[24:25]
	v_bfe_u32 v24, v23, 16, 1
	v_bfe_u32 v0, v21, 16, 1
	v_bfe_u32 v15, v20, 16, 1
	v_bfe_u32 v25, v22, 16, 1
	v_add3_u32 v22, v22, v25, s33
	v_add3_u32 v23, v23, v24, s33
	v_add3_u32 v15, v20, v15, s33
	v_add3_u32 v0, v21, v0, s33
	v_perm_b32 v21, v0, v15, s27
	v_perm_b32 v20, v23, v22, s27
	global_store_dwordx2 v[18:19], v[20:21], off offset:128
	global_load_dwordx2 v[20:21], v[16:17], off offset:160
	v_pk_mul_f32 v[10:11], v[10:11], v[14:15] op_sel_hi:[1,0]
	s_waitcnt vmcnt(0)
; DEVI float bf2f(u16 h) { return __uint_as_float(((unsigned)h) << 16); }
; DEVI float bfs(short h) { return __uint_as_float(((unsigned)(u16)h) << 16); }
; DEVI float silu_f(float x) { return x / (1.f + __expf(-x)); }
; template <int DQK, int QT, bool NA> ...
;     ...
;     for (int dt = 0; dt < 8; ++dt) {
;       int dv = dt * 16 + quad * 4;
;       bf16x4 g = *(const bf16x4*)(proj + (size_t)r * NP + gatecol + h * 128 + dv);
;       bf16x4 ov;
; #pragma unroll
;       for (int j = 0; j < 4; ++j) {
;         float y = bf2f(f2bf(o[dt][qt][j] * il));
;         ov[j] = (short)f2bf(y * silu_f(bfs(g[j])));
;       }
;       *(bf16x4*)(ys + (size_t)r * 2048 + ycol + h * 128 + dv) = ov;
	v_lshlrev_b32_e32 v15, 16, v20
	v_and_b32_e32 v0, 0xffff0000, v20
	v_mul_f32_e32 v20, 0xbfb8aa3b, v15
	v_exp_f32_e32 v22, v20
	v_and_b32_sdwa v20, v11, v195 dst_sel:DWORD dst_unused:UNUSED_PAD src0_sel:WORD_1 src1_sel:DWORD
	v_and_b32_sdwa v23, v10, v195 dst_sel:DWORD dst_unused:UNUSED_PAD src0_sel:WORD_1 src1_sel:DWORD
	v_add3_u32 v11, v11, v20, s33
	v_mul_f32_e32 v20, 0xbfb8aa3b, v0
	v_add3_u32 v10, v10, v23, s33
	v_exp_f32_e32 v23, v20
	v_pk_mul_f32 v[12:13], v[12:13], v[14:15] op_sel_hi:[1,0]
	v_and_b32_e32 v11, 0xffff0000, v11
	v_and_b32_e32 v10, 0xffff0000, v10
	v_pk_add_f32 v[22:23], v[22:23], 1.0 op_sel_hi:[1,0]
	s_nop 0
	v_rcp_f32_e32 v20, v23
	s_nop 0
	s_nop 0
	v_fma_f32 v25, -v23, v20, 1.0
	v_fma_f32 v20, v25, v20, v20
	v_mul_f32_e32 v23, v0, v20
	v_rcp_f32_e32 v0, v22
	s_nop 0
	s_nop 0
	v_fma_f32 v24, -v22, v0, 1.0
	v_fma_f32 v0, v24, v0, v0
	v_mul_f32_e32 v22, v15, v0
	v_and_b32_e32 v0, 0xffff0000, v21
	v_lshlrev_b32_e32 v15, 16, v21
	v_and_b32_sdwa v21, v13, v195 dst_sel:DWORD dst_unused:UNUSED_PAD src0_sel:WORD_1 src1_sel:DWORD
	v_mul_f32_e32 v20, 0xbfb8aa3b, v15
	v_add3_u32 v13, v13, v21, s33
	v_mul_f32_e32 v21, 0xbfb8aa3b, v0
	v_exp_f32_e32 v20, v20
	v_exp_f32_e32 v21, v21
	v_pk_mul_f32 v[10:11], v[22:23], v[10:11]
	v_and_b32_sdwa v22, v12, v195 dst_sel:DWORD dst_unused:UNUSED_PAD src0_sel:WORD_1 src1_sel:DWORD
	v_add3_u32 v12, v12, v22, s33
	v_pk_add_f32 v[20:21], v[20:21], 1.0 op_sel_hi:[1,0]
	v_and_b32_e32 v13, 0xffff0000, v13
	v_rcp_f32_e32 v22, v21
	s_nop 0
	v_and_b32_e32 v12, 0xffff0000, v12
	v_fma_f32 v24, -v21, v22, 1.0
	v_fma_f32 v22, v24, v22, v22
	v_mul_f32_e32 v21, v0, v22
	v_rcp_f32_e32 v0, v20
	s_nop 0
	s_nop 0
	v_fma_f32 v23, -v20, v0, 1.0
	v_fma_f32 v0, v23, v0, v0
	v_mul_f32_e32 v20, v15, v0
	v_pk_mul_f32 v[12:13], v[20:21], v[12:13]
	v_bfe_u32 v20, v11, 16, 1
	v_bfe_u32 v0, v13, 16, 1
	v_bfe_u32 v15, v12, 16, 1
	v_bfe_u32 v21, v10, 16, 1
	v_add3_u32 v10, v10, v21, s33
	v_add3_u32 v20, v11, v20, s33
	v_add3_u32 v11, v12, v15, s33
	v_add3_u32 v0, v13, v0, s33
	v_perm_b32 v11, v0, v11, s27
	v_perm_b32 v10, v20, v10, s27
	global_store_dwordx2 v[18:19], v[10:11], off offset:160
	global_load_dwordx2 v[10:11], v[16:17], off offset:192
	v_pk_mul_f32 v[6:7], v[6:7], v[14:15] op_sel_hi:[1,0]
	s_waitcnt vmcnt(0)
	v_and_b32_e32 v0, 0xffff0000, v10
	v_lshlrev_b32_e32 v10, 16, v10
	v_and_b32_sdwa v13, v7, v195 dst_sel:DWORD dst_unused:UNUSED_PAD src0_sel:WORD_1 src1_sel:DWORD
	v_mul_f32_e32 v12, 0xbfb8aa3b, v10
	v_add3_u32 v7, v7, v13, s33
	v_mul_f32_e32 v13, 0xbfb8aa3b, v0
	v_exp_f32_e32 v12, v12
	v_exp_f32_e32 v13, v13
	v_and_b32_sdwa v15, v6, v195 dst_sel:DWORD dst_unused:UNUSED_PAD src0_sel:WORD_1 src1_sel:DWORD
	v_add3_u32 v6, v6, v15, s33
	v_and_b32_e32 v7, 0xffff0000, v7
	v_pk_add_f32 v[12:13], v[12:13], 1.0 op_sel_hi:[1,0]
	v_and_b32_e32 v6, 0xffff0000, v6
	v_rcp_f32_e32 v15, v13
	s_nop 0
	s_nop 0
	v_fma_f32 v21, -v13, v15, 1.0
	v_fma_f32 v15, v21, v15, v15
	v_mul_f32_e32 v13, v0, v15
	v_rcp_f32_e32 v0, v12
	s_nop 0
	s_nop 0
	v_fma_f32 v20, -v12, v0, 1.0
	v_fma_f32 v0, v20, v0, v0
	v_mul_f32_e32 v12, v10, v0
	v_pk_mul_f32 v[8:9], v[8:9], v[14:15] op_sel_hi:[1,0]
	v_pk_mul_f32 v[6:7], v[12:13], v[6:7]
	v_and_b32_e32 v0, 0xffff0000, v11
	v_lshlrev_b32_e32 v12, 16, v11
	v_and_b32_sdwa v11, v9, v195 dst_sel:DWORD dst_unused:UNUSED_PAD src0_sel:WORD_1 src1_sel:DWORD
	v_mul_f32_e32 v10, 0xbfb8aa3b, v12
	v_add3_u32 v9, v9, v11, s33
	v_mul_f32_e32 v11, 0xbfb8aa3b, v0
	v_exp_f32_e32 v10, v10
	v_exp_f32_e32 v11, v11
	v_and_b32_sdwa v13, v8, v195 dst_sel:DWORD dst_unused:UNUSED_PAD src0_sel:WORD_1 src1_sel:DWORD
	v_add3_u32 v8, v8, v13, s33
	v_and_b32_e32 v9, 0xffff0000, v9
	v_pk_add_f32 v[10:11], v[10:11], 1.0 op_sel_hi:[1,0]
	v_and_b32_e32 v8, 0xffff0000, v8
	v_rcp_f32_e32 v13, v11
	s_nop 0
	s_nop 0
	v_fma_f32 v20, -v11, v13, 1.0
	v_fma_f32 v13, v20, v13, v13
	v_mul_f32_e32 v11, v0, v13
	v_rcp_f32_e32 v0, v10
	s_nop 0
	s_nop 0
	v_fma_f32 v15, -v10, v0, 1.0
	v_fma_f32 v0, v15, v0, v0
	v_mul_f32_e32 v10, v12, v0
	v_pk_mul_f32 v[8:9], v[10:11], v[8:9]
	v_bfe_u32 v11, v7, 16, 1
	v_bfe_u32 v0, v9, 16, 1
	v_bfe_u32 v10, v8, 16, 1
	v_bfe_u32 v12, v6, 16, 1
	v_add3_u32 v6, v6, v12, s33
	v_add3_u32 v11, v7, v11, s33
	v_add3_u32 v7, v8, v10, s33
	v_add3_u32 v0, v9, v0, s33
	v_perm_b32 v7, v0, v7, s27
	v_perm_b32 v6, v11, v6, s27
	global_store_dwordx2 v[18:19], v[6:7], off offset:192
	global_load_dwordx2 v[6:7], v[16:17], off offset:224
	v_pk_mul_f32 v[2:3], v[2:3], v[14:15] op_sel_hi:[1,0]
	s_waitcnt vmcnt(0)
	v_and_b32_e32 v0, 0xffff0000, v6
	v_lshlrev_b32_e32 v6, 16, v6
	v_and_b32_sdwa v9, v3, v195 dst_sel:DWORD dst_unused:UNUSED_PAD src0_sel:WORD_1 src1_sel:DWORD
	v_mul_f32_e32 v8, 0xbfb8aa3b, v6
	v_add3_u32 v3, v3, v9, s33
	v_mul_f32_e32 v9, 0xbfb8aa3b, v0
	v_exp_f32_e32 v8, v8
	v_exp_f32_e32 v9, v9
	v_and_b32_sdwa v10, v2, v195 dst_sel:DWORD dst_unused:UNUSED_PAD src0_sel:WORD_1 src1_sel:DWORD
	v_add3_u32 v2, v2, v10, s33
	v_and_b32_e32 v3, 0xffff0000, v3
	v_pk_add_f32 v[8:9], v[8:9], 1.0 op_sel_hi:[1,0]
	v_and_b32_e32 v2, 0xffff0000, v2
	v_rcp_f32_e32 v10, v9
	s_nop 0
	s_nop 0
	v_fma_f32 v12, -v9, v10, 1.0
	v_fma_f32 v10, v12, v10, v10
	v_mul_f32_e32 v9, v0, v10
	v_rcp_f32_e32 v0, v8
	s_nop 0
	v_pk_mul_f32 v[4:5], v[4:5], v[14:15] op_sel_hi:[1,0]
	v_fma_f32 v11, -v8, v0, 1.0
	v_fma_f32 v0, v11, v0, v0
	v_mul_f32_e32 v8, v6, v0
	v_pk_mul_f32 v[2:3], v[8:9], v[2:3]
	v_and_b32_e32 v0, 0xffff0000, v7
	v_lshlrev_b32_e32 v8, 16, v7
	v_and_b32_sdwa v7, v5, v195 dst_sel:DWORD dst_unused:UNUSED_PAD src0_sel:WORD_1 src1_sel:DWORD
	v_mul_f32_e32 v6, 0xbfb8aa3b, v8
	v_add3_u32 v5, v5, v7, s33
	v_mul_f32_e32 v7, 0xbfb8aa3b, v0
	v_exp_f32_e32 v6, v6
	v_exp_f32_e32 v7, v7
	v_and_b32_sdwa v9, v4, v195 dst_sel:DWORD dst_unused:UNUSED_PAD src0_sel:WORD_1 src1_sel:DWORD
	v_add3_u32 v4, v4, v9, s33
	v_and_b32_e32 v5, 0xffff0000, v5
	v_pk_add_f32 v[6:7], v[6:7], 1.0 op_sel_hi:[1,0]
	v_and_b32_e32 v4, 0xffff0000, v4
	v_rcp_f32_e32 v9, v7
	s_nop 0
	s_nop 0
	v_fma_f32 v11, -v7, v9, 1.0
	v_fma_f32 v9, v11, v9, v9
	v_mul_f32_e32 v7, v0, v9
	v_rcp_f32_e32 v0, v6
	s_nop 0
	s_nop 0
	v_fma_f32 v10, -v6, v0, 1.0
	v_fma_f32 v0, v10, v0, v0
	v_mul_f32_e32 v6, v8, v0
	v_pk_mul_f32 v[4:5], v[6:7], v[4:5]
	v_bfe_u32 v7, v3, 16, 1
	v_bfe_u32 v0, v5, 16, 1
	v_bfe_u32 v6, v4, 16, 1
	v_bfe_u32 v8, v2, 16, 1
	v_add3_u32 v2, v2, v8, s33
	v_add3_u32 v7, v3, v7, s33
	v_add3_u32 v3, v4, v6, s33
	v_add3_u32 v0, v5, v0, s33
	v_perm_b32 v3, v0, v3, s27
	v_perm_b32 v2, v7, v2, s27
	global_store_dwordx2 v[18:19], v[2:3], off offset:224
